# cross attention LDS image: 256-B rows with 16-B slots rotated by 2*(row&7) (conflict-free for ds_read_b128 lane groups and transposed reads; the 272-B pitch was 2-way) + q fragments fetched half a sec
# speedup vs baseline: 1.0202x; 1.0062x over previous
; #define LAS __attribute__((address_space(3)))
; __device__ __forceinline__ int opaque_tid() { int t = (int)threadIdx.x; asm volatile("" : "+v"(t)); return t; }
; __device__ __forceinline__ f32x4 mfma16(bf16x8 a, bf16x8 b, f32x4 c) { return __builtin_amdgcn_mfma_f32_16x16x32_bf16(a, b, c, 0, 0, 0); }
; #define LDS_BARRIER() do { asm volatile("s_waitcnt lgkmcnt(0)" ::: "memory"); __builtin_amdgcn_s_barrier(); asm volatile("" ::: "memory"); } while (0)
; __device__ void cross_items(const Params& p, LAS unsigned char* lds) {
;     const int tid = opaque_tid(), lane = tid & 63, w = __builtin_amdgcn_readfirstlane(tid >> 6), idx = lane & 15, g = lane >> 4;
;     unsigned char* ws = p.ws;
;     bf16_t* oc = (bf16_t*)(ws + OFF_OC);
;     const unsigned lbase = (unsigned)(size_t)lds;
;     const int piece = tid & 15, srow = tid >> 4;
;     const int G = (int)gridDim.x;
;     u32x4 pre[8];
;     ...
;     const int pmx = 8 * ((int)blockIdx.x & 7) + ((int)blockIdx.x >> 5), hdx = ((int)blockIdx.x >> 3) & 3;
;     const int item0 = (pmx >> 4) * 128 + hdx * 32 + 2 * (pmx & 15);
;     { const bf16_t* kvb0 = (const bf16_t*)(ws + OFF_MKV) + (size_t)((item0 >> 7) * 256) * 4096 + ((item0 >> 5) & 3) * 512; XLOAD(kvb0, 0); }
;     for (int item = item0; item < item0 + 2; ++item) {
;         const int b = item >> 7, head = (item >> 5) & 3, qb = item & 31;
;         const size_t tok = (size_t)(b * SEQ + qb * 128 + 16 * w + idx);
;         const bf16_t* qrow = (const bf16_t*)(ws + OFF_B1) + tok * DM + head * 512 + 8 * g;
;         const bf16_t* kvb = (const bf16_t*)(ws + OFF_MKV) + (size_t)(b * 256) * 4096 + head * 512;
;         f32x4 sc[16];
; #pragma unroll
;         for (int kt = 0; kt < 16; ++kt) sc[kt] = (f32x4){0.f, 0.f, 0.f, 0.f};
;         for (int c = 0; c < 4; ++c) {
;             LAS unsigned char* buf = lds + (c & 1) * KV_BUF;
;             XSTORE(buf);
;             bf16x8 qf[4];
; #pragma unroll
;             for (int ks = 0; ks < 4; ++ks) qf[ks] = *(const bf16x8*)(qrow + c * 128 + 32 * ks);
;             XLOAD(kvb, c + 1);
;             LDS_BARRIER();
; #pragma unroll
;             for (int kt = 0; kt < 16; ++kt)
; #pragma unroll
;                 for (int ks = 0; ks < 4; ++ks) sc[kt] = mfma16(frag_row(buf, KV_STRIDE, 16 * kt, 32 * ks, idx, g), qf[ks], sc[kt]);
.LBB0_391:
	s_or_b64 exec, exec, s[0:1]
	v_mov_b32_e32 v40, v212
	s_waitcnt vmcnt(0) lgkmcnt(0)
	s_barrier
	v_readlane_b32 s0, v254, 29
	v_and_b32_e32 v243, 63, v212
	v_lshrrev_b32_e32 v242, 6, v212
	s_nop 1
	v_readfirstlane_b32 s4, v242
	s_lshr_b32 s0, s0, 9
	s_and_b32 s1, s0, 7
	s_lshl_b32 s1, s1, 3
	s_lshr_b32 s2, s0, 5
	s_add_i32 s1, s1, s2
	s_lshr_b32 s2, s0, 3
	s_and_b32 s2, s2, 3
	s_lshr_b32 s3, s1, 4
	s_add_u32 s6, s92, 0x1000
	s_addc_u32 s7, s93, 0
	v_and_b32_e32 v4, 15, v243
	v_lshrrev_b32_e32 v5, 4, v243
	v_and_b32_e32 v6, 15, v212
	v_lshrrev_b32_e32 v7, 4, v212
	v_and_b32_e32 v8, 7, v7
	v_lshl_add_u32 v8, v8, 1, v6
	v_and_b32_e32 v8, 15, v8
	v_lshlrev_b32_e32 v8, 4, v8
	v_lshl_add_u32 v0, v7, 8, v8
	v_add_u32_e32 v1, 0x10000, v0
	v_and_b32_e32 v9, 7, v4
	v_lshlrev_b32_e32 v9, 1, v9
	v_add_u32_e32 v9, v9, v5
	v_add_u32_e32 v10, 0, v9
	v_and_b32_e32 v10, 15, v10
	v_lshlrev_b32_e32 v10, 4, v10
	v_lshl_add_u32 v2, v4, 8, v10
	v_add_u32_e32 v10, 4, v9
	v_and_b32_e32 v10, 15, v10
	v_lshlrev_b32_e32 v10, 4, v10
	v_lshl_add_u32 v208, v4, 8, v10
	v_add_u32_e32 v10, 8, v9
	v_and_b32_e32 v10, 15, v10
	v_lshlrev_b32_e32 v10, 4, v10
	v_lshl_add_u32 v209, v4, 8, v10
	v_add_u32_e32 v10, 12, v9
	v_and_b32_e32 v10, 15, v10
	v_lshlrev_b32_e32 v10, 4, v10
	v_lshl_add_u32 v210, v4, 8, v10
	s_lshl_b32 s5, s1, 20
	s_lshl_b32 s8, s4, 16
	s_add_i32 s5, s5, s8
	s_lshl_b32 s8, s2, 10
	s_add_i32 s5, s5, s8
	v_lshlrev_b32_e32 v246, 12, v4
	v_add_u32_e32 v246, s5, v246
	v_lshl_add_u32 v248, v5, 3, v246
	v_add_u32_e32 v248, 0xd100000, v248
	v_add_u32_e32 v249, 0x80000, v248
	v_lshl_add_u32 v246, v5, 4, v246
	v_add_u32_e32 v247, 0x80000, v246
	s_lshl_b32 s5, s3, 21
	s_add_i32 s5, s5, s8
	s_add_i32 s5, s5, 0xc400000
	v_lshlrev_b32_e32 v242, 13, v7
	v_lshl_add_u32 v242, v6, 4, v242
	v_add_u32_e32 v242, s5, v242
	global_load_dwordx4 v[164:167], v242, s[92:93]
	v_add_u32_e32 v243, 0x40000, v242
	global_load_dwordx4 v[168:171], v243, s[92:93]
	v_add_u32_e32 v243, 0x80000, v242
	global_load_dwordx4 v[172:175], v243, s[92:93]
	v_add_u32_e32 v243, 0xc0000, v242
	global_load_dwordx4 v[176:179], v243, s[92:93]
	v_add_u32_e32 v243, 0x100000, v242
	global_load_dwordx4 v[180:183], v243, s[92:93]
	v_add_u32_e32 v243, 0x140000, v242
	global_load_dwordx4 v[184:187], v243, s[92:93]
	v_add_u32_e32 v243, 0x180000, v242
	global_load_dwordx4 v[188:191], v243, s[92:93]
	v_add_u32_e32 v243, 0x1c0000, v242
	global_load_dwordx4 v[192:195], v243, s[92:93]
	global_load_dwordx4 v[132:135], v246, s[92:93] offset:0
	global_load_dwordx4 v[136:139], v246, s[92:93] offset:64
	global_load_dwordx4 v[148:151], v247, s[92:93] offset:0
	global_load_dwordx4 v[152:155], v247, s[92:93] offset:64
	global_load_dwordx4 v[140:143], v246, s[92:93] offset:128
	global_load_dwordx4 v[144:147], v246, s[92:93] offset:192
	global_load_dwordx4 v[156:159], v247, s[92:93] offset:128
	global_load_dwordx4 v[160:163], v247, s[92:93] offset:192
	s_waitcnt vmcnt(15)
	ds_write_b128 v0, v[164:167]
	s_waitcnt vmcnt(14)
	ds_write_b128 v0, v[168:171] offset:8192
	s_waitcnt vmcnt(13)
	ds_write_b128 v0, v[172:175] offset:16384
	s_waitcnt vmcnt(12)
	ds_write_b128 v0, v[176:179] offset:24576
	s_waitcnt vmcnt(11)
	ds_write_b128 v0, v[180:183] offset:32768
	s_waitcnt vmcnt(10)
	ds_write_b128 v0, v[184:187] offset:40960
	s_waitcnt vmcnt(9)
	ds_write_b128 v0, v[188:191] offset:49152
	s_waitcnt vmcnt(8)
	ds_write_b128 v0, v[192:195] offset:57344
	global_load_dwordx4 v[164:167], v242, s[92:93] offset:256
	v_add_u32_e32 v243, 0x40000, v242
	global_load_dwordx4 v[168:171], v243, s[92:93] offset:256
	v_add_u32_e32 v243, 0x80000, v242
	global_load_dwordx4 v[172:175], v243, s[92:93] offset:256
	v_add_u32_e32 v243, 0xc0000, v242
	global_load_dwordx4 v[176:179], v243, s[92:93] offset:256
	v_add_u32_e32 v243, 0x100000, v242
	global_load_dwordx4 v[180:183], v243, s[92:93] offset:256
	v_add_u32_e32 v243, 0x140000, v242
	global_load_dwordx4 v[184:187], v243, s[92:93] offset:256
	v_add_u32_e32 v243, 0x180000, v242
	global_load_dwordx4 v[188:191], v243, s[92:93] offset:256
	v_add_u32_e32 v243, 0x1c0000, v242
	global_load_dwordx4 v[192:195], v243, s[92:93] offset:256
	s_waitcnt lgkmcnt(0)
	s_barrier
	ds_read_b128 v[196:199], v2
	ds_read_b128 v[200:203], v2 offset:4096
	ds_read_b128 v[204:207], v208
	ds_read_b128 v[220:223], v208 offset:4096
	ds_read_b128 v[230:233], v2 offset:8192
	ds_read_b128 v[234:237], v2 offset:12288
	ds_read_b128 v[238:241], v208 offset:8192
	s_waitcnt vmcnt(12) lgkmcnt(6)
	v_mfma_f32_16x16x32_bf16 v[4:7], v[196:199], v[132:135], 0
	v_mfma_f32_16x16x32_bf16 v[68:71], v[196:199], v[148:151], 0
	ds_read_b128 v[196:199], v208 offset:12288
	s_waitcnt lgkmcnt(6)
	v_mfma_f32_16x16x32_bf16 v[8:11], v[200:203], v[132:135], 0
	v_mfma_f32_16x16x32_bf16 v[72:75], v[200:203], v[148:151], 0
	ds_read_b128 v[200:203], v2 offset:16384
	s_waitcnt lgkmcnt(6)
	v_mfma_f32_16x16x32_bf16 v[4:7], v[204:207], v[136:139], v[4:7]
	v_mfma_f32_16x16x32_bf16 v[68:71], v[204:207], v[152:155], v[68:71]
	ds_read_b128 v[204:207], v2 offset:20480
	s_waitcnt lgkmcnt(6)
	v_mfma_f32_16x16x32_bf16 v[8:11], v[220:223], v[136:139], v[8:11]
	v_mfma_f32_16x16x32_bf16 v[72:75], v[220:223], v[152:155], v[72:75]
	ds_read_b128 v[220:223], v208 offset:16384
	s_waitcnt lgkmcnt(6)
	v_mfma_f32_16x16x32_bf16 v[12:15], v[230:233], v[132:135], 0
	v_mfma_f32_16x16x32_bf16 v[76:79], v[230:233], v[148:151], 0
	ds_read_b128 v[230:233], v208 offset:20480
	s_waitcnt lgkmcnt(6)
	v_mfma_f32_16x16x32_bf16 v[16:19], v[234:237], v[132:135], 0
	v_mfma_f32_16x16x32_bf16 v[80:83], v[234:237], v[148:151], 0
	ds_read_b128 v[234:237], v2 offset:24576
	s_waitcnt lgkmcnt(6)
; #define LAS __attribute__((address_space(3)))
; __device__ __forceinline__ f32x4 mfma16(bf16x8 a, bf16x8 b, f32x4 c) { return __builtin_amdgcn_mfma_f32_16x16x32_bf16(a, b, c, 0, 0, 0); }
; #define LDS_BARRIER() do { asm volatile("s_waitcnt lgkmcnt(0)" ::: "memory"); __builtin_amdgcn_s_barrier(); asm volatile("" ::: "memory"); } while (0)
; #define XLOAD(kvbase, c8) do { const bf16_t* _src = (kvbase) + (((c8) >= 4) ? 2048 : 0) + ((c8) & 3) * 128 + piece * 8; \
;         _Pragma("unroll") for (int _it = 0; _it < 8; ++_it) pre[_it] = *(const u32x4*)(_src + (size_t)(srow + 32 * _it) * 4096); } while (0)
; #define XSTORE(buf) do { _Pragma("unroll") for (int _it = 0; _it < 8; ++_it) *(LAS u32x4*)((buf) + (srow + 32 * _it) * KV_STRIDE + piece * 16) = pre[_it]; } while (0)
; __device__ void cross_items(const Params& p, LAS unsigned char* lds) {
;     ...
;         for (int c = 0; c < 4; ++c) {
;             LAS unsigned char* buf = lds + (c & 1) * KV_BUF;
;             XSTORE(buf);
;             bf16x8 qf[4];
; #pragma unroll
;             for (int ks = 0; ks < 4; ++ks) qf[ks] = *(const bf16x8*)(qrow + c * 128 + 32 * ks);
;             XLOAD(kvb, c + 1);
;             LDS_BARRIER();
; #pragma unroll
;             for (int kt = 0; kt < 16; ++kt)
; #pragma unroll
;                 for (int ks = 0; ks < 4; ++ks) sc[kt] = mfma16(frag_row(buf, KV_STRIDE, 16 * kt, 32 * ks, idx, g), qf[ks], sc[kt]);
	v_mfma_f32_16x16x32_bf16 v[12:15], v[238:241], v[136:139], v[12:15]
	v_mfma_f32_16x16x32_bf16 v[76:79], v[238:241], v[152:155], v[76:79]
	ds_read_b128 v[238:241], v2 offset:28672
	s_waitcnt lgkmcnt(6)
	v_mfma_f32_16x16x32_bf16 v[16:19], v[196:199], v[136:139], v[16:19]
	v_mfma_f32_16x16x32_bf16 v[80:83], v[196:199], v[152:155], v[80:83]
	ds_read_b128 v[196:199], v208 offset:24576
	s_waitcnt lgkmcnt(6)
	v_mfma_f32_16x16x32_bf16 v[20:23], v[200:203], v[132:135], 0
	v_mfma_f32_16x16x32_bf16 v[84:87], v[200:203], v[148:151], 0
	ds_read_b128 v[200:203], v208 offset:28672
	s_waitcnt lgkmcnt(6)
	v_mfma_f32_16x16x32_bf16 v[24:27], v[204:207], v[132:135], 0
	v_mfma_f32_16x16x32_bf16 v[88:91], v[204:207], v[148:151], 0
	ds_read_b128 v[204:207], v2 offset:32768
	s_waitcnt lgkmcnt(6)
	v_mfma_f32_16x16x32_bf16 v[20:23], v[220:223], v[136:139], v[20:23]
	v_mfma_f32_16x16x32_bf16 v[84:87], v[220:223], v[152:155], v[84:87]
	ds_read_b128 v[220:223], v2 offset:36864
	s_waitcnt lgkmcnt(6)
	v_mfma_f32_16x16x32_bf16 v[24:27], v[230:233], v[136:139], v[24:27]
	v_mfma_f32_16x16x32_bf16 v[88:91], v[230:233], v[152:155], v[88:91]
	ds_read_b128 v[230:233], v208 offset:32768
	s_waitcnt lgkmcnt(6)
	v_mfma_f32_16x16x32_bf16 v[28:31], v[234:237], v[132:135], 0
	v_mfma_f32_16x16x32_bf16 v[92:95], v[234:237], v[148:151], 0
	ds_read_b128 v[234:237], v208 offset:36864
	s_waitcnt lgkmcnt(6)
	v_mfma_f32_16x16x32_bf16 v[32:35], v[238:241], v[132:135], 0
	v_mfma_f32_16x16x32_bf16 v[96:99], v[238:241], v[148:151], 0
	ds_read_b128 v[238:241], v2 offset:40960
	s_waitcnt lgkmcnt(6)
	v_mfma_f32_16x16x32_bf16 v[28:31], v[196:199], v[136:139], v[28:31]
	v_mfma_f32_16x16x32_bf16 v[92:95], v[196:199], v[152:155], v[92:95]
	ds_read_b128 v[196:199], v2 offset:45056
	s_waitcnt lgkmcnt(6)
	v_mfma_f32_16x16x32_bf16 v[32:35], v[200:203], v[136:139], v[32:35]
	v_mfma_f32_16x16x32_bf16 v[96:99], v[200:203], v[152:155], v[96:99]
	ds_read_b128 v[200:203], v208 offset:40960
	s_waitcnt lgkmcnt(6)
	v_mfma_f32_16x16x32_bf16 v[36:39], v[204:207], v[132:135], 0
	v_mfma_f32_16x16x32_bf16 v[100:103], v[204:207], v[148:151], 0
	ds_read_b128 v[204:207], v208 offset:45056
	s_waitcnt lgkmcnt(6)
	v_mfma_f32_16x16x32_bf16 v[40:43], v[220:223], v[132:135], 0
	v_mfma_f32_16x16x32_bf16 v[104:107], v[220:223], v[148:151], 0
	ds_read_b128 v[220:223], v2 offset:49152
	s_waitcnt lgkmcnt(6)
	v_mfma_f32_16x16x32_bf16 v[36:39], v[230:233], v[136:139], v[36:39]
	v_mfma_f32_16x16x32_bf16 v[100:103], v[230:233], v[152:155], v[100:103]
	ds_read_b128 v[230:233], v2 offset:53248
	s_waitcnt lgkmcnt(6)
	v_mfma_f32_16x16x32_bf16 v[40:43], v[234:237], v[136:139], v[40:43]
	v_mfma_f32_16x16x32_bf16 v[104:107], v[234:237], v[152:155], v[104:107]
	ds_read_b128 v[234:237], v208 offset:49152
	s_waitcnt lgkmcnt(6)
	v_mfma_f32_16x16x32_bf16 v[44:47], v[238:241], v[132:135], 0
	v_mfma_f32_16x16x32_bf16 v[108:111], v[238:241], v[148:151], 0
	ds_read_b128 v[238:241], v208 offset:53248
	s_waitcnt lgkmcnt(6)
	v_mfma_f32_16x16x32_bf16 v[48:51], v[196:199], v[132:135], 0
	v_mfma_f32_16x16x32_bf16 v[112:115], v[196:199], v[148:151], 0
	ds_read_b128 v[196:199], v2 offset:57344
	s_waitcnt lgkmcnt(6)
	v_mfma_f32_16x16x32_bf16 v[44:47], v[200:203], v[136:139], v[44:47]
	v_mfma_f32_16x16x32_bf16 v[108:111], v[200:203], v[152:155], v[108:111]
	ds_read_b128 v[200:203], v2 offset:61440
	s_waitcnt lgkmcnt(6)
	v_mfma_f32_16x16x32_bf16 v[48:51], v[204:207], v[136:139], v[48:51]
	v_mfma_f32_16x16x32_bf16 v[112:115], v[204:207], v[152:155], v[112:115]
	ds_read_b128 v[204:207], v208 offset:57344
	s_waitcnt lgkmcnt(6)
	v_mfma_f32_16x16x32_bf16 v[52:55], v[220:223], v[132:135], 0
	v_mfma_f32_16x16x32_bf16 v[116:119], v[220:223], v[148:151], 0
	ds_read_b128 v[220:223], v208 offset:61440
	s_waitcnt lgkmcnt(6)
	v_mfma_f32_16x16x32_bf16 v[56:59], v[230:233], v[132:135], 0
	v_mfma_f32_16x16x32_bf16 v[120:123], v[230:233], v[148:151], 0
	s_waitcnt lgkmcnt(5)
	v_mfma_f32_16x16x32_bf16 v[52:55], v[234:237], v[136:139], v[52:55]
	v_mfma_f32_16x16x32_bf16 v[116:119], v[234:237], v[152:155], v[116:119]
	s_waitcnt lgkmcnt(4)
	v_mfma_f32_16x16x32_bf16 v[56:59], v[238:241], v[136:139], v[56:59]
	v_mfma_f32_16x16x32_bf16 v[120:123], v[238:241], v[152:155], v[120:123]
	s_waitcnt lgkmcnt(3)
	v_mfma_f32_16x16x32_bf16 v[60:63], v[196:199], v[132:135], 0
	v_mfma_f32_16x16x32_bf16 v[124:127], v[196:199], v[148:151], 0
	s_waitcnt lgkmcnt(2)
	v_mfma_f32_16x16x32_bf16 v[64:67], v[200:203], v[132:135], 0
	v_mfma_f32_16x16x32_bf16 v[128:131], v[200:203], v[148:151], 0
	s_waitcnt lgkmcnt(1)
	v_mfma_f32_16x16x32_bf16 v[60:63], v[204:207], v[136:139], v[60:63]
	v_mfma_f32_16x16x32_bf16 v[124:127], v[204:207], v[152:155], v[124:127]
	s_waitcnt lgkmcnt(0)
	v_mfma_f32_16x16x32_bf16 v[64:67], v[220:223], v[136:139], v[64:67]
	v_mfma_f32_16x16x32_bf16 v[128:131], v[220:223], v[152:155], v[128:131]
	global_load_dwordx4 v[132:135], v246, s[92:93] offset:256
	global_load_dwordx4 v[136:139], v246, s[92:93] offset:320
	global_load_dwordx4 v[148:151], v247, s[92:93] offset:256
	global_load_dwordx4 v[152:155], v247, s[92:93] offset:320
	ds_read_b128 v[196:199], v209
	ds_read_b128 v[200:203], v209 offset:4096
	ds_read_b128 v[204:207], v210
	ds_read_b128 v[220:223], v210 offset:4096
	ds_read_b128 v[230:233], v209 offset:8192
	ds_read_b128 v[234:237], v209 offset:12288
	ds_read_b128 v[238:241], v210 offset:8192
	s_waitcnt vmcnt(12) lgkmcnt(6)
	v_mfma_f32_16x16x32_bf16 v[4:7], v[196:199], v[140:143], v[4:7]
	v_mfma_f32_16x16x32_bf16 v[68:71], v[196:199], v[156:159], v[68:71]
	ds_read_b128 v[196:199], v210 offset:12288
	s_waitcnt lgkmcnt(6)
; __device__ __forceinline__ f32x4 mfma16(bf16x8 a, bf16x8 b, f32x4 c) { return __builtin_amdgcn_mfma_f32_16x16x32_bf16(a, b, c, 0, 0, 0); }
; __device__ void cross_items(const Params& p, LAS unsigned char* lds) {
;     ...
; #pragma unroll
;             for (int kt = 0; kt < 16; ++kt)
; #pragma unroll
;                 for (int ks = 0; ks < 4; ++ks) sc[kt] = mfma16(frag_row(buf, KV_STRIDE, 16 * kt, 32 * ks, idx, g), qf[ks], sc[kt]);
	v_mfma_f32_16x16x32_bf16 v[8:11], v[200:203], v[140:143], v[8:11]
	v_mfma_f32_16x16x32_bf16 v[72:75], v[200:203], v[156:159], v[72:75]
	ds_read_b128 v[200:203], v209 offset:16384
	s_waitcnt lgkmcnt(6)
	v_mfma_f32_16x16x32_bf16 v[4:7], v[204:207], v[144:147], v[4:7]
	v_mfma_f32_16x16x32_bf16 v[68:71], v[204:207], v[160:163], v[68:71]
	ds_read_b128 v[204:207], v209 offset:20480
	s_waitcnt lgkmcnt(6)
	v_mfma_f32_16x16x32_bf16 v[8:11], v[220:223], v[144:147], v[8:11]
	v_mfma_f32_16x16x32_bf16 v[72:75], v[220:223], v[160:163], v[72:75]
	ds_read_b128 v[220:223], v210 offset:16384
	s_waitcnt lgkmcnt(6)
	v_mfma_f32_16x16x32_bf16 v[12:15], v[230:233], v[140:143], v[12:15]
	v_mfma_f32_16x16x32_bf16 v[76:79], v[230:233], v[156:159], v[76:79]
	ds_read_b128 v[230:233], v210 offset:20480
	s_waitcnt lgkmcnt(6)
	v_mfma_f32_16x16x32_bf16 v[16:19], v[234:237], v[140:143], v[16:19]
	v_mfma_f32_16x16x32_bf16 v[80:83], v[234:237], v[156:159], v[80:83]
	ds_read_b128 v[234:237], v209 offset:24576
	s_waitcnt lgkmcnt(6)
	v_mfma_f32_16x16x32_bf16 v[12:15], v[238:241], v[144:147], v[12:15]
	v_mfma_f32_16x16x32_bf16 v[76:79], v[238:241], v[160:163], v[76:79]
	ds_read_b128 v[238:241], v209 offset:28672
	s_waitcnt lgkmcnt(6)
	v_mfma_f32_16x16x32_bf16 v[16:19], v[196:199], v[144:147], v[16:19]
	v_mfma_f32_16x16x32_bf16 v[80:83], v[196:199], v[160:163], v[80:83]
	ds_read_b128 v[196:199], v210 offset:24576
	s_waitcnt lgkmcnt(6)
	v_mfma_f32_16x16x32_bf16 v[20:23], v[200:203], v[140:143], v[20:23]
	v_mfma_f32_16x16x32_bf16 v[84:87], v[200:203], v[156:159], v[84:87]
	ds_read_b128 v[200:203], v210 offset:28672
	s_waitcnt lgkmcnt(6)
	v_mfma_f32_16x16x32_bf16 v[24:27], v[204:207], v[140:143], v[24:27]
	v_mfma_f32_16x16x32_bf16 v[88:91], v[204:207], v[156:159], v[88:91]
	ds_read_b128 v[204:207], v209 offset:32768
	s_waitcnt lgkmcnt(6)
	v_mfma_f32_16x16x32_bf16 v[20:23], v[220:223], v[144:147], v[20:23]
	v_mfma_f32_16x16x32_bf16 v[84:87], v[220:223], v[160:163], v[84:87]
	ds_read_b128 v[220:223], v209 offset:36864
	s_waitcnt lgkmcnt(6)
	v_mfma_f32_16x16x32_bf16 v[24:27], v[230:233], v[144:147], v[24:27]
	v_mfma_f32_16x16x32_bf16 v[88:91], v[230:233], v[160:163], v[88:91]
	ds_read_b128 v[230:233], v210 offset:32768
	s_waitcnt lgkmcnt(6)
	v_mfma_f32_16x16x32_bf16 v[28:31], v[234:237], v[140:143], v[28:31]
	v_mfma_f32_16x16x32_bf16 v[92:95], v[234:237], v[156:159], v[92:95]
	ds_read_b128 v[234:237], v210 offset:36864
	s_waitcnt lgkmcnt(6)
	v_mfma_f32_16x16x32_bf16 v[32:35], v[238:241], v[140:143], v[32:35]
	v_mfma_f32_16x16x32_bf16 v[96:99], v[238:241], v[156:159], v[96:99]
	ds_read_b128 v[238:241], v209 offset:40960
	s_waitcnt lgkmcnt(6)
	v_mfma_f32_16x16x32_bf16 v[28:31], v[196:199], v[144:147], v[28:31]
	v_mfma_f32_16x16x32_bf16 v[92:95], v[196:199], v[160:163], v[92:95]
	ds_read_b128 v[196:199], v209 offset:45056
	s_waitcnt lgkmcnt(6)
	v_mfma_f32_16x16x32_bf16 v[32:35], v[200:203], v[144:147], v[32:35]
	v_mfma_f32_16x16x32_bf16 v[96:99], v[200:203], v[160:163], v[96:99]
	ds_read_b128 v[200:203], v210 offset:40960
	s_waitcnt lgkmcnt(6)
	v_mfma_f32_16x16x32_bf16 v[36:39], v[204:207], v[140:143], v[36:39]
	v_mfma_f32_16x16x32_bf16 v[100:103], v[204:207], v[156:159], v[100:103]
	ds_read_b128 v[204:207], v210 offset:45056
	s_waitcnt lgkmcnt(6)
	v_mfma_f32_16x16x32_bf16 v[40:43], v[220:223], v[140:143], v[40:43]
	v_mfma_f32_16x16x32_bf16 v[104:107], v[220:223], v[156:159], v[104:107]
	ds_read_b128 v[220:223], v209 offset:49152
	s_waitcnt lgkmcnt(6)
	v_mfma_f32_16x16x32_bf16 v[36:39], v[230:233], v[144:147], v[36:39]
	v_mfma_f32_16x16x32_bf16 v[100:103], v[230:233], v[160:163], v[100:103]
	ds_read_b128 v[230:233], v209 offset:53248
	s_waitcnt lgkmcnt(6)
	v_mfma_f32_16x16x32_bf16 v[40:43], v[234:237], v[144:147], v[40:43]
	v_mfma_f32_16x16x32_bf16 v[104:107], v[234:237], v[160:163], v[104:107]
	ds_read_b128 v[234:237], v210 offset:49152
	s_waitcnt lgkmcnt(6)
	v_mfma_f32_16x16x32_bf16 v[44:47], v[238:241], v[140:143], v[44:47]
	v_mfma_f32_16x16x32_bf16 v[108:111], v[238:241], v[156:159], v[108:111]
	ds_read_b128 v[238:241], v210 offset:53248
	s_waitcnt lgkmcnt(6)
	v_mfma_f32_16x16x32_bf16 v[48:51], v[196:199], v[140:143], v[48:51]
	v_mfma_f32_16x16x32_bf16 v[112:115], v[196:199], v[156:159], v[112:115]
	ds_read_b128 v[196:199], v209 offset:57344
	s_waitcnt lgkmcnt(6)
	v_mfma_f32_16x16x32_bf16 v[44:47], v[200:203], v[144:147], v[44:47]
	v_mfma_f32_16x16x32_bf16 v[108:111], v[200:203], v[160:163], v[108:111]
	ds_read_b128 v[200:203], v209 offset:61440
	s_waitcnt lgkmcnt(6)
	v_mfma_f32_16x16x32_bf16 v[48:51], v[204:207], v[144:147], v[48:51]
	v_mfma_f32_16x16x32_bf16 v[112:115], v[204:207], v[160:163], v[112:115]
	ds_read_b128 v[204:207], v210 offset:57344
	s_waitcnt lgkmcnt(6)
	v_mfma_f32_16x16x32_bf16 v[52:55], v[220:223], v[140:143], v[52:55]
	v_mfma_f32_16x16x32_bf16 v[116:119], v[220:223], v[156:159], v[116:119]
	ds_read_b128 v[220:223], v210 offset:61440
	s_waitcnt lgkmcnt(6)
	v_mfma_f32_16x16x32_bf16 v[56:59], v[230:233], v[140:143], v[56:59]
	v_mfma_f32_16x16x32_bf16 v[120:123], v[230:233], v[156:159], v[120:123]
	s_waitcnt lgkmcnt(5)
	v_mfma_f32_16x16x32_bf16 v[52:55], v[234:237], v[144:147], v[52:55]
	v_mfma_f32_16x16x32_bf16 v[116:119], v[234:237], v[160:163], v[116:119]
	s_waitcnt lgkmcnt(4)
	v_mfma_f32_16x16x32_bf16 v[56:59], v[238:241], v[144:147], v[56:59]
	v_mfma_f32_16x16x32_bf16 v[120:123], v[238:241], v[160:163], v[120:123]
	s_waitcnt lgkmcnt(3)
	v_mfma_f32_16x16x32_bf16 v[60:63], v[196:199], v[140:143], v[60:63]
	v_mfma_f32_16x16x32_bf16 v[124:127], v[196:199], v[156:159], v[124:127]
	s_waitcnt lgkmcnt(2)
; #define LAS __attribute__((address_space(3)))
; __device__ __forceinline__ f32x4 mfma16(bf16x8 a, bf16x8 b, f32x4 c) { return __builtin_amdgcn_mfma_f32_16x16x32_bf16(a, b, c, 0, 0, 0); }
; #define LDS_BARRIER() do { asm volatile("s_waitcnt lgkmcnt(0)" ::: "memory"); __builtin_amdgcn_s_barrier(); asm volatile("" ::: "memory"); } while (0)
; #define XLOAD(kvbase, c8) do { const bf16_t* _src = (kvbase) + (((c8) >= 4) ? 2048 : 0) + ((c8) & 3) * 128 + piece * 8; \
;         _Pragma("unroll") for (int _it = 0; _it < 8; ++_it) pre[_it] = *(const u32x4*)(_src + (size_t)(srow + 32 * _it) * 4096); } while (0)
; #define XSTORE(buf) do { _Pragma("unroll") for (int _it = 0; _it < 8; ++_it) *(LAS u32x4*)((buf) + (srow + 32 * _it) * KV_STRIDE + piece * 16) = pre[_it]; } while (0)
; __device__ void cross_items(const Params& p, LAS unsigned char* lds) {
;     ...
;         for (int c = 0; c < 4; ++c) {
;             LAS unsigned char* buf = lds + (c & 1) * KV_BUF;
;             XSTORE(buf);
;             bf16x8 qf[4];
; #pragma unroll
;             for (int ks = 0; ks < 4; ++ks) qf[ks] = *(const bf16x8*)(qrow + c * 128 + 32 * ks);
;             XLOAD(kvb, c + 1);
;             LDS_BARRIER();
; #pragma unroll
;             for (int kt = 0; kt < 16; ++kt)
; #pragma unroll
;                 for (int ks = 0; ks < 4; ++ks) sc[kt] = mfma16(frag_row(buf, KV_STRIDE, 16 * kt, 32 * ks, idx, g), qf[ks], sc[kt]);
	v_mfma_f32_16x16x32_bf16 v[64:67], v[200:203], v[140:143], v[64:67]
	v_mfma_f32_16x16x32_bf16 v[128:131], v[200:203], v[156:159], v[128:131]
	s_waitcnt lgkmcnt(1)
	v_mfma_f32_16x16x32_bf16 v[60:63], v[204:207], v[144:147], v[60:63]
	v_mfma_f32_16x16x32_bf16 v[124:127], v[204:207], v[160:163], v[124:127]
	s_waitcnt lgkmcnt(0)
	v_mfma_f32_16x16x32_bf16 v[64:67], v[220:223], v[144:147], v[64:67]
	v_mfma_f32_16x16x32_bf16 v[128:131], v[220:223], v[160:163], v[128:131]
	global_load_dwordx4 v[140:143], v246, s[92:93] offset:384
	global_load_dwordx4 v[144:147], v246, s[92:93] offset:448
	global_load_dwordx4 v[156:159], v247, s[92:93] offset:384
	global_load_dwordx4 v[160:163], v247, s[92:93] offset:448
	v_xor_b32_e32 v2, 0x10000, v2
	v_xor_b32_e32 v208, 0x10000, v208
	v_xor_b32_e32 v209, 0x10000, v209
	v_xor_b32_e32 v210, 0x10000, v210
	s_waitcnt vmcnt(15)
	ds_write_b128 v1, v[164:167]
	s_waitcnt vmcnt(14)
	ds_write_b128 v1, v[168:171] offset:8192
	s_waitcnt vmcnt(13)
	ds_write_b128 v1, v[172:175] offset:16384
	s_waitcnt vmcnt(12)
	ds_write_b128 v1, v[176:179] offset:24576
	s_waitcnt vmcnt(11)
	ds_write_b128 v1, v[180:183] offset:32768
	s_waitcnt vmcnt(10)
	ds_write_b128 v1, v[184:187] offset:40960
	s_waitcnt vmcnt(9)
	ds_write_b128 v1, v[188:191] offset:49152
	s_waitcnt vmcnt(8)
	ds_write_b128 v1, v[192:195] offset:57344
	global_load_dwordx4 v[164:167], v242, s[92:93] offset:512
	v_add_u32_e32 v243, 0x40000, v242
	global_load_dwordx4 v[168:171], v243, s[92:93] offset:512
	v_add_u32_e32 v243, 0x80000, v242
	global_load_dwordx4 v[172:175], v243, s[92:93] offset:512
	v_add_u32_e32 v243, 0xc0000, v242
	global_load_dwordx4 v[176:179], v243, s[92:93] offset:512
	v_add_u32_e32 v243, 0x100000, v242
	global_load_dwordx4 v[180:183], v243, s[92:93] offset:512
	v_add_u32_e32 v243, 0x140000, v242
	global_load_dwordx4 v[184:187], v243, s[92:93] offset:512
	v_add_u32_e32 v243, 0x180000, v242
	global_load_dwordx4 v[188:191], v243, s[92:93] offset:512
	v_add_u32_e32 v243, 0x1c0000, v242
	global_load_dwordx4 v[192:195], v243, s[92:93] offset:512
	s_waitcnt lgkmcnt(0)
	s_barrier
	ds_read_b128 v[196:199], v2
	ds_read_b128 v[200:203], v2 offset:4096
	ds_read_b128 v[204:207], v208
	ds_read_b128 v[220:223], v208 offset:4096
	ds_read_b128 v[230:233], v2 offset:8192
	ds_read_b128 v[234:237], v2 offset:12288
	ds_read_b128 v[238:241], v208 offset:8192
	s_waitcnt vmcnt(12) lgkmcnt(6)
	v_mfma_f32_16x16x32_bf16 v[4:7], v[196:199], v[132:135], v[4:7]
	v_mfma_f32_16x16x32_bf16 v[68:71], v[196:199], v[148:151], v[68:71]
	ds_read_b128 v[196:199], v208 offset:12288
	s_waitcnt lgkmcnt(6)
	v_mfma_f32_16x16x32_bf16 v[8:11], v[200:203], v[132:135], v[8:11]
	v_mfma_f32_16x16x32_bf16 v[72:75], v[200:203], v[148:151], v[72:75]
	ds_read_b128 v[200:203], v2 offset:16384
	s_waitcnt lgkmcnt(6)
	v_mfma_f32_16x16x32_bf16 v[4:7], v[204:207], v[136:139], v[4:7]
	v_mfma_f32_16x16x32_bf16 v[68:71], v[204:207], v[152:155], v[68:71]
	ds_read_b128 v[204:207], v2 offset:20480
	s_waitcnt lgkmcnt(6)
	v_mfma_f32_16x16x32_bf16 v[8:11], v[220:223], v[136:139], v[8:11]
	v_mfma_f32_16x16x32_bf16 v[72:75], v[220:223], v[152:155], v[72:75]
	ds_read_b128 v[220:223], v208 offset:16384
	s_waitcnt lgkmcnt(6)
	v_mfma_f32_16x16x32_bf16 v[12:15], v[230:233], v[132:135], v[12:15]
	v_mfma_f32_16x16x32_bf16 v[76:79], v[230:233], v[148:151], v[76:79]
	ds_read_b128 v[230:233], v208 offset:20480
	s_waitcnt lgkmcnt(6)
	v_mfma_f32_16x16x32_bf16 v[16:19], v[234:237], v[132:135], v[16:19]
	v_mfma_f32_16x16x32_bf16 v[80:83], v[234:237], v[148:151], v[80:83]
	ds_read_b128 v[234:237], v2 offset:24576
	s_waitcnt lgkmcnt(6)
	v_mfma_f32_16x16x32_bf16 v[12:15], v[238:241], v[136:139], v[12:15]
	v_mfma_f32_16x16x32_bf16 v[76:79], v[238:241], v[152:155], v[76:79]
	ds_read_b128 v[238:241], v2 offset:28672
	s_waitcnt lgkmcnt(6)
	v_mfma_f32_16x16x32_bf16 v[16:19], v[196:199], v[136:139], v[16:19]
	v_mfma_f32_16x16x32_bf16 v[80:83], v[196:199], v[152:155], v[80:83]
	ds_read_b128 v[196:199], v208 offset:24576
	s_waitcnt lgkmcnt(6)
	v_mfma_f32_16x16x32_bf16 v[20:23], v[200:203], v[132:135], v[20:23]
	v_mfma_f32_16x16x32_bf16 v[84:87], v[200:203], v[148:151], v[84:87]
	ds_read_b128 v[200:203], v208 offset:28672
	s_waitcnt lgkmcnt(6)
	v_mfma_f32_16x16x32_bf16 v[24:27], v[204:207], v[132:135], v[24:27]
	v_mfma_f32_16x16x32_bf16 v[88:91], v[204:207], v[148:151], v[88:91]
	ds_read_b128 v[204:207], v2 offset:32768
	s_waitcnt lgkmcnt(6)
	v_mfma_f32_16x16x32_bf16 v[20:23], v[220:223], v[136:139], v[20:23]
	v_mfma_f32_16x16x32_bf16 v[84:87], v[220:223], v[152:155], v[84:87]
	ds_read_b128 v[220:223], v2 offset:36864
	s_waitcnt lgkmcnt(6)
	v_mfma_f32_16x16x32_bf16 v[24:27], v[230:233], v[136:139], v[24:27]
	v_mfma_f32_16x16x32_bf16 v[88:91], v[230:233], v[152:155], v[88:91]
	ds_read_b128 v[230:233], v208 offset:32768
	s_waitcnt lgkmcnt(6)
	v_mfma_f32_16x16x32_bf16 v[28:31], v[234:237], v[132:135], v[28:31]
	v_mfma_f32_16x16x32_bf16 v[92:95], v[234:237], v[148:151], v[92:95]
	ds_read_b128 v[234:237], v208 offset:36864
	s_waitcnt lgkmcnt(6)
	v_mfma_f32_16x16x32_bf16 v[32:35], v[238:241], v[132:135], v[32:35]
	v_mfma_f32_16x16x32_bf16 v[96:99], v[238:241], v[148:151], v[96:99]
	ds_read_b128 v[238:241], v2 offset:40960
	s_waitcnt lgkmcnt(6)
	v_mfma_f32_16x16x32_bf16 v[28:31], v[196:199], v[136:139], v[28:31]
	v_mfma_f32_16x16x32_bf16 v[92:95], v[196:199], v[152:155], v[92:95]
	ds_read_b128 v[196:199], v2 offset:45056
	s_waitcnt lgkmcnt(6)
	v_mfma_f32_16x16x32_bf16 v[32:35], v[200:203], v[136:139], v[32:35]
	v_mfma_f32_16x16x32_bf16 v[96:99], v[200:203], v[152:155], v[96:99]
	ds_read_b128 v[200:203], v208 offset:40960
	s_waitcnt lgkmcnt(6)
; __device__ __forceinline__ f32x4 mfma16(bf16x8 a, bf16x8 b, f32x4 c) { return __builtin_amdgcn_mfma_f32_16x16x32_bf16(a, b, c, 0, 0, 0); }
; __device__ void cross_items(const Params& p, LAS unsigned char* lds) {
;     ...
;             for (int ks = 0; ks < 4; ++ks) qf[ks] = *(const bf16x8*)(qrow + c * 128 + 32 * ks);
;     ...
;             for (int kt = 0; kt < 16; ++kt)
; #pragma unroll
;                 for (int ks = 0; ks < 4; ++ks) sc[kt] = mfma16(frag_row(buf, KV_STRIDE, 16 * kt, 32 * ks, idx, g), qf[ks], sc[kt]);
	v_mfma_f32_16x16x32_bf16 v[36:39], v[204:207], v[132:135], v[36:39]
	v_mfma_f32_16x16x32_bf16 v[100:103], v[204:207], v[148:151], v[100:103]
	ds_read_b128 v[204:207], v208 offset:45056
	s_waitcnt lgkmcnt(6)
	v_mfma_f32_16x16x32_bf16 v[40:43], v[220:223], v[132:135], v[40:43]
	v_mfma_f32_16x16x32_bf16 v[104:107], v[220:223], v[148:151], v[104:107]
	ds_read_b128 v[220:223], v2 offset:49152
	s_waitcnt lgkmcnt(6)
	v_mfma_f32_16x16x32_bf16 v[36:39], v[230:233], v[136:139], v[36:39]
	v_mfma_f32_16x16x32_bf16 v[100:103], v[230:233], v[152:155], v[100:103]
	ds_read_b128 v[230:233], v2 offset:53248
	s_waitcnt lgkmcnt(6)
	v_mfma_f32_16x16x32_bf16 v[40:43], v[234:237], v[136:139], v[40:43]
	v_mfma_f32_16x16x32_bf16 v[104:107], v[234:237], v[152:155], v[104:107]
	ds_read_b128 v[234:237], v208 offset:49152
	s_waitcnt lgkmcnt(6)
	v_mfma_f32_16x16x32_bf16 v[44:47], v[238:241], v[132:135], v[44:47]
	v_mfma_f32_16x16x32_bf16 v[108:111], v[238:241], v[148:151], v[108:111]
	ds_read_b128 v[238:241], v208 offset:53248
	s_waitcnt lgkmcnt(6)
	v_mfma_f32_16x16x32_bf16 v[48:51], v[196:199], v[132:135], v[48:51]
	v_mfma_f32_16x16x32_bf16 v[112:115], v[196:199], v[148:151], v[112:115]
	ds_read_b128 v[196:199], v2 offset:57344
	s_waitcnt lgkmcnt(6)
	v_mfma_f32_16x16x32_bf16 v[44:47], v[200:203], v[136:139], v[44:47]
	v_mfma_f32_16x16x32_bf16 v[108:111], v[200:203], v[152:155], v[108:111]
	ds_read_b128 v[200:203], v2 offset:61440
	s_waitcnt lgkmcnt(6)
	v_mfma_f32_16x16x32_bf16 v[48:51], v[204:207], v[136:139], v[48:51]
	v_mfma_f32_16x16x32_bf16 v[112:115], v[204:207], v[152:155], v[112:115]
	ds_read_b128 v[204:207], v208 offset:57344
	s_waitcnt lgkmcnt(6)
	v_mfma_f32_16x16x32_bf16 v[52:55], v[220:223], v[132:135], v[52:55]
	v_mfma_f32_16x16x32_bf16 v[116:119], v[220:223], v[148:151], v[116:119]
	ds_read_b128 v[220:223], v208 offset:61440
	s_waitcnt lgkmcnt(6)
	v_mfma_f32_16x16x32_bf16 v[56:59], v[230:233], v[132:135], v[56:59]
	v_mfma_f32_16x16x32_bf16 v[120:123], v[230:233], v[148:151], v[120:123]
	s_waitcnt lgkmcnt(5)
	v_mfma_f32_16x16x32_bf16 v[52:55], v[234:237], v[136:139], v[52:55]
	v_mfma_f32_16x16x32_bf16 v[116:119], v[234:237], v[152:155], v[116:119]
	s_waitcnt lgkmcnt(4)
	v_mfma_f32_16x16x32_bf16 v[56:59], v[238:241], v[136:139], v[56:59]
	v_mfma_f32_16x16x32_bf16 v[120:123], v[238:241], v[152:155], v[120:123]
	s_waitcnt lgkmcnt(3)
	v_mfma_f32_16x16x32_bf16 v[60:63], v[196:199], v[132:135], v[60:63]
	v_mfma_f32_16x16x32_bf16 v[124:127], v[196:199], v[148:151], v[124:127]
	s_waitcnt lgkmcnt(2)
	v_mfma_f32_16x16x32_bf16 v[64:67], v[200:203], v[132:135], v[64:67]
	v_mfma_f32_16x16x32_bf16 v[128:131], v[200:203], v[148:151], v[128:131]
	s_waitcnt lgkmcnt(1)
	v_mfma_f32_16x16x32_bf16 v[60:63], v[204:207], v[136:139], v[60:63]
	v_mfma_f32_16x16x32_bf16 v[124:127], v[204:207], v[152:155], v[124:127]
	s_waitcnt lgkmcnt(0)
	v_mfma_f32_16x16x32_bf16 v[64:67], v[220:223], v[136:139], v[64:67]
	v_mfma_f32_16x16x32_bf16 v[128:131], v[220:223], v[152:155], v[128:131]
	global_load_dwordx4 v[132:135], v246, s[92:93] offset:512
	global_load_dwordx4 v[136:139], v246, s[92:93] offset:576
	global_load_dwordx4 v[148:151], v247, s[92:93] offset:512
	global_load_dwordx4 v[152:155], v247, s[92:93] offset:576
	ds_read_b128 v[196:199], v209
	ds_read_b128 v[200:203], v209 offset:4096
	ds_read_b128 v[204:207], v210
	ds_read_b128 v[220:223], v210 offset:4096
	ds_read_b128 v[230:233], v209 offset:8192
	ds_read_b128 v[234:237], v209 offset:12288
	ds_read_b128 v[238:241], v210 offset:8192
	s_waitcnt vmcnt(12) lgkmcnt(6)
	v_mfma_f32_16x16x32_bf16 v[4:7], v[196:199], v[140:143], v[4:7]
	v_mfma_f32_16x16x32_bf16 v[68:71], v[196:199], v[156:159], v[68:71]
	ds_read_b128 v[196:199], v210 offset:12288
	s_waitcnt lgkmcnt(6)
	v_mfma_f32_16x16x32_bf16 v[8:11], v[200:203], v[140:143], v[8:11]
	v_mfma_f32_16x16x32_bf16 v[72:75], v[200:203], v[156:159], v[72:75]
	ds_read_b128 v[200:203], v209 offset:16384
	s_waitcnt lgkmcnt(6)
	v_mfma_f32_16x16x32_bf16 v[4:7], v[204:207], v[144:147], v[4:7]
	v_mfma_f32_16x16x32_bf16 v[68:71], v[204:207], v[160:163], v[68:71]
	ds_read_b128 v[204:207], v209 offset:20480
	s_waitcnt lgkmcnt(6)
	v_mfma_f32_16x16x32_bf16 v[8:11], v[220:223], v[144:147], v[8:11]
	v_mfma_f32_16x16x32_bf16 v[72:75], v[220:223], v[160:163], v[72:75]
	ds_read_b128 v[220:223], v210 offset:16384
	s_waitcnt lgkmcnt(6)
	v_mfma_f32_16x16x32_bf16 v[12:15], v[230:233], v[140:143], v[12:15]
	v_mfma_f32_16x16x32_bf16 v[76:79], v[230:233], v[156:159], v[76:79]
	ds_read_b128 v[230:233], v210 offset:20480
	s_waitcnt lgkmcnt(6)
	v_mfma_f32_16x16x32_bf16 v[16:19], v[234:237], v[140:143], v[16:19]
	v_mfma_f32_16x16x32_bf16 v[80:83], v[234:237], v[156:159], v[80:83]
	ds_read_b128 v[234:237], v209 offset:24576
	s_waitcnt lgkmcnt(6)
	v_mfma_f32_16x16x32_bf16 v[12:15], v[238:241], v[144:147], v[12:15]
	v_mfma_f32_16x16x32_bf16 v[76:79], v[238:241], v[160:163], v[76:79]
	ds_read_b128 v[238:241], v209 offset:28672
	s_waitcnt lgkmcnt(6)
	v_mfma_f32_16x16x32_bf16 v[16:19], v[196:199], v[144:147], v[16:19]
	v_mfma_f32_16x16x32_bf16 v[80:83], v[196:199], v[160:163], v[80:83]
	ds_read_b128 v[196:199], v210 offset:24576
	s_waitcnt lgkmcnt(6)
	v_mfma_f32_16x16x32_bf16 v[20:23], v[200:203], v[140:143], v[20:23]
	v_mfma_f32_16x16x32_bf16 v[84:87], v[200:203], v[156:159], v[84:87]
	ds_read_b128 v[200:203], v210 offset:28672
	s_waitcnt lgkmcnt(6)
	v_mfma_f32_16x16x32_bf16 v[24:27], v[204:207], v[140:143], v[24:27]
	v_mfma_f32_16x16x32_bf16 v[88:91], v[204:207], v[156:159], v[88:91]
	ds_read_b128 v[204:207], v209 offset:32768
	s_waitcnt lgkmcnt(6)
; __device__ __forceinline__ f32x4 mfma16(bf16x8 a, bf16x8 b, f32x4 c) { return __builtin_amdgcn_mfma_f32_16x16x32_bf16(a, b, c, 0, 0, 0); }
; #define XLOAD(kvbase, c8) do { const bf16_t* _src = (kvbase) + (((c8) >= 4) ? 2048 : 0) + ((c8) & 3) * 128 + piece * 8; \
;         _Pragma("unroll") for (int _it = 0; _it < 8; ++_it) pre[_it] = *(const u32x4*)(_src + (size_t)(srow + 32 * _it) * 4096); } while (0)
; #define XSTORE(buf) do { _Pragma("unroll") for (int _it = 0; _it < 8; ++_it) *(LAS u32x4*)((buf) + (srow + 32 * _it) * KV_STRIDE + piece * 16) = pre[_it]; } while (0)
; __device__ void cross_items(const Params& p, LAS unsigned char* lds) {
;     ...
;             XSTORE(buf);
;             bf16x8 qf[4];
; #pragma unroll
;             for (int ks = 0; ks < 4; ++ks) qf[ks] = *(const bf16x8*)(qrow + c * 128 + 32 * ks);
;             XLOAD(kvb, c + 1);
;     ...
;             for (int kt = 0; kt < 16; ++kt)
; #pragma unroll
;                 for (int ks = 0; ks < 4; ++ks) sc[kt] = mfma16(frag_row(buf, KV_STRIDE, 16 * kt, 32 * ks, idx, g), qf[ks], sc[kt]);
	v_mfma_f32_16x16x32_bf16 v[20:23], v[220:223], v[144:147], v[20:23]
	v_mfma_f32_16x16x32_bf16 v[84:87], v[220:223], v[160:163], v[84:87]
	ds_read_b128 v[220:223], v209 offset:36864
	s_waitcnt lgkmcnt(6)
	v_mfma_f32_16x16x32_bf16 v[24:27], v[230:233], v[144:147], v[24:27]
	v_mfma_f32_16x16x32_bf16 v[88:91], v[230:233], v[160:163], v[88:91]
	ds_read_b128 v[230:233], v210 offset:32768
	s_waitcnt lgkmcnt(6)
	v_mfma_f32_16x16x32_bf16 v[28:31], v[234:237], v[140:143], v[28:31]
	v_mfma_f32_16x16x32_bf16 v[92:95], v[234:237], v[156:159], v[92:95]
	ds_read_b128 v[234:237], v210 offset:36864
	s_waitcnt lgkmcnt(6)
	v_mfma_f32_16x16x32_bf16 v[32:35], v[238:241], v[140:143], v[32:35]
	v_mfma_f32_16x16x32_bf16 v[96:99], v[238:241], v[156:159], v[96:99]
	ds_read_b128 v[238:241], v209 offset:40960
	s_waitcnt lgkmcnt(6)
	v_mfma_f32_16x16x32_bf16 v[28:31], v[196:199], v[144:147], v[28:31]
	v_mfma_f32_16x16x32_bf16 v[92:95], v[196:199], v[160:163], v[92:95]
	ds_read_b128 v[196:199], v209 offset:45056
	s_waitcnt lgkmcnt(6)
	v_mfma_f32_16x16x32_bf16 v[32:35], v[200:203], v[144:147], v[32:35]
	v_mfma_f32_16x16x32_bf16 v[96:99], v[200:203], v[160:163], v[96:99]
	ds_read_b128 v[200:203], v210 offset:40960
	s_waitcnt lgkmcnt(6)
	v_mfma_f32_16x16x32_bf16 v[36:39], v[204:207], v[140:143], v[36:39]
	v_mfma_f32_16x16x32_bf16 v[100:103], v[204:207], v[156:159], v[100:103]
	ds_read_b128 v[204:207], v210 offset:45056
	s_waitcnt lgkmcnt(6)
	v_mfma_f32_16x16x32_bf16 v[40:43], v[220:223], v[140:143], v[40:43]
	v_mfma_f32_16x16x32_bf16 v[104:107], v[220:223], v[156:159], v[104:107]
	ds_read_b128 v[220:223], v209 offset:49152
	s_waitcnt lgkmcnt(6)
	v_mfma_f32_16x16x32_bf16 v[36:39], v[230:233], v[144:147], v[36:39]
	v_mfma_f32_16x16x32_bf16 v[100:103], v[230:233], v[160:163], v[100:103]
	ds_read_b128 v[230:233], v209 offset:53248
	s_waitcnt lgkmcnt(6)
	v_mfma_f32_16x16x32_bf16 v[40:43], v[234:237], v[144:147], v[40:43]
	v_mfma_f32_16x16x32_bf16 v[104:107], v[234:237], v[160:163], v[104:107]
	ds_read_b128 v[234:237], v210 offset:49152
	s_waitcnt lgkmcnt(6)
	v_mfma_f32_16x16x32_bf16 v[44:47], v[238:241], v[140:143], v[44:47]
	v_mfma_f32_16x16x32_bf16 v[108:111], v[238:241], v[156:159], v[108:111]
	ds_read_b128 v[238:241], v210 offset:53248
	s_waitcnt lgkmcnt(6)
	v_mfma_f32_16x16x32_bf16 v[48:51], v[196:199], v[140:143], v[48:51]
	v_mfma_f32_16x16x32_bf16 v[112:115], v[196:199], v[156:159], v[112:115]
	ds_read_b128 v[196:199], v209 offset:57344
	s_waitcnt lgkmcnt(6)
	v_mfma_f32_16x16x32_bf16 v[44:47], v[200:203], v[144:147], v[44:47]
	v_mfma_f32_16x16x32_bf16 v[108:111], v[200:203], v[160:163], v[108:111]
	ds_read_b128 v[200:203], v209 offset:61440
	s_waitcnt lgkmcnt(6)
	v_mfma_f32_16x16x32_bf16 v[48:51], v[204:207], v[144:147], v[48:51]
	v_mfma_f32_16x16x32_bf16 v[112:115], v[204:207], v[160:163], v[112:115]
	ds_read_b128 v[204:207], v210 offset:57344
	s_waitcnt lgkmcnt(6)
	v_mfma_f32_16x16x32_bf16 v[52:55], v[220:223], v[140:143], v[52:55]
	v_mfma_f32_16x16x32_bf16 v[116:119], v[220:223], v[156:159], v[116:119]
	ds_read_b128 v[220:223], v210 offset:61440
	s_waitcnt lgkmcnt(6)
	v_mfma_f32_16x16x32_bf16 v[56:59], v[230:233], v[140:143], v[56:59]
	v_mfma_f32_16x16x32_bf16 v[120:123], v[230:233], v[156:159], v[120:123]
	s_waitcnt lgkmcnt(5)
	v_mfma_f32_16x16x32_bf16 v[52:55], v[234:237], v[144:147], v[52:55]
	v_mfma_f32_16x16x32_bf16 v[116:119], v[234:237], v[160:163], v[116:119]
	s_waitcnt lgkmcnt(4)
	v_mfma_f32_16x16x32_bf16 v[56:59], v[238:241], v[144:147], v[56:59]
	v_mfma_f32_16x16x32_bf16 v[120:123], v[238:241], v[160:163], v[120:123]
	s_waitcnt lgkmcnt(3)
	v_mfma_f32_16x16x32_bf16 v[60:63], v[196:199], v[140:143], v[60:63]
	v_mfma_f32_16x16x32_bf16 v[124:127], v[196:199], v[156:159], v[124:127]
	s_waitcnt lgkmcnt(2)
	v_mfma_f32_16x16x32_bf16 v[64:67], v[200:203], v[140:143], v[64:67]
	v_mfma_f32_16x16x32_bf16 v[128:131], v[200:203], v[156:159], v[128:131]
	s_waitcnt lgkmcnt(1)
	v_mfma_f32_16x16x32_bf16 v[60:63], v[204:207], v[144:147], v[60:63]
	v_mfma_f32_16x16x32_bf16 v[124:127], v[204:207], v[160:163], v[124:127]
	s_waitcnt lgkmcnt(0)
	v_mfma_f32_16x16x32_bf16 v[64:67], v[220:223], v[144:147], v[64:67]
	v_mfma_f32_16x16x32_bf16 v[128:131], v[220:223], v[160:163], v[128:131]
	global_load_dwordx4 v[140:143], v246, s[92:93] offset:640
	global_load_dwordx4 v[144:147], v246, s[92:93] offset:704
	global_load_dwordx4 v[156:159], v247, s[92:93] offset:640
	global_load_dwordx4 v[160:163], v247, s[92:93] offset:704
	v_xor_b32_e32 v2, 0x10000, v2
	v_xor_b32_e32 v208, 0x10000, v208
	v_xor_b32_e32 v209, 0x10000, v209
	v_xor_b32_e32 v210, 0x10000, v210
	s_waitcnt vmcnt(15)
	ds_write_b128 v0, v[164:167]
	s_waitcnt vmcnt(14)
	ds_write_b128 v0, v[168:171] offset:8192
	s_waitcnt vmcnt(13)
	ds_write_b128 v0, v[172:175] offset:16384
	s_waitcnt vmcnt(12)
	ds_write_b128 v0, v[176:179] offset:24576
	s_waitcnt vmcnt(11)
	ds_write_b128 v0, v[180:183] offset:32768
	s_waitcnt vmcnt(10)
	ds_write_b128 v0, v[184:187] offset:40960
	s_waitcnt vmcnt(9)
	ds_write_b128 v0, v[188:191] offset:49152
	s_waitcnt vmcnt(8)
	ds_write_b128 v0, v[192:195] offset:57344
	global_load_dwordx4 v[164:167], v242, s[92:93] offset:768
	v_add_u32_e32 v243, 0x40000, v242
	global_load_dwordx4 v[168:171], v243, s[92:93] offset:768
	v_add_u32_e32 v243, 0x80000, v242
	global_load_dwordx4 v[172:175], v243, s[92:93] offset:768
	v_add_u32_e32 v243, 0xc0000, v242
	global_load_dwordx4 v[176:179], v243, s[92:93] offset:768
	v_add_u32_e32 v243, 0x100000, v242
	global_load_dwordx4 v[180:183], v243, s[92:93] offset:768
	v_add_u32_e32 v243, 0x140000, v242
	global_load_dwordx4 v[184:187], v243, s[92:93] offset:768
	v_add_u32_e32 v243, 0x180000, v242
	global_load_dwordx4 v[188:191], v243, s[92:93] offset:768
	v_add_u32_e32 v243, 0x1c0000, v242
	global_load_dwordx4 v[192:195], v243, s[92:93] offset:768
	s_waitcnt lgkmcnt(0)
	s_barrier
; __device__ __forceinline__ f32x4 mfma16(bf16x8 a, bf16x8 b, f32x4 c) { return __builtin_amdgcn_mfma_f32_16x16x32_bf16(a, b, c, 0, 0, 0); }
; __device__ void cross_items(const Params& p, LAS unsigned char* lds) {
;     ...
;             for (int kt = 0; kt < 16; ++kt)
; #pragma unroll
;                 for (int ks = 0; ks < 4; ++ks) sc[kt] = mfma16(frag_row(buf, KV_STRIDE, 16 * kt, 32 * ks, idx, g), qf[ks], sc[kt]);
	ds_read_b128 v[196:199], v2
	ds_read_b128 v[200:203], v2 offset:4096
	ds_read_b128 v[204:207], v208
	ds_read_b128 v[220:223], v208 offset:4096
	ds_read_b128 v[230:233], v2 offset:8192
	ds_read_b128 v[234:237], v2 offset:12288
	ds_read_b128 v[238:241], v208 offset:8192
	s_waitcnt vmcnt(12) lgkmcnt(6)
	v_mfma_f32_16x16x32_bf16 v[4:7], v[196:199], v[132:135], v[4:7]
	v_mfma_f32_16x16x32_bf16 v[68:71], v[196:199], v[148:151], v[68:71]
	ds_read_b128 v[196:199], v208 offset:12288
	s_waitcnt lgkmcnt(6)
	v_mfma_f32_16x16x32_bf16 v[8:11], v[200:203], v[132:135], v[8:11]
	v_mfma_f32_16x16x32_bf16 v[72:75], v[200:203], v[148:151], v[72:75]
	ds_read_b128 v[200:203], v2 offset:16384
	s_waitcnt lgkmcnt(6)
	v_mfma_f32_16x16x32_bf16 v[4:7], v[204:207], v[136:139], v[4:7]
	v_mfma_f32_16x16x32_bf16 v[68:71], v[204:207], v[152:155], v[68:71]
	ds_read_b128 v[204:207], v2 offset:20480
	s_waitcnt lgkmcnt(6)
	v_mfma_f32_16x16x32_bf16 v[8:11], v[220:223], v[136:139], v[8:11]
	v_mfma_f32_16x16x32_bf16 v[72:75], v[220:223], v[152:155], v[72:75]
	ds_read_b128 v[220:223], v208 offset:16384
	s_waitcnt lgkmcnt(6)
	v_mfma_f32_16x16x32_bf16 v[12:15], v[230:233], v[132:135], v[12:15]
	v_mfma_f32_16x16x32_bf16 v[76:79], v[230:233], v[148:151], v[76:79]
	ds_read_b128 v[230:233], v208 offset:20480
	s_waitcnt lgkmcnt(6)
	v_mfma_f32_16x16x32_bf16 v[16:19], v[234:237], v[132:135], v[16:19]
	v_mfma_f32_16x16x32_bf16 v[80:83], v[234:237], v[148:151], v[80:83]
	ds_read_b128 v[234:237], v2 offset:24576
	s_waitcnt lgkmcnt(6)
	v_mfma_f32_16x16x32_bf16 v[12:15], v[238:241], v[136:139], v[12:15]
	v_mfma_f32_16x16x32_bf16 v[76:79], v[238:241], v[152:155], v[76:79]
	ds_read_b128 v[238:241], v2 offset:28672
	s_waitcnt lgkmcnt(6)
	v_mfma_f32_16x16x32_bf16 v[16:19], v[196:199], v[136:139], v[16:19]
	v_mfma_f32_16x16x32_bf16 v[80:83], v[196:199], v[152:155], v[80:83]
	ds_read_b128 v[196:199], v208 offset:24576
	s_waitcnt lgkmcnt(6)
	v_mfma_f32_16x16x32_bf16 v[20:23], v[200:203], v[132:135], v[20:23]
	v_mfma_f32_16x16x32_bf16 v[84:87], v[200:203], v[148:151], v[84:87]
	ds_read_b128 v[200:203], v208 offset:28672
	s_waitcnt lgkmcnt(6)
	v_mfma_f32_16x16x32_bf16 v[24:27], v[204:207], v[132:135], v[24:27]
	v_mfma_f32_16x16x32_bf16 v[88:91], v[204:207], v[148:151], v[88:91]
	ds_read_b128 v[204:207], v2 offset:32768
	s_waitcnt lgkmcnt(6)
	v_mfma_f32_16x16x32_bf16 v[20:23], v[220:223], v[136:139], v[20:23]
	v_mfma_f32_16x16x32_bf16 v[84:87], v[220:223], v[152:155], v[84:87]
	ds_read_b128 v[220:223], v2 offset:36864
	s_waitcnt lgkmcnt(6)
	v_mfma_f32_16x16x32_bf16 v[24:27], v[230:233], v[136:139], v[24:27]
	v_mfma_f32_16x16x32_bf16 v[88:91], v[230:233], v[152:155], v[88:91]
	ds_read_b128 v[230:233], v208 offset:32768
	s_waitcnt lgkmcnt(6)
	v_mfma_f32_16x16x32_bf16 v[28:31], v[234:237], v[132:135], v[28:31]
	v_mfma_f32_16x16x32_bf16 v[92:95], v[234:237], v[148:151], v[92:95]
	ds_read_b128 v[234:237], v208 offset:36864
	s_waitcnt lgkmcnt(6)
	v_mfma_f32_16x16x32_bf16 v[32:35], v[238:241], v[132:135], v[32:35]
	v_mfma_f32_16x16x32_bf16 v[96:99], v[238:241], v[148:151], v[96:99]
	ds_read_b128 v[238:241], v2 offset:40960
	s_waitcnt lgkmcnt(6)
	v_mfma_f32_16x16x32_bf16 v[28:31], v[196:199], v[136:139], v[28:31]
	v_mfma_f32_16x16x32_bf16 v[92:95], v[196:199], v[152:155], v[92:95]
	ds_read_b128 v[196:199], v2 offset:45056
	s_waitcnt lgkmcnt(6)
	v_mfma_f32_16x16x32_bf16 v[32:35], v[200:203], v[136:139], v[32:35]
	v_mfma_f32_16x16x32_bf16 v[96:99], v[200:203], v[152:155], v[96:99]
	ds_read_b128 v[200:203], v208 offset:40960
	s_waitcnt lgkmcnt(6)
	v_mfma_f32_16x16x32_bf16 v[36:39], v[204:207], v[132:135], v[36:39]
	v_mfma_f32_16x16x32_bf16 v[100:103], v[204:207], v[148:151], v[100:103]
	ds_read_b128 v[204:207], v208 offset:45056
	s_waitcnt lgkmcnt(6)
	v_mfma_f32_16x16x32_bf16 v[40:43], v[220:223], v[132:135], v[40:43]
	v_mfma_f32_16x16x32_bf16 v[104:107], v[220:223], v[148:151], v[104:107]
	ds_read_b128 v[220:223], v2 offset:49152
	s_waitcnt lgkmcnt(6)
	v_mfma_f32_16x16x32_bf16 v[36:39], v[230:233], v[136:139], v[36:39]
	v_mfma_f32_16x16x32_bf16 v[100:103], v[230:233], v[152:155], v[100:103]
	ds_read_b128 v[230:233], v2 offset:53248
	s_waitcnt lgkmcnt(6)
	v_mfma_f32_16x16x32_bf16 v[40:43], v[234:237], v[136:139], v[40:43]
	v_mfma_f32_16x16x32_bf16 v[104:107], v[234:237], v[152:155], v[104:107]
	ds_read_b128 v[234:237], v208 offset:49152
	s_waitcnt lgkmcnt(6)
	v_mfma_f32_16x16x32_bf16 v[44:47], v[238:241], v[132:135], v[44:47]
	v_mfma_f32_16x16x32_bf16 v[108:111], v[238:241], v[148:151], v[108:111]
	ds_read_b128 v[238:241], v208 offset:53248
	s_waitcnt lgkmcnt(6)
	v_mfma_f32_16x16x32_bf16 v[48:51], v[196:199], v[132:135], v[48:51]
	v_mfma_f32_16x16x32_bf16 v[112:115], v[196:199], v[148:151], v[112:115]
	ds_read_b128 v[196:199], v2 offset:57344
	s_waitcnt lgkmcnt(6)
	v_mfma_f32_16x16x32_bf16 v[44:47], v[200:203], v[136:139], v[44:47]
	v_mfma_f32_16x16x32_bf16 v[108:111], v[200:203], v[152:155], v[108:111]
	ds_read_b128 v[200:203], v2 offset:61440
	s_waitcnt lgkmcnt(6)
	v_mfma_f32_16x16x32_bf16 v[48:51], v[204:207], v[136:139], v[48:51]
	v_mfma_f32_16x16x32_bf16 v[112:115], v[204:207], v[152:155], v[112:115]
	ds_read_b128 v[204:207], v208 offset:57344
	s_waitcnt lgkmcnt(6)
	v_mfma_f32_16x16x32_bf16 v[52:55], v[220:223], v[132:135], v[52:55]
	v_mfma_f32_16x16x32_bf16 v[116:119], v[220:223], v[148:151], v[116:119]
	ds_read_b128 v[220:223], v208 offset:61440
	s_waitcnt lgkmcnt(6)
	v_mfma_f32_16x16x32_bf16 v[56:59], v[230:233], v[132:135], v[56:59]
	v_mfma_f32_16x16x32_bf16 v[120:123], v[230:233], v[148:151], v[120:123]
	s_waitcnt lgkmcnt(5)
; __device__ __forceinline__ f32x4 mfma16(bf16x8 a, bf16x8 b, f32x4 c) { return __builtin_amdgcn_mfma_f32_16x16x32_bf16(a, b, c, 0, 0, 0); }
; __device__ void cross_items(const Params& p, LAS unsigned char* lds) {
;     ...
;             for (int ks = 0; ks < 4; ++ks) qf[ks] = *(const bf16x8*)(qrow + c * 128 + 32 * ks);
;     ...
;             for (int kt = 0; kt < 16; ++kt)
; #pragma unroll
;                 for (int ks = 0; ks < 4; ++ks) sc[kt] = mfma16(frag_row(buf, KV_STRIDE, 16 * kt, 32 * ks, idx, g), qf[ks], sc[kt]);
	v_mfma_f32_16x16x32_bf16 v[52:55], v[234:237], v[136:139], v[52:55]
	v_mfma_f32_16x16x32_bf16 v[116:119], v[234:237], v[152:155], v[116:119]
	s_waitcnt lgkmcnt(4)
	v_mfma_f32_16x16x32_bf16 v[56:59], v[238:241], v[136:139], v[56:59]
	v_mfma_f32_16x16x32_bf16 v[120:123], v[238:241], v[152:155], v[120:123]
	s_waitcnt lgkmcnt(3)
	v_mfma_f32_16x16x32_bf16 v[60:63], v[196:199], v[132:135], v[60:63]
	v_mfma_f32_16x16x32_bf16 v[124:127], v[196:199], v[148:151], v[124:127]
	s_waitcnt lgkmcnt(2)
	v_mfma_f32_16x16x32_bf16 v[64:67], v[200:203], v[132:135], v[64:67]
	v_mfma_f32_16x16x32_bf16 v[128:131], v[200:203], v[148:151], v[128:131]
	s_waitcnt lgkmcnt(1)
	v_mfma_f32_16x16x32_bf16 v[60:63], v[204:207], v[136:139], v[60:63]
	v_mfma_f32_16x16x32_bf16 v[124:127], v[204:207], v[152:155], v[124:127]
	s_waitcnt lgkmcnt(0)
	v_mfma_f32_16x16x32_bf16 v[64:67], v[220:223], v[136:139], v[64:67]
	v_mfma_f32_16x16x32_bf16 v[128:131], v[220:223], v[152:155], v[128:131]
	global_load_dwordx4 v[132:135], v246, s[92:93] offset:768
	global_load_dwordx4 v[136:139], v246, s[92:93] offset:832
	global_load_dwordx4 v[148:151], v247, s[92:93] offset:768
	global_load_dwordx4 v[152:155], v247, s[92:93] offset:832
	ds_read_b128 v[196:199], v209
	ds_read_b128 v[200:203], v209 offset:4096
	ds_read_b128 v[204:207], v210
	ds_read_b128 v[220:223], v210 offset:4096
	ds_read_b128 v[230:233], v209 offset:8192
	ds_read_b128 v[234:237], v209 offset:12288
	ds_read_b128 v[238:241], v210 offset:8192
	s_waitcnt vmcnt(12) lgkmcnt(6)
	v_mfma_f32_16x16x32_bf16 v[4:7], v[196:199], v[140:143], v[4:7]
	v_mfma_f32_16x16x32_bf16 v[68:71], v[196:199], v[156:159], v[68:71]
	ds_read_b128 v[196:199], v210 offset:12288
	s_waitcnt lgkmcnt(6)
	v_mfma_f32_16x16x32_bf16 v[8:11], v[200:203], v[140:143], v[8:11]
	v_mfma_f32_16x16x32_bf16 v[72:75], v[200:203], v[156:159], v[72:75]
	ds_read_b128 v[200:203], v209 offset:16384
	s_waitcnt lgkmcnt(6)
	v_mfma_f32_16x16x32_bf16 v[4:7], v[204:207], v[144:147], v[4:7]
	v_mfma_f32_16x16x32_bf16 v[68:71], v[204:207], v[160:163], v[68:71]
	ds_read_b128 v[204:207], v209 offset:20480
	s_waitcnt lgkmcnt(6)
	v_mfma_f32_16x16x32_bf16 v[8:11], v[220:223], v[144:147], v[8:11]
	v_mfma_f32_16x16x32_bf16 v[72:75], v[220:223], v[160:163], v[72:75]
	ds_read_b128 v[220:223], v210 offset:16384
	s_waitcnt lgkmcnt(6)
	v_mfma_f32_16x16x32_bf16 v[12:15], v[230:233], v[140:143], v[12:15]
	v_mfma_f32_16x16x32_bf16 v[76:79], v[230:233], v[156:159], v[76:79]
	ds_read_b128 v[230:233], v210 offset:20480
	s_waitcnt lgkmcnt(6)
	v_mfma_f32_16x16x32_bf16 v[16:19], v[234:237], v[140:143], v[16:19]
	v_mfma_f32_16x16x32_bf16 v[80:83], v[234:237], v[156:159], v[80:83]
	ds_read_b128 v[234:237], v209 offset:24576
	s_waitcnt lgkmcnt(6)
	v_mfma_f32_16x16x32_bf16 v[12:15], v[238:241], v[144:147], v[12:15]
	v_mfma_f32_16x16x32_bf16 v[76:79], v[238:241], v[160:163], v[76:79]
	ds_read_b128 v[238:241], v209 offset:28672
	s_waitcnt lgkmcnt(6)
	v_mfma_f32_16x16x32_bf16 v[16:19], v[196:199], v[144:147], v[16:19]
	v_mfma_f32_16x16x32_bf16 v[80:83], v[196:199], v[160:163], v[80:83]
	ds_read_b128 v[196:199], v210 offset:24576
	s_waitcnt lgkmcnt(6)
	v_mfma_f32_16x16x32_bf16 v[20:23], v[200:203], v[140:143], v[20:23]
	v_mfma_f32_16x16x32_bf16 v[84:87], v[200:203], v[156:159], v[84:87]
	ds_read_b128 v[200:203], v210 offset:28672
	s_waitcnt lgkmcnt(6)
	v_mfma_f32_16x16x32_bf16 v[24:27], v[204:207], v[140:143], v[24:27]
	v_mfma_f32_16x16x32_bf16 v[88:91], v[204:207], v[156:159], v[88:91]
	ds_read_b128 v[204:207], v209 offset:32768
	s_waitcnt lgkmcnt(6)
	v_mfma_f32_16x16x32_bf16 v[20:23], v[220:223], v[144:147], v[20:23]
	v_mfma_f32_16x16x32_bf16 v[84:87], v[220:223], v[160:163], v[84:87]
	ds_read_b128 v[220:223], v209 offset:36864
	s_waitcnt lgkmcnt(6)
	v_mfma_f32_16x16x32_bf16 v[24:27], v[230:233], v[144:147], v[24:27]
	v_mfma_f32_16x16x32_bf16 v[88:91], v[230:233], v[160:163], v[88:91]
	ds_read_b128 v[230:233], v210 offset:32768
	s_waitcnt lgkmcnt(6)
	v_mfma_f32_16x16x32_bf16 v[28:31], v[234:237], v[140:143], v[28:31]
	v_mfma_f32_16x16x32_bf16 v[92:95], v[234:237], v[156:159], v[92:95]
	ds_read_b128 v[234:237], v210 offset:36864
	s_waitcnt lgkmcnt(6)
	v_mfma_f32_16x16x32_bf16 v[32:35], v[238:241], v[140:143], v[32:35]
	v_mfma_f32_16x16x32_bf16 v[96:99], v[238:241], v[156:159], v[96:99]
	ds_read_b128 v[238:241], v209 offset:40960
	s_waitcnt lgkmcnt(6)
	v_mfma_f32_16x16x32_bf16 v[28:31], v[196:199], v[144:147], v[28:31]
	v_mfma_f32_16x16x32_bf16 v[92:95], v[196:199], v[160:163], v[92:95]
	ds_read_b128 v[196:199], v209 offset:45056
	s_waitcnt lgkmcnt(6)
	v_mfma_f32_16x16x32_bf16 v[32:35], v[200:203], v[144:147], v[32:35]
	v_mfma_f32_16x16x32_bf16 v[96:99], v[200:203], v[160:163], v[96:99]
	ds_read_b128 v[200:203], v210 offset:40960
	s_waitcnt lgkmcnt(6)
	v_mfma_f32_16x16x32_bf16 v[36:39], v[204:207], v[140:143], v[36:39]
	v_mfma_f32_16x16x32_bf16 v[100:103], v[204:207], v[156:159], v[100:103]
	ds_read_b128 v[204:207], v210 offset:45056
	s_waitcnt lgkmcnt(6)
	v_mfma_f32_16x16x32_bf16 v[40:43], v[220:223], v[140:143], v[40:43]
	v_mfma_f32_16x16x32_bf16 v[104:107], v[220:223], v[156:159], v[104:107]
	ds_read_b128 v[220:223], v209 offset:49152
	s_waitcnt lgkmcnt(6)
	v_mfma_f32_16x16x32_bf16 v[36:39], v[230:233], v[144:147], v[36:39]
	v_mfma_f32_16x16x32_bf16 v[100:103], v[230:233], v[160:163], v[100:103]
	ds_read_b128 v[230:233], v209 offset:53248
	s_waitcnt lgkmcnt(6)
	v_mfma_f32_16x16x32_bf16 v[40:43], v[234:237], v[144:147], v[40:43]
	v_mfma_f32_16x16x32_bf16 v[104:107], v[234:237], v[160:163], v[104:107]
	ds_read_b128 v[234:237], v210 offset:49152
	s_waitcnt lgkmcnt(6)
; __device__ __forceinline__ f32x4 mfma16(bf16x8 a, bf16x8 b, f32x4 c) { return __builtin_amdgcn_mfma_f32_16x16x32_bf16(a, b, c, 0, 0, 0); }
; #define XLOAD(kvbase, c8) do { const bf16_t* _src = (kvbase) + (((c8) >= 4) ? 2048 : 0) + ((c8) & 3) * 128 + piece * 8; \
;         _Pragma("unroll") for (int _it = 0; _it < 8; ++_it) pre[_it] = *(const u32x4*)(_src + (size_t)(srow + 32 * _it) * 4096); } while (0)
; #define XSTORE(buf) do { _Pragma("unroll") for (int _it = 0; _it < 8; ++_it) *(LAS u32x4*)((buf) + (srow + 32 * _it) * KV_STRIDE + piece * 16) = pre[_it]; } while (0)
; __device__ void cross_items(const Params& p, LAS unsigned char* lds) {
;     ...
;             XSTORE(buf);
;             bf16x8 qf[4];
; #pragma unroll
;             for (int ks = 0; ks < 4; ++ks) qf[ks] = *(const bf16x8*)(qrow + c * 128 + 32 * ks);
;             XLOAD(kvb, c + 1);
;     ...
;             for (int kt = 0; kt < 16; ++kt)
; #pragma unroll
;                 for (int ks = 0; ks < 4; ++ks) sc[kt] = mfma16(frag_row(buf, KV_STRIDE, 16 * kt, 32 * ks, idx, g), qf[ks], sc[kt]);
	v_mfma_f32_16x16x32_bf16 v[44:47], v[238:241], v[140:143], v[44:47]
	v_mfma_f32_16x16x32_bf16 v[108:111], v[238:241], v[156:159], v[108:111]
	ds_read_b128 v[238:241], v210 offset:53248
	s_waitcnt lgkmcnt(6)
	v_mfma_f32_16x16x32_bf16 v[48:51], v[196:199], v[140:143], v[48:51]
	v_mfma_f32_16x16x32_bf16 v[112:115], v[196:199], v[156:159], v[112:115]
	ds_read_b128 v[196:199], v209 offset:57344
	s_waitcnt lgkmcnt(6)
	v_mfma_f32_16x16x32_bf16 v[44:47], v[200:203], v[144:147], v[44:47]
	v_mfma_f32_16x16x32_bf16 v[108:111], v[200:203], v[160:163], v[108:111]
	ds_read_b128 v[200:203], v209 offset:61440
	s_waitcnt lgkmcnt(6)
	v_mfma_f32_16x16x32_bf16 v[48:51], v[204:207], v[144:147], v[48:51]
	v_mfma_f32_16x16x32_bf16 v[112:115], v[204:207], v[160:163], v[112:115]
	ds_read_b128 v[204:207], v210 offset:57344
	s_waitcnt lgkmcnt(6)
	v_mfma_f32_16x16x32_bf16 v[52:55], v[220:223], v[140:143], v[52:55]
	v_mfma_f32_16x16x32_bf16 v[116:119], v[220:223], v[156:159], v[116:119]
	ds_read_b128 v[220:223], v210 offset:61440
	s_waitcnt lgkmcnt(6)
	v_mfma_f32_16x16x32_bf16 v[56:59], v[230:233], v[140:143], v[56:59]
	v_mfma_f32_16x16x32_bf16 v[120:123], v[230:233], v[156:159], v[120:123]
	s_waitcnt lgkmcnt(5)
	v_mfma_f32_16x16x32_bf16 v[52:55], v[234:237], v[144:147], v[52:55]
	v_mfma_f32_16x16x32_bf16 v[116:119], v[234:237], v[160:163], v[116:119]
	s_waitcnt lgkmcnt(4)
	v_mfma_f32_16x16x32_bf16 v[56:59], v[238:241], v[144:147], v[56:59]
	v_mfma_f32_16x16x32_bf16 v[120:123], v[238:241], v[160:163], v[120:123]
	s_waitcnt lgkmcnt(3)
	v_mfma_f32_16x16x32_bf16 v[60:63], v[196:199], v[140:143], v[60:63]
	v_mfma_f32_16x16x32_bf16 v[124:127], v[196:199], v[156:159], v[124:127]
	s_waitcnt lgkmcnt(2)
	v_mfma_f32_16x16x32_bf16 v[64:67], v[200:203], v[140:143], v[64:67]
	v_mfma_f32_16x16x32_bf16 v[128:131], v[200:203], v[156:159], v[128:131]
	s_waitcnt lgkmcnt(1)
	v_mfma_f32_16x16x32_bf16 v[60:63], v[204:207], v[144:147], v[60:63]
	v_mfma_f32_16x16x32_bf16 v[124:127], v[204:207], v[160:163], v[124:127]
	s_waitcnt lgkmcnt(0)
	v_mfma_f32_16x16x32_bf16 v[64:67], v[220:223], v[144:147], v[64:67]
	v_mfma_f32_16x16x32_bf16 v[128:131], v[220:223], v[160:163], v[128:131]
	global_load_dwordx4 v[140:143], v246, s[92:93] offset:896
	global_load_dwordx4 v[144:147], v246, s[92:93] offset:960
	global_load_dwordx4 v[156:159], v247, s[92:93] offset:896
	global_load_dwordx4 v[160:163], v247, s[92:93] offset:960
	v_xor_b32_e32 v2, 0x10000, v2
	v_xor_b32_e32 v208, 0x10000, v208
	v_xor_b32_e32 v209, 0x10000, v209
	v_xor_b32_e32 v210, 0x10000, v210
	s_waitcnt vmcnt(15)
	ds_write_b128 v1, v[164:167]
	s_waitcnt vmcnt(14)
	ds_write_b128 v1, v[168:171] offset:8192
	s_waitcnt vmcnt(13)
	ds_write_b128 v1, v[172:175] offset:16384
	s_waitcnt vmcnt(12)
	ds_write_b128 v1, v[176:179] offset:24576
	s_waitcnt vmcnt(11)
	ds_write_b128 v1, v[180:183] offset:32768
	s_waitcnt vmcnt(10)
	ds_write_b128 v1, v[184:187] offset:40960
	s_waitcnt vmcnt(9)
	ds_write_b128 v1, v[188:191] offset:49152
	s_waitcnt vmcnt(8)
	ds_write_b128 v1, v[192:195] offset:57344
	global_load_dwordx4 v[164:167], v242, s[6:7]
	v_add_u32_e32 v243, 0x40000, v242
	global_load_dwordx4 v[168:171], v243, s[6:7]
	v_add_u32_e32 v243, 0x80000, v242
	global_load_dwordx4 v[172:175], v243, s[6:7]
	v_add_u32_e32 v243, 0xc0000, v242
	global_load_dwordx4 v[176:179], v243, s[6:7]
	v_add_u32_e32 v243, 0x100000, v242
	global_load_dwordx4 v[180:183], v243, s[6:7]
	v_add_u32_e32 v243, 0x140000, v242
	global_load_dwordx4 v[184:187], v243, s[6:7]
	v_add_u32_e32 v243, 0x180000, v242
	global_load_dwordx4 v[188:191], v243, s[6:7]
	v_add_u32_e32 v243, 0x1c0000, v242
	global_load_dwordx4 v[192:195], v243, s[6:7]
	s_waitcnt lgkmcnt(0)
	s_barrier
	ds_read_b128 v[196:199], v2
	ds_read_b128 v[200:203], v2 offset:4096
	ds_read_b128 v[204:207], v208
	ds_read_b128 v[220:223], v208 offset:4096
	ds_read_b128 v[230:233], v2 offset:8192
	ds_read_b128 v[234:237], v2 offset:12288
	ds_read_b128 v[238:241], v208 offset:8192
	s_waitcnt vmcnt(12) lgkmcnt(6)
	v_mfma_f32_16x16x32_bf16 v[4:7], v[196:199], v[132:135], v[4:7]
	v_mfma_f32_16x16x32_bf16 v[68:71], v[196:199], v[148:151], v[68:71]
	ds_read_b128 v[196:199], v208 offset:12288
	s_waitcnt lgkmcnt(6)
	v_mfma_f32_16x16x32_bf16 v[8:11], v[200:203], v[132:135], v[8:11]
	v_mfma_f32_16x16x32_bf16 v[72:75], v[200:203], v[148:151], v[72:75]
	ds_read_b128 v[200:203], v2 offset:16384
	s_waitcnt lgkmcnt(6)
	v_mfma_f32_16x16x32_bf16 v[4:7], v[204:207], v[136:139], v[4:7]
	v_mfma_f32_16x16x32_bf16 v[68:71], v[204:207], v[152:155], v[68:71]
	ds_read_b128 v[204:207], v2 offset:20480
	s_waitcnt lgkmcnt(6)
	v_mfma_f32_16x16x32_bf16 v[8:11], v[220:223], v[136:139], v[8:11]
	v_mfma_f32_16x16x32_bf16 v[72:75], v[220:223], v[152:155], v[72:75]
	ds_read_b128 v[220:223], v208 offset:16384
	s_waitcnt lgkmcnt(6)
	v_mfma_f32_16x16x32_bf16 v[12:15], v[230:233], v[132:135], v[12:15]
	v_mfma_f32_16x16x32_bf16 v[76:79], v[230:233], v[148:151], v[76:79]
	ds_read_b128 v[230:233], v208 offset:20480
	s_waitcnt lgkmcnt(6)
	v_mfma_f32_16x16x32_bf16 v[16:19], v[234:237], v[132:135], v[16:19]
	v_mfma_f32_16x16x32_bf16 v[80:83], v[234:237], v[148:151], v[80:83]
	ds_read_b128 v[234:237], v2 offset:24576
	s_waitcnt lgkmcnt(6)
	v_mfma_f32_16x16x32_bf16 v[12:15], v[238:241], v[136:139], v[12:15]
	v_mfma_f32_16x16x32_bf16 v[76:79], v[238:241], v[152:155], v[76:79]
	ds_read_b128 v[238:241], v2 offset:28672
	s_waitcnt lgkmcnt(6)
	v_mfma_f32_16x16x32_bf16 v[16:19], v[196:199], v[136:139], v[16:19]
	v_mfma_f32_16x16x32_bf16 v[80:83], v[196:199], v[152:155], v[80:83]
	ds_read_b128 v[196:199], v208 offset:24576
	s_waitcnt lgkmcnt(6)
; __device__ __forceinline__ f32x4 mfma16(bf16x8 a, bf16x8 b, f32x4 c) { return __builtin_amdgcn_mfma_f32_16x16x32_bf16(a, b, c, 0, 0, 0); }
; __device__ void cross_items(const Params& p, LAS unsigned char* lds) {
;     ...
;             for (int kt = 0; kt < 16; ++kt)
; #pragma unroll
;                 for (int ks = 0; ks < 4; ++ks) sc[kt] = mfma16(frag_row(buf, KV_STRIDE, 16 * kt, 32 * ks, idx, g), qf[ks], sc[kt]);
	v_mfma_f32_16x16x32_bf16 v[20:23], v[200:203], v[132:135], v[20:23]
	v_mfma_f32_16x16x32_bf16 v[84:87], v[200:203], v[148:151], v[84:87]
	ds_read_b128 v[200:203], v208 offset:28672
	s_waitcnt lgkmcnt(6)
	v_mfma_f32_16x16x32_bf16 v[24:27], v[204:207], v[132:135], v[24:27]
	v_mfma_f32_16x16x32_bf16 v[88:91], v[204:207], v[148:151], v[88:91]
	ds_read_b128 v[204:207], v2 offset:32768
	s_waitcnt lgkmcnt(6)
	v_mfma_f32_16x16x32_bf16 v[20:23], v[220:223], v[136:139], v[20:23]
	v_mfma_f32_16x16x32_bf16 v[84:87], v[220:223], v[152:155], v[84:87]
	ds_read_b128 v[220:223], v2 offset:36864
	s_waitcnt lgkmcnt(6)
	v_mfma_f32_16x16x32_bf16 v[24:27], v[230:233], v[136:139], v[24:27]
	v_mfma_f32_16x16x32_bf16 v[88:91], v[230:233], v[152:155], v[88:91]
	ds_read_b128 v[230:233], v208 offset:32768
	s_waitcnt lgkmcnt(6)
	v_mfma_f32_16x16x32_bf16 v[28:31], v[234:237], v[132:135], v[28:31]
	v_mfma_f32_16x16x32_bf16 v[92:95], v[234:237], v[148:151], v[92:95]
	ds_read_b128 v[234:237], v208 offset:36864
	s_waitcnt lgkmcnt(6)
	v_mfma_f32_16x16x32_bf16 v[32:35], v[238:241], v[132:135], v[32:35]
	v_mfma_f32_16x16x32_bf16 v[96:99], v[238:241], v[148:151], v[96:99]
	ds_read_b128 v[238:241], v2 offset:40960
	s_waitcnt lgkmcnt(6)
	v_mfma_f32_16x16x32_bf16 v[28:31], v[196:199], v[136:139], v[28:31]
	v_mfma_f32_16x16x32_bf16 v[92:95], v[196:199], v[152:155], v[92:95]
	ds_read_b128 v[196:199], v2 offset:45056
	s_waitcnt lgkmcnt(6)
	v_mfma_f32_16x16x32_bf16 v[32:35], v[200:203], v[136:139], v[32:35]
	v_mfma_f32_16x16x32_bf16 v[96:99], v[200:203], v[152:155], v[96:99]
	ds_read_b128 v[200:203], v208 offset:40960
	s_waitcnt lgkmcnt(6)
	v_mfma_f32_16x16x32_bf16 v[36:39], v[204:207], v[132:135], v[36:39]
	v_mfma_f32_16x16x32_bf16 v[100:103], v[204:207], v[148:151], v[100:103]
	ds_read_b128 v[204:207], v208 offset:45056
	s_waitcnt lgkmcnt(6)
	v_mfma_f32_16x16x32_bf16 v[40:43], v[220:223], v[132:135], v[40:43]
	v_mfma_f32_16x16x32_bf16 v[104:107], v[220:223], v[148:151], v[104:107]
	ds_read_b128 v[220:223], v2 offset:49152
	s_waitcnt lgkmcnt(6)
	v_mfma_f32_16x16x32_bf16 v[36:39], v[230:233], v[136:139], v[36:39]
	v_mfma_f32_16x16x32_bf16 v[100:103], v[230:233], v[152:155], v[100:103]
	ds_read_b128 v[230:233], v2 offset:53248
	s_waitcnt lgkmcnt(6)
	v_mfma_f32_16x16x32_bf16 v[40:43], v[234:237], v[136:139], v[40:43]
	v_mfma_f32_16x16x32_bf16 v[104:107], v[234:237], v[152:155], v[104:107]
	ds_read_b128 v[234:237], v208 offset:49152
	s_waitcnt lgkmcnt(6)
	v_mfma_f32_16x16x32_bf16 v[44:47], v[238:241], v[132:135], v[44:47]
	v_mfma_f32_16x16x32_bf16 v[108:111], v[238:241], v[148:151], v[108:111]
	ds_read_b128 v[238:241], v208 offset:53248
	s_waitcnt lgkmcnt(6)
	v_mfma_f32_16x16x32_bf16 v[48:51], v[196:199], v[132:135], v[48:51]
	v_mfma_f32_16x16x32_bf16 v[112:115], v[196:199], v[148:151], v[112:115]
	ds_read_b128 v[196:199], v2 offset:57344
	s_waitcnt lgkmcnt(6)
	v_mfma_f32_16x16x32_bf16 v[44:47], v[200:203], v[136:139], v[44:47]
	v_mfma_f32_16x16x32_bf16 v[108:111], v[200:203], v[152:155], v[108:111]
	ds_read_b128 v[200:203], v2 offset:61440
	s_waitcnt lgkmcnt(6)
	v_mfma_f32_16x16x32_bf16 v[48:51], v[204:207], v[136:139], v[48:51]
	v_mfma_f32_16x16x32_bf16 v[112:115], v[204:207], v[152:155], v[112:115]
	ds_read_b128 v[204:207], v208 offset:57344
	s_waitcnt lgkmcnt(6)
	v_mfma_f32_16x16x32_bf16 v[52:55], v[220:223], v[132:135], v[52:55]
	v_mfma_f32_16x16x32_bf16 v[116:119], v[220:223], v[148:151], v[116:119]
	ds_read_b128 v[220:223], v208 offset:61440
	s_waitcnt lgkmcnt(6)
	v_mfma_f32_16x16x32_bf16 v[56:59], v[230:233], v[132:135], v[56:59]
	v_mfma_f32_16x16x32_bf16 v[120:123], v[230:233], v[148:151], v[120:123]
	s_waitcnt lgkmcnt(5)
	v_mfma_f32_16x16x32_bf16 v[52:55], v[234:237], v[136:139], v[52:55]
	v_mfma_f32_16x16x32_bf16 v[116:119], v[234:237], v[152:155], v[116:119]
	s_waitcnt lgkmcnt(4)
	v_mfma_f32_16x16x32_bf16 v[56:59], v[238:241], v[136:139], v[56:59]
	v_mfma_f32_16x16x32_bf16 v[120:123], v[238:241], v[152:155], v[120:123]
	s_waitcnt lgkmcnt(3)
	v_mfma_f32_16x16x32_bf16 v[60:63], v[196:199], v[132:135], v[60:63]
	v_mfma_f32_16x16x32_bf16 v[124:127], v[196:199], v[148:151], v[124:127]
	s_waitcnt lgkmcnt(2)
	v_mfma_f32_16x16x32_bf16 v[64:67], v[200:203], v[132:135], v[64:67]
	v_mfma_f32_16x16x32_bf16 v[128:131], v[200:203], v[148:151], v[128:131]
	s_waitcnt lgkmcnt(1)
	v_mfma_f32_16x16x32_bf16 v[60:63], v[204:207], v[136:139], v[60:63]
	v_mfma_f32_16x16x32_bf16 v[124:127], v[204:207], v[152:155], v[124:127]
	s_waitcnt lgkmcnt(0)
	v_mfma_f32_16x16x32_bf16 v[64:67], v[220:223], v[136:139], v[64:67]
	v_mfma_f32_16x16x32_bf16 v[128:131], v[220:223], v[152:155], v[128:131]
	ds_read_b128 v[196:199], v209
	ds_read_b128 v[200:203], v209 offset:4096
	ds_read_b128 v[204:207], v210
	ds_read_b128 v[220:223], v210 offset:4096
	ds_read_b128 v[230:233], v209 offset:8192
	ds_read_b128 v[234:237], v209 offset:12288
	ds_read_b128 v[238:241], v210 offset:8192
	s_waitcnt vmcnt(8) lgkmcnt(6)
	v_mfma_f32_16x16x32_bf16 v[4:7], v[196:199], v[140:143], v[4:7]
	v_mfma_f32_16x16x32_bf16 v[68:71], v[196:199], v[156:159], v[68:71]
	ds_read_b128 v[196:199], v210 offset:12288
	s_waitcnt lgkmcnt(6)
	v_mfma_f32_16x16x32_bf16 v[8:11], v[200:203], v[140:143], v[8:11]
	v_mfma_f32_16x16x32_bf16 v[72:75], v[200:203], v[156:159], v[72:75]
	ds_read_b128 v[200:203], v209 offset:16384
	s_waitcnt lgkmcnt(6)
	v_mfma_f32_16x16x32_bf16 v[4:7], v[204:207], v[144:147], v[4:7]
	v_mfma_f32_16x16x32_bf16 v[68:71], v[204:207], v[160:163], v[68:71]
	ds_read_b128 v[204:207], v209 offset:20480
	s_waitcnt lgkmcnt(6)
	v_mfma_f32_16x16x32_bf16 v[8:11], v[220:223], v[144:147], v[8:11]
	v_mfma_f32_16x16x32_bf16 v[72:75], v[220:223], v[160:163], v[72:75]
	ds_read_b128 v[220:223], v210 offset:16384
	s_waitcnt lgkmcnt(6)
; __device__ __forceinline__ f32x4 mfma16(bf16x8 a, bf16x8 b, f32x4 c) { return __builtin_amdgcn_mfma_f32_16x16x32_bf16(a, b, c, 0, 0, 0); }
; __device__ void cross_items(const Params& p, LAS unsigned char* lds) {
;     ...
;             for (int kt = 0; kt < 16; ++kt)
; #pragma unroll
;                 for (int ks = 0; ks < 4; ++ks) sc[kt] = mfma16(frag_row(buf, KV_STRIDE, 16 * kt, 32 * ks, idx, g), qf[ks], sc[kt]);
	v_mfma_f32_16x16x32_bf16 v[12:15], v[230:233], v[140:143], v[12:15]
	v_mfma_f32_16x16x32_bf16 v[76:79], v[230:233], v[156:159], v[76:79]
	ds_read_b128 v[230:233], v210 offset:20480
	s_waitcnt lgkmcnt(6)
	v_mfma_f32_16x16x32_bf16 v[16:19], v[234:237], v[140:143], v[16:19]
	v_mfma_f32_16x16x32_bf16 v[80:83], v[234:237], v[156:159], v[80:83]
	ds_read_b128 v[234:237], v209 offset:24576
	s_waitcnt lgkmcnt(6)
	v_mfma_f32_16x16x32_bf16 v[12:15], v[238:241], v[144:147], v[12:15]
	v_mfma_f32_16x16x32_bf16 v[76:79], v[238:241], v[160:163], v[76:79]
	ds_read_b128 v[238:241], v209 offset:28672
	s_waitcnt lgkmcnt(6)
	v_mfma_f32_16x16x32_bf16 v[16:19], v[196:199], v[144:147], v[16:19]
	v_mfma_f32_16x16x32_bf16 v[80:83], v[196:199], v[160:163], v[80:83]
	ds_read_b128 v[196:199], v210 offset:24576
	s_waitcnt lgkmcnt(6)
	v_mfma_f32_16x16x32_bf16 v[20:23], v[200:203], v[140:143], v[20:23]
	v_mfma_f32_16x16x32_bf16 v[84:87], v[200:203], v[156:159], v[84:87]
	ds_read_b128 v[200:203], v210 offset:28672
	s_waitcnt lgkmcnt(6)
	v_mfma_f32_16x16x32_bf16 v[24:27], v[204:207], v[140:143], v[24:27]
	v_mfma_f32_16x16x32_bf16 v[88:91], v[204:207], v[156:159], v[88:91]
	ds_read_b128 v[204:207], v209 offset:32768
	s_waitcnt lgkmcnt(6)
	v_mfma_f32_16x16x32_bf16 v[20:23], v[220:223], v[144:147], v[20:23]
	v_mfma_f32_16x16x32_bf16 v[84:87], v[220:223], v[160:163], v[84:87]
	ds_read_b128 v[220:223], v209 offset:36864
	s_waitcnt lgkmcnt(6)
	v_mfma_f32_16x16x32_bf16 v[24:27], v[230:233], v[144:147], v[24:27]
	v_mfma_f32_16x16x32_bf16 v[88:91], v[230:233], v[160:163], v[88:91]
	ds_read_b128 v[230:233], v210 offset:32768
	s_waitcnt lgkmcnt(6)
	v_mfma_f32_16x16x32_bf16 v[28:31], v[234:237], v[140:143], v[28:31]
	v_mfma_f32_16x16x32_bf16 v[92:95], v[234:237], v[156:159], v[92:95]
	ds_read_b128 v[234:237], v210 offset:36864
	s_waitcnt lgkmcnt(6)
	v_mfma_f32_16x16x32_bf16 v[32:35], v[238:241], v[140:143], v[32:35]
	v_mfma_f32_16x16x32_bf16 v[96:99], v[238:241], v[156:159], v[96:99]
	ds_read_b128 v[238:241], v209 offset:40960
	s_waitcnt lgkmcnt(6)
	v_mfma_f32_16x16x32_bf16 v[28:31], v[196:199], v[144:147], v[28:31]
	v_mfma_f32_16x16x32_bf16 v[92:95], v[196:199], v[160:163], v[92:95]
	ds_read_b128 v[196:199], v209 offset:45056
	s_waitcnt lgkmcnt(6)
	v_mfma_f32_16x16x32_bf16 v[32:35], v[200:203], v[144:147], v[32:35]
	v_mfma_f32_16x16x32_bf16 v[96:99], v[200:203], v[160:163], v[96:99]
	ds_read_b128 v[200:203], v210 offset:40960
	s_waitcnt lgkmcnt(6)
	v_mfma_f32_16x16x32_bf16 v[36:39], v[204:207], v[140:143], v[36:39]
	v_mfma_f32_16x16x32_bf16 v[100:103], v[204:207], v[156:159], v[100:103]
	ds_read_b128 v[204:207], v210 offset:45056
	s_waitcnt lgkmcnt(6)
	v_mfma_f32_16x16x32_bf16 v[40:43], v[220:223], v[140:143], v[40:43]
	v_mfma_f32_16x16x32_bf16 v[104:107], v[220:223], v[156:159], v[104:107]
	ds_read_b128 v[220:223], v209 offset:49152
	s_waitcnt lgkmcnt(6)
	v_mfma_f32_16x16x32_bf16 v[36:39], v[230:233], v[144:147], v[36:39]
	v_mfma_f32_16x16x32_bf16 v[100:103], v[230:233], v[160:163], v[100:103]
	ds_read_b128 v[230:233], v209 offset:53248
	s_waitcnt lgkmcnt(6)
	v_mfma_f32_16x16x32_bf16 v[40:43], v[234:237], v[144:147], v[40:43]
	v_mfma_f32_16x16x32_bf16 v[104:107], v[234:237], v[160:163], v[104:107]
	ds_read_b128 v[234:237], v210 offset:49152
	s_waitcnt lgkmcnt(6)
	v_mfma_f32_16x16x32_bf16 v[44:47], v[238:241], v[140:143], v[44:47]
	v_mfma_f32_16x16x32_bf16 v[108:111], v[238:241], v[156:159], v[108:111]
	ds_read_b128 v[238:241], v210 offset:53248
	s_waitcnt lgkmcnt(6)
	v_mfma_f32_16x16x32_bf16 v[48:51], v[196:199], v[140:143], v[48:51]
	v_mfma_f32_16x16x32_bf16 v[112:115], v[196:199], v[156:159], v[112:115]
	ds_read_b128 v[196:199], v209 offset:57344
	s_waitcnt lgkmcnt(6)
	v_mfma_f32_16x16x32_bf16 v[44:47], v[200:203], v[144:147], v[44:47]
	v_mfma_f32_16x16x32_bf16 v[108:111], v[200:203], v[160:163], v[108:111]
	ds_read_b128 v[200:203], v209 offset:61440
	s_waitcnt lgkmcnt(6)
	v_mfma_f32_16x16x32_bf16 v[48:51], v[204:207], v[144:147], v[48:51]
	v_mfma_f32_16x16x32_bf16 v[112:115], v[204:207], v[160:163], v[112:115]
	ds_read_b128 v[204:207], v210 offset:57344
	s_waitcnt lgkmcnt(6)
	v_mfma_f32_16x16x32_bf16 v[52:55], v[220:223], v[140:143], v[52:55]
	v_mfma_f32_16x16x32_bf16 v[116:119], v[220:223], v[156:159], v[116:119]
	ds_read_b128 v[220:223], v210 offset:61440
	s_waitcnt lgkmcnt(6)
	v_mfma_f32_16x16x32_bf16 v[56:59], v[230:233], v[140:143], v[56:59]
	v_mfma_f32_16x16x32_bf16 v[120:123], v[230:233], v[156:159], v[120:123]
	s_waitcnt lgkmcnt(5)
	v_mfma_f32_16x16x32_bf16 v[52:55], v[234:237], v[144:147], v[52:55]
	v_mfma_f32_16x16x32_bf16 v[116:119], v[234:237], v[160:163], v[116:119]
	s_waitcnt lgkmcnt(4)
	v_mfma_f32_16x16x32_bf16 v[56:59], v[238:241], v[144:147], v[56:59]
	v_mfma_f32_16x16x32_bf16 v[120:123], v[238:241], v[160:163], v[120:123]
	s_waitcnt lgkmcnt(3)
	v_mfma_f32_16x16x32_bf16 v[60:63], v[196:199], v[140:143], v[60:63]
	v_mfma_f32_16x16x32_bf16 v[124:127], v[196:199], v[156:159], v[124:127]
	s_waitcnt lgkmcnt(2)
	v_mfma_f32_16x16x32_bf16 v[64:67], v[200:203], v[140:143], v[64:67]
	v_mfma_f32_16x16x32_bf16 v[128:131], v[200:203], v[156:159], v[128:131]
	s_waitcnt lgkmcnt(1)
	v_mfma_f32_16x16x32_bf16 v[60:63], v[204:207], v[144:147], v[60:63]
	v_mfma_f32_16x16x32_bf16 v[124:127], v[204:207], v[160:163], v[124:127]
	s_waitcnt lgkmcnt(0)
; __device__ __forceinline__ f32x4 mfma16(bf16x8 a, bf16x8 b, f32x4 c) { return __builtin_amdgcn_mfma_f32_16x16x32_bf16(a, b, c, 0, 0, 0); }
; __device__ void cross_items(const Params& p, LAS unsigned char* lds) {
;     ...
;                 for (int ks = 0; ks < 4; ++ks) sc[kt] = mfma16(frag_row(buf, KV_STRIDE, 16 * kt, 32 * ks, idx, g), qf[ks], sc[kt]);
;         }
;         const float scl = 0.04419417382415922f * LOG2E;
;         float mx = -1e30f;
; #pragma unroll
;         for (int kt = 0; kt < 16; ++kt)
; #pragma unroll
;             for (int rr = 0; rr < 4; ++rr) { const float sv = sc[kt][rr] * scl; sc[kt][rr] = sv; mx = fmaxf(mx, sv); }
;         mx = fmaxf(mx, __shfl_xor(mx, 16)); mx = fmaxf(mx, __shfl_xor(mx, 32));
	v_mfma_f32_16x16x32_bf16 v[64:67], v[220:223], v[144:147], v[64:67]
	v_mfma_f32_16x16x32_bf16 v[128:131], v[220:223], v[160:163], v[128:131]
	v_xor_b32_e32 v2, 0x10000, v2
	v_xor_b32_e32 v208, 0x10000, v208
	v_xor_b32_e32 v209, 0x10000, v209
	v_xor_b32_e32 v210, 0x10000, v210
	s_nop 7
	s_nop 7
	v_and_b32_e32 v199, 63, v212
	v_xor_b32_e32 v196, 16, v199
	v_lshlrev_b32_e32 v196, 2, v196
	v_xor_b32_e32 v197, 32, v199
	v_lshlrev_b32_e32 v197, 2, v197
	s_mov_b32 s5, 0x3d8293ee
	v_mov_b32_e32 v198, 0xf149f2ca
	v_mul_f32_e32 v199, 0x3d8293ee, v4
	v_mul_f32_e32 v200, 0x3d8293ee, v5
	v_max3_f32 v198, v198, v199, v200
	v_mul_f32_e32 v199, 0x3d8293ee, v6
	v_mul_f32_e32 v200, 0x3d8293ee, v7
	v_max3_f32 v198, v198, v199, v200
	v_mul_f32_e32 v199, 0x3d8293ee, v8
	v_mul_f32_e32 v200, 0x3d8293ee, v9
	v_max3_f32 v198, v198, v199, v200
	v_mul_f32_e32 v199, 0x3d8293ee, v10
	v_mul_f32_e32 v200, 0x3d8293ee, v11
	v_max3_f32 v198, v198, v199, v200
	v_mul_f32_e32 v199, 0x3d8293ee, v12
	v_mul_f32_e32 v200, 0x3d8293ee, v13
	v_max3_f32 v198, v198, v199, v200
	v_mul_f32_e32 v199, 0x3d8293ee, v14
	v_mul_f32_e32 v200, 0x3d8293ee, v15
	v_max3_f32 v198, v198, v199, v200
	v_mul_f32_e32 v199, 0x3d8293ee, v16
	v_mul_f32_e32 v200, 0x3d8293ee, v17
	v_max3_f32 v198, v198, v199, v200
	v_mul_f32_e32 v199, 0x3d8293ee, v18
	v_mul_f32_e32 v200, 0x3d8293ee, v19
	v_max3_f32 v198, v198, v199, v200
	v_mul_f32_e32 v199, 0x3d8293ee, v20
	v_mul_f32_e32 v200, 0x3d8293ee, v21
	v_max3_f32 v198, v198, v199, v200
	v_mul_f32_e32 v199, 0x3d8293ee, v22
	v_mul_f32_e32 v200, 0x3d8293ee, v23
	v_max3_f32 v198, v198, v199, v200
	v_mul_f32_e32 v199, 0x3d8293ee, v24
	v_mul_f32_e32 v200, 0x3d8293ee, v25
	v_max3_f32 v198, v198, v199, v200
	v_mul_f32_e32 v199, 0x3d8293ee, v26
	v_mul_f32_e32 v200, 0x3d8293ee, v27
	v_max3_f32 v198, v198, v199, v200
	v_mul_f32_e32 v199, 0x3d8293ee, v28
	v_mul_f32_e32 v200, 0x3d8293ee, v29
	v_max3_f32 v198, v198, v199, v200
	v_mul_f32_e32 v199, 0x3d8293ee, v30
	v_mul_f32_e32 v200, 0x3d8293ee, v31
	v_max3_f32 v198, v198, v199, v200
	v_mul_f32_e32 v199, 0x3d8293ee, v32
	v_mul_f32_e32 v200, 0x3d8293ee, v33
	v_max3_f32 v198, v198, v199, v200
	v_mul_f32_e32 v199, 0x3d8293ee, v34
	v_mul_f32_e32 v200, 0x3d8293ee, v35
	v_max3_f32 v198, v198, v199, v200
	v_mul_f32_e32 v199, 0x3d8293ee, v36
	v_mul_f32_e32 v200, 0x3d8293ee, v37
	v_max3_f32 v198, v198, v199, v200
	v_mul_f32_e32 v199, 0x3d8293ee, v38
	v_mul_f32_e32 v200, 0x3d8293ee, v39
	v_max3_f32 v198, v198, v199, v200
	v_mul_f32_e32 v199, 0x3d8293ee, v40
	v_mul_f32_e32 v200, 0x3d8293ee, v41
	v_max3_f32 v198, v198, v199, v200
	v_mul_f32_e32 v199, 0x3d8293ee, v42
	v_mul_f32_e32 v200, 0x3d8293ee, v43
	v_max3_f32 v198, v198, v199, v200
	v_mul_f32_e32 v199, 0x3d8293ee, v44
	v_mul_f32_e32 v200, 0x3d8293ee, v45
	v_max3_f32 v198, v198, v199, v200
	v_mul_f32_e32 v199, 0x3d8293ee, v46
	v_mul_f32_e32 v200, 0x3d8293ee, v47
	v_max3_f32 v198, v198, v199, v200
	v_mul_f32_e32 v199, 0x3d8293ee, v48
	v_mul_f32_e32 v200, 0x3d8293ee, v49
	v_max3_f32 v198, v198, v199, v200
	v_mul_f32_e32 v199, 0x3d8293ee, v50
	v_mul_f32_e32 v200, 0x3d8293ee, v51
	v_max3_f32 v198, v198, v199, v200
	v_mul_f32_e32 v199, 0x3d8293ee, v52
	v_mul_f32_e32 v200, 0x3d8293ee, v53
	v_max3_f32 v198, v198, v199, v200
	v_mul_f32_e32 v199, 0x3d8293ee, v54
	v_mul_f32_e32 v200, 0x3d8293ee, v55
	v_max3_f32 v198, v198, v199, v200
	v_mul_f32_e32 v199, 0x3d8293ee, v56
	v_mul_f32_e32 v200, 0x3d8293ee, v57
	v_max3_f32 v198, v198, v199, v200
	v_mul_f32_e32 v199, 0x3d8293ee, v58
	v_mul_f32_e32 v200, 0x3d8293ee, v59
	v_max3_f32 v198, v198, v199, v200
	v_mul_f32_e32 v199, 0x3d8293ee, v60
	v_mul_f32_e32 v200, 0x3d8293ee, v61
	v_max3_f32 v198, v198, v199, v200
	v_mul_f32_e32 v199, 0x3d8293ee, v62
	v_mul_f32_e32 v200, 0x3d8293ee, v63
	v_max3_f32 v198, v198, v199, v200
	v_mul_f32_e32 v199, 0x3d8293ee, v64
	v_mul_f32_e32 v200, 0x3d8293ee, v65
	v_max3_f32 v198, v198, v199, v200
	v_mul_f32_e32 v199, 0x3d8293ee, v66
	v_mul_f32_e32 v200, 0x3d8293ee, v67
	v_max3_f32 v198, v198, v199, v200
	ds_bpermute_b32 v199, v196, v198
	s_waitcnt lgkmcnt(0)
	v_max_f32_e32 v198, v198, v199
	ds_bpermute_b32 v199, v197, v198
	s_waitcnt lgkmcnt(0)
	v_max_f32_e32 v198, v198, v199
	v_fma_f32 v4, v4, s5, -v198
	v_fma_f32 v5, v5, s5, -v198
	v_fma_f32 v6, v6, s5, -v198
	v_fma_f32 v7, v7, s5, -v198
	v_fma_f32 v8, v8, s5, -v198
	v_fma_f32 v9, v9, s5, -v198
	v_fma_f32 v10, v10, s5, -v198
	v_fma_f32 v11, v11, s5, -v198
	v_fma_f32 v12, v12, s5, -v198
	v_fma_f32 v13, v13, s5, -v198
	v_fma_f32 v14, v14, s5, -v198
	v_fma_f32 v15, v15, s5, -v198
	v_fma_f32 v16, v16, s5, -v198
	v_fma_f32 v17, v17, s5, -v198
	v_fma_f32 v18, v18, s5, -v198
	v_fma_f32 v19, v19, s5, -v198
	v_fma_f32 v20, v20, s5, -v198
	v_fma_f32 v21, v21, s5, -v198
	v_fma_f32 v22, v22, s5, -v198
	v_fma_f32 v23, v23, s5, -v198
	v_fma_f32 v24, v24, s5, -v198
	v_fma_f32 v25, v25, s5, -v198
	v_fma_f32 v26, v26, s5, -v198
	v_fma_f32 v27, v27, s5, -v198
	v_fma_f32 v28, v28, s5, -v198
	v_fma_f32 v29, v29, s5, -v198
	v_fma_f32 v30, v30, s5, -v198
	v_fma_f32 v31, v31, s5, -v198
	v_fma_f32 v32, v32, s5, -v198
	v_fma_f32 v33, v33, s5, -v198
	v_fma_f32 v34, v34, s5, -v198
	v_fma_f32 v35, v35, s5, -v198
	v_fma_f32 v36, v36, s5, -v198
	v_fma_f32 v37, v37, s5, -v198
	v_fma_f32 v38, v38, s5, -v198
	v_fma_f32 v39, v39, s5, -v198
	v_fma_f32 v40, v40, s5, -v198
	v_fma_f32 v41, v41, s5, -v198
	v_fma_f32 v42, v42, s5, -v198
	v_fma_f32 v43, v43, s5, -v198
	v_fma_f32 v44, v44, s5, -v198
	v_fma_f32 v45, v45, s5, -v198
	v_fma_f32 v46, v46, s5, -v198
	v_fma_f32 v47, v47, s5, -v198
	v_fma_f32 v48, v48, s5, -v198
	v_fma_f32 v49, v49, s5, -v198
	v_fma_f32 v50, v50, s5, -v198
	v_fma_f32 v51, v51, s5, -v198
; __device__ __forceinline__ unsigned cvt_pk_bf16(float lo, float hi) { const f32x2v v = {lo, hi}; const b16x2v r = __builtin_convertvector(v, b16x2v); return __builtin_bit_cast(unsigned, r); }
; __device__ __forceinline__ float fexp2(float x) { return __builtin_amdgcn_exp2f(x); }
; __device__ void cross_items(const Params& p, LAS unsigned char* lds) {
;     ...
;         float sum = 0.f;
; #pragma unroll
;         for (int kt = 0; kt < 16; ++kt)
; #pragma unroll
;             for (int rr = 0; rr < 4; ++rr) { const float e = fexp2(sc[kt][rr] - mx); sc[kt][rr] = e; sum += e; }
;         sum += __shfl_xor(sum, 16); sum += __shfl_xor(sum, 32);
;         const float inv = 1.0f / sum;
;         bf16x8 pf[8];
; #pragma unroll
;         for (int sx = 0; sx < 8; ++sx) { u32x4 pw; pw.x = cvt_pk_bf16(sc[2 * sx][0], sc[2 * sx][1]); pw.y = cvt_pk_bf16(sc[2 * sx][2], sc[2 * sx][3]); pw.z = cvt_pk_bf16(sc[2 * sx + 1][0], sc[2 * sx + 1][1]); pw.w = cvt_pk_bf16(sc[2 * sx + 1][2], sc[2 * sx + 1][3]);
;             pf[sx] = __builtin_bit_cast(bf16x8, pw); }
	v_fma_f32 v52, v52, s5, -v198
	v_fma_f32 v53, v53, s5, -v198
	v_fma_f32 v54, v54, s5, -v198
	v_fma_f32 v55, v55, s5, -v198
	v_fma_f32 v56, v56, s5, -v198
	v_fma_f32 v57, v57, s5, -v198
	v_fma_f32 v58, v58, s5, -v198
	v_fma_f32 v59, v59, s5, -v198
	v_fma_f32 v60, v60, s5, -v198
	v_fma_f32 v61, v61, s5, -v198
	v_fma_f32 v62, v62, s5, -v198
	v_fma_f32 v63, v63, s5, -v198
	v_fma_f32 v64, v64, s5, -v198
	v_fma_f32 v65, v65, s5, -v198
	v_fma_f32 v66, v66, s5, -v198
	v_fma_f32 v67, v67, s5, -v198
	v_exp_f32_e32 v4, v4
	v_exp_f32_e32 v5, v5
	v_exp_f32_e32 v6, v6
	v_exp_f32_e32 v7, v7
	v_exp_f32_e32 v8, v8
	v_exp_f32_e32 v9, v9
	v_exp_f32_e32 v10, v10
	v_exp_f32_e32 v11, v11
	v_exp_f32_e32 v12, v12
	v_exp_f32_e32 v13, v13
	v_exp_f32_e32 v14, v14
	v_exp_f32_e32 v15, v15
	v_exp_f32_e32 v16, v16
	v_exp_f32_e32 v17, v17
	v_exp_f32_e32 v18, v18
	v_exp_f32_e32 v19, v19
	v_exp_f32_e32 v20, v20
	v_exp_f32_e32 v21, v21
	v_exp_f32_e32 v22, v22
	v_exp_f32_e32 v23, v23
	v_exp_f32_e32 v24, v24
	v_exp_f32_e32 v25, v25
	v_exp_f32_e32 v26, v26
	v_exp_f32_e32 v27, v27
	v_exp_f32_e32 v28, v28
	v_exp_f32_e32 v29, v29
	v_exp_f32_e32 v30, v30
	v_exp_f32_e32 v31, v31
	v_exp_f32_e32 v32, v32
	v_exp_f32_e32 v33, v33
	v_exp_f32_e32 v34, v34
	v_exp_f32_e32 v35, v35
	v_exp_f32_e32 v36, v36
	v_exp_f32_e32 v37, v37
	v_exp_f32_e32 v38, v38
	v_exp_f32_e32 v39, v39
	v_exp_f32_e32 v40, v40
	v_exp_f32_e32 v41, v41
	v_exp_f32_e32 v42, v42
	v_exp_f32_e32 v43, v43
	v_exp_f32_e32 v44, v44
	v_exp_f32_e32 v45, v45
	v_exp_f32_e32 v46, v46
	v_exp_f32_e32 v47, v47
	v_exp_f32_e32 v48, v48
	v_exp_f32_e32 v49, v49
	v_exp_f32_e32 v50, v50
	v_exp_f32_e32 v51, v51
	v_exp_f32_e32 v52, v52
	v_exp_f32_e32 v53, v53
	v_exp_f32_e32 v54, v54
	v_exp_f32_e32 v55, v55
	v_exp_f32_e32 v56, v56
	v_exp_f32_e32 v57, v57
	v_exp_f32_e32 v58, v58
	v_exp_f32_e32 v59, v59
	v_exp_f32_e32 v60, v60
	v_exp_f32_e32 v61, v61
	v_exp_f32_e32 v62, v62
	v_exp_f32_e32 v63, v63
	v_exp_f32_e32 v64, v64
	v_exp_f32_e32 v65, v65
	v_exp_f32_e32 v66, v66
	v_exp_f32_e32 v67, v67
	s_nop 0
	v_add_f32_e32 v201, 0, v4
	v_add_f32_e32 v201, v5, v201
	v_add_f32_e32 v201, v6, v201
	v_add_f32_e32 v201, v7, v201
	v_add_f32_e32 v201, v8, v201
	v_add_f32_e32 v201, v9, v201
	v_add_f32_e32 v201, v10, v201
	v_add_f32_e32 v201, v11, v201
	v_add_f32_e32 v201, v12, v201
	v_add_f32_e32 v201, v13, v201
	v_add_f32_e32 v201, v14, v201
	v_add_f32_e32 v201, v15, v201
	v_add_f32_e32 v201, v16, v201
	v_add_f32_e32 v201, v17, v201
	v_add_f32_e32 v201, v18, v201
	v_add_f32_e32 v201, v19, v201
	v_add_f32_e32 v201, v20, v201
	v_add_f32_e32 v201, v21, v201
	v_add_f32_e32 v201, v22, v201
	v_add_f32_e32 v201, v23, v201
	v_add_f32_e32 v201, v24, v201
	v_add_f32_e32 v201, v25, v201
	v_add_f32_e32 v201, v26, v201
	v_add_f32_e32 v201, v27, v201
	v_add_f32_e32 v201, v28, v201
	v_add_f32_e32 v201, v29, v201
	v_add_f32_e32 v201, v30, v201
	v_add_f32_e32 v201, v31, v201
	v_add_f32_e32 v201, v32, v201
	v_add_f32_e32 v201, v33, v201
	v_add_f32_e32 v201, v34, v201
	v_add_f32_e32 v201, v35, v201
	v_add_f32_e32 v201, v36, v201
	v_add_f32_e32 v201, v37, v201
	v_add_f32_e32 v201, v38, v201
	v_add_f32_e32 v201, v39, v201
	v_add_f32_e32 v201, v40, v201
	v_add_f32_e32 v201, v41, v201
	v_add_f32_e32 v201, v42, v201
	v_add_f32_e32 v201, v43, v201
	v_add_f32_e32 v201, v44, v201
	v_add_f32_e32 v201, v45, v201
	v_add_f32_e32 v201, v46, v201
	v_add_f32_e32 v201, v47, v201
	v_add_f32_e32 v201, v48, v201
	v_add_f32_e32 v201, v49, v201
	v_add_f32_e32 v201, v50, v201
	v_add_f32_e32 v201, v51, v201
	v_add_f32_e32 v201, v52, v201
	v_add_f32_e32 v201, v53, v201
	v_add_f32_e32 v201, v54, v201
	v_add_f32_e32 v201, v55, v201
	v_add_f32_e32 v201, v56, v201
	v_add_f32_e32 v201, v57, v201
	v_add_f32_e32 v201, v58, v201
	v_add_f32_e32 v201, v59, v201
	v_add_f32_e32 v201, v60, v201
	v_add_f32_e32 v201, v61, v201
	v_add_f32_e32 v201, v62, v201
	v_add_f32_e32 v201, v63, v201
	v_add_f32_e32 v201, v64, v201
	v_add_f32_e32 v201, v65, v201
	v_add_f32_e32 v201, v66, v201
	v_add_f32_e32 v201, v67, v201
	ds_bpermute_b32 v199, v196, v201
	s_waitcnt lgkmcnt(0)
	v_add_f32_e32 v201, v201, v199
	ds_bpermute_b32 v199, v197, v201
	s_waitcnt lgkmcnt(0)
	v_add_f32_e32 v201, v201, v199
	v_div_scale_f32 v199, s[8:9], v201, v201, 1.0
	v_rcp_f32_e32 v200, v199
	s_nop 0
	v_fma_f32 v244, -v199, v200, 1.0
	v_fmac_f32_e32 v200, v244, v200
	v_div_scale_f32 v244, vcc, 1.0, v201, 1.0
	v_mul_f32_e32 v202, v244, v200
	v_fma_f32 v203, -v199, v202, v244
	v_fmac_f32_e32 v202, v203, v200
	v_fma_f32 v199, -v199, v202, v244
	s_nop 1
	v_div_fmas_f32 v199, v199, v200, v202
	v_div_fixup_f32 v244, v199, v201, 1.0
	v_cvt_pk_bf16_f32 v4, v4, v5
	v_cvt_pk_bf16_f32 v5, v6, v7
	v_cvt_pk_bf16_f32 v6, v8, v9
	v_cvt_pk_bf16_f32 v7, v10, v11
	v_cvt_pk_bf16_f32 v12, v12, v13
	v_cvt_pk_bf16_f32 v13, v14, v15
	v_cvt_pk_bf16_f32 v14, v16, v17
	v_cvt_pk_bf16_f32 v15, v18, v19
	v_cvt_pk_bf16_f32 v20, v20, v21
	v_cvt_pk_bf16_f32 v21, v22, v23
	v_cvt_pk_bf16_f32 v22, v24, v25
	v_cvt_pk_bf16_f32 v23, v26, v27
	v_cvt_pk_bf16_f32 v28, v28, v29
	v_cvt_pk_bf16_f32 v29, v30, v31
	v_cvt_pk_bf16_f32 v30, v32, v33
	v_cvt_pk_bf16_f32 v31, v34, v35
	v_cvt_pk_bf16_f32 v36, v36, v37
	v_cvt_pk_bf16_f32 v37, v38, v39
	v_cvt_pk_bf16_f32 v38, v40, v41
	v_cvt_pk_bf16_f32 v39, v42, v43
	v_cvt_pk_bf16_f32 v44, v44, v45
	v_cvt_pk_bf16_f32 v45, v46, v47
	v_cvt_pk_bf16_f32 v46, v48, v49
	v_cvt_pk_bf16_f32 v47, v50, v51
	v_cvt_pk_bf16_f32 v52, v52, v53
	v_cvt_pk_bf16_f32 v53, v54, v55
	v_cvt_pk_bf16_f32 v54, v56, v57
	v_cvt_pk_bf16_f32 v55, v58, v59
	v_cvt_pk_bf16_f32 v60, v60, v61
	v_cvt_pk_bf16_f32 v61, v62, v63
	v_cvt_pk_bf16_f32 v62, v64, v65
	v_cvt_pk_bf16_f32 v63, v66, v67
; __device__ void cross_items(const Params& p, LAS unsigned char* lds) {
;     ...
;         float mx = -1e30f;
; #pragma unroll
;         for (int kt = 0; kt < 16; ++kt)
; #pragma unroll
;             for (int rr = 0; rr < 4; ++rr) { const float sv = sc[kt][rr] * scl; sc[kt][rr] = sv; mx = fmaxf(mx, sv); }
;         mx = fmaxf(mx, __shfl_xor(mx, 16)); mx = fmaxf(mx, __shfl_xor(mx, 32));
	v_mov_b32_e32 v198, 0xf149f2ca
	v_mul_f32_e32 v199, 0x3d8293ee, v68
	v_mul_f32_e32 v200, 0x3d8293ee, v69
	v_max3_f32 v198, v198, v199, v200
	v_mul_f32_e32 v199, 0x3d8293ee, v70
	v_mul_f32_e32 v200, 0x3d8293ee, v71
	v_max3_f32 v198, v198, v199, v200
	v_mul_f32_e32 v199, 0x3d8293ee, v72
	v_mul_f32_e32 v200, 0x3d8293ee, v73
	v_max3_f32 v198, v198, v199, v200
	v_mul_f32_e32 v199, 0x3d8293ee, v74
	v_mul_f32_e32 v200, 0x3d8293ee, v75
	v_max3_f32 v198, v198, v199, v200
	v_mul_f32_e32 v199, 0x3d8293ee, v76
	v_mul_f32_e32 v200, 0x3d8293ee, v77
	v_max3_f32 v198, v198, v199, v200
	v_mul_f32_e32 v199, 0x3d8293ee, v78
	v_mul_f32_e32 v200, 0x3d8293ee, v79
	v_max3_f32 v198, v198, v199, v200
	v_mul_f32_e32 v199, 0x3d8293ee, v80
	v_mul_f32_e32 v200, 0x3d8293ee, v81
	v_max3_f32 v198, v198, v199, v200
	v_mul_f32_e32 v199, 0x3d8293ee, v82
	v_mul_f32_e32 v200, 0x3d8293ee, v83
	v_max3_f32 v198, v198, v199, v200
	v_mul_f32_e32 v199, 0x3d8293ee, v84
	v_mul_f32_e32 v200, 0x3d8293ee, v85
	v_max3_f32 v198, v198, v199, v200
	v_mul_f32_e32 v199, 0x3d8293ee, v86
	v_mul_f32_e32 v200, 0x3d8293ee, v87
	v_max3_f32 v198, v198, v199, v200
	v_mul_f32_e32 v199, 0x3d8293ee, v88
	v_mul_f32_e32 v200, 0x3d8293ee, v89
	v_max3_f32 v198, v198, v199, v200
	v_mul_f32_e32 v199, 0x3d8293ee, v90
	v_mul_f32_e32 v200, 0x3d8293ee, v91
	v_max3_f32 v198, v198, v199, v200
	v_mul_f32_e32 v199, 0x3d8293ee, v92
	v_mul_f32_e32 v200, 0x3d8293ee, v93
	v_max3_f32 v198, v198, v199, v200
	v_mul_f32_e32 v199, 0x3d8293ee, v94
	v_mul_f32_e32 v200, 0x3d8293ee, v95
	v_max3_f32 v198, v198, v199, v200
	v_mul_f32_e32 v199, 0x3d8293ee, v96
	v_mul_f32_e32 v200, 0x3d8293ee, v97
	v_max3_f32 v198, v198, v199, v200
	v_mul_f32_e32 v199, 0x3d8293ee, v98
	v_mul_f32_e32 v200, 0x3d8293ee, v99
	v_max3_f32 v198, v198, v199, v200
	v_mul_f32_e32 v199, 0x3d8293ee, v100
	v_mul_f32_e32 v200, 0x3d8293ee, v101
	v_max3_f32 v198, v198, v199, v200
	v_mul_f32_e32 v199, 0x3d8293ee, v102
	v_mul_f32_e32 v200, 0x3d8293ee, v103
	v_max3_f32 v198, v198, v199, v200
	v_mul_f32_e32 v199, 0x3d8293ee, v104
	v_mul_f32_e32 v200, 0x3d8293ee, v105
	v_max3_f32 v198, v198, v199, v200
	v_mul_f32_e32 v199, 0x3d8293ee, v106
	v_mul_f32_e32 v200, 0x3d8293ee, v107
	v_max3_f32 v198, v198, v199, v200
	v_mul_f32_e32 v199, 0x3d8293ee, v108
	v_mul_f32_e32 v200, 0x3d8293ee, v109
	v_max3_f32 v198, v198, v199, v200
	v_mul_f32_e32 v199, 0x3d8293ee, v110
	v_mul_f32_e32 v200, 0x3d8293ee, v111
	v_max3_f32 v198, v198, v199, v200
	v_mul_f32_e32 v199, 0x3d8293ee, v112
	v_mul_f32_e32 v200, 0x3d8293ee, v113
	v_max3_f32 v198, v198, v199, v200
	v_mul_f32_e32 v199, 0x3d8293ee, v114
	v_mul_f32_e32 v200, 0x3d8293ee, v115
	v_max3_f32 v198, v198, v199, v200
	v_mul_f32_e32 v199, 0x3d8293ee, v116
	v_mul_f32_e32 v200, 0x3d8293ee, v117
	v_max3_f32 v198, v198, v199, v200
	v_mul_f32_e32 v199, 0x3d8293ee, v118
	v_mul_f32_e32 v200, 0x3d8293ee, v119
	v_max3_f32 v198, v198, v199, v200
	v_mul_f32_e32 v199, 0x3d8293ee, v120
	v_mul_f32_e32 v200, 0x3d8293ee, v121
	v_max3_f32 v198, v198, v199, v200
	v_mul_f32_e32 v199, 0x3d8293ee, v122
	v_mul_f32_e32 v200, 0x3d8293ee, v123
	v_max3_f32 v198, v198, v199, v200
	v_mul_f32_e32 v199, 0x3d8293ee, v124
	v_mul_f32_e32 v200, 0x3d8293ee, v125
	v_max3_f32 v198, v198, v199, v200
	v_mul_f32_e32 v199, 0x3d8293ee, v126
	v_mul_f32_e32 v200, 0x3d8293ee, v127
	v_max3_f32 v198, v198, v199, v200
	v_mul_f32_e32 v199, 0x3d8293ee, v128
	v_mul_f32_e32 v200, 0x3d8293ee, v129
	v_max3_f32 v198, v198, v199, v200
	v_mul_f32_e32 v199, 0x3d8293ee, v130
	v_mul_f32_e32 v200, 0x3d8293ee, v131
	v_max3_f32 v198, v198, v199, v200
	ds_bpermute_b32 v199, v196, v198
	s_waitcnt lgkmcnt(0)
	v_max_f32_e32 v198, v198, v199
	ds_bpermute_b32 v199, v197, v198
	s_waitcnt lgkmcnt(0)
	v_max_f32_e32 v198, v198, v199
	v_fma_f32 v68, v68, s5, -v198
	v_fma_f32 v69, v69, s5, -v198
	v_fma_f32 v70, v70, s5, -v198
	v_fma_f32 v71, v71, s5, -v198
	v_fma_f32 v72, v72, s5, -v198
	v_fma_f32 v73, v73, s5, -v198
	v_fma_f32 v74, v74, s5, -v198
	v_fma_f32 v75, v75, s5, -v198
	v_fma_f32 v76, v76, s5, -v198
	v_fma_f32 v77, v77, s5, -v198
	v_fma_f32 v78, v78, s5, -v198
	v_fma_f32 v79, v79, s5, -v198
	v_fma_f32 v80, v80, s5, -v198
	v_fma_f32 v81, v81, s5, -v198
	v_fma_f32 v82, v82, s5, -v198
	v_fma_f32 v83, v83, s5, -v198
	v_fma_f32 v84, v84, s5, -v198
	v_fma_f32 v85, v85, s5, -v198
	v_fma_f32 v86, v86, s5, -v198
	v_fma_f32 v87, v87, s5, -v198
	v_fma_f32 v88, v88, s5, -v198
	v_fma_f32 v89, v89, s5, -v198
	v_fma_f32 v90, v90, s5, -v198
	v_fma_f32 v91, v91, s5, -v198
	v_fma_f32 v92, v92, s5, -v198
	v_fma_f32 v93, v93, s5, -v198
	v_fma_f32 v94, v94, s5, -v198
	v_fma_f32 v95, v95, s5, -v198
	v_fma_f32 v96, v96, s5, -v198
	v_fma_f32 v97, v97, s5, -v198
	v_fma_f32 v98, v98, s5, -v198
	v_fma_f32 v99, v99, s5, -v198
	v_fma_f32 v100, v100, s5, -v198
	v_fma_f32 v101, v101, s5, -v198
	v_fma_f32 v102, v102, s5, -v198
	v_fma_f32 v103, v103, s5, -v198
	v_fma_f32 v104, v104, s5, -v198
	v_fma_f32 v105, v105, s5, -v198
	v_fma_f32 v106, v106, s5, -v198
	v_fma_f32 v107, v107, s5, -v198
	v_fma_f32 v108, v108, s5, -v198
	v_fma_f32 v109, v109, s5, -v198
	v_fma_f32 v110, v110, s5, -v198
	v_fma_f32 v111, v111, s5, -v198
	v_fma_f32 v112, v112, s5, -v198
	v_fma_f32 v113, v113, s5, -v198
	v_fma_f32 v114, v114, s5, -v198
	v_fma_f32 v115, v115, s5, -v198
	v_fma_f32 v116, v116, s5, -v198
	v_fma_f32 v117, v117, s5, -v198
	v_fma_f32 v118, v118, s5, -v198
	v_fma_f32 v119, v119, s5, -v198
	v_fma_f32 v120, v120, s5, -v198
	v_fma_f32 v121, v121, s5, -v198
	v_fma_f32 v122, v122, s5, -v198
	v_fma_f32 v123, v123, s5, -v198
	v_fma_f32 v124, v124, s5, -v198
	v_fma_f32 v125, v125, s5, -v198
	v_fma_f32 v126, v126, s5, -v198
	v_fma_f32 v127, v127, s5, -v198
; __device__ __forceinline__ unsigned cvt_pk_bf16(float lo, float hi) { const f32x2v v = {lo, hi}; const b16x2v r = __builtin_convertvector(v, b16x2v); return __builtin_bit_cast(unsigned, r); }
; __device__ __forceinline__ float fexp2(float x) { return __builtin_amdgcn_exp2f(x); }
; __device__ void cross_items(const Params& p, LAS unsigned char* lds) {
;     ...
;         for (int kt = 0; kt < 16; ++kt)
; #pragma unroll
;             for (int rr = 0; rr < 4; ++rr) { const float e = fexp2(sc[kt][rr] - mx); sc[kt][rr] = e; sum += e; }
;         sum += __shfl_xor(sum, 16); sum += __shfl_xor(sum, 32);
;         const float inv = 1.0f / sum;
;         bf16x8 pf[8];
; #pragma unroll
;         for (int sx = 0; sx < 8; ++sx) { u32x4 pw; pw.x = cvt_pk_bf16(sc[2 * sx][0], sc[2 * sx][1]); pw.y = cvt_pk_bf16(sc[2 * sx][2], sc[2 * sx][3]); pw.z = cvt_pk_bf16(sc[2 * sx + 1][0], sc[2 * sx + 1][1]); pw.w = cvt_pk_bf16(sc[2 * sx + 1][2], sc[2 * sx + 1][3]);
;             pf[sx] = __builtin_bit_cast(bf16x8, pw); }
;     ...
; #pragma unroll
;             for (int sx = 0; sx < 8; ++sx) {
;                 const unsigned aA = bb + (unsigned)((32 * sx + 4 * g + (idx >> 2)) * KV_STRIDE + 8 * (idx & 3));
;                 const unsigned aB = aA + 16u * KV_STRIDE;
	v_fma_f32 v128, v128, s5, -v198
	v_fma_f32 v129, v129, s5, -v198
	v_fma_f32 v130, v130, s5, -v198
	v_fma_f32 v131, v131, s5, -v198
	v_exp_f32_e32 v68, v68
	v_exp_f32_e32 v69, v69
	v_exp_f32_e32 v70, v70
	v_exp_f32_e32 v71, v71
	v_exp_f32_e32 v72, v72
	v_exp_f32_e32 v73, v73
	v_exp_f32_e32 v74, v74
	v_exp_f32_e32 v75, v75
	v_exp_f32_e32 v76, v76
	v_exp_f32_e32 v77, v77
	v_exp_f32_e32 v78, v78
	v_exp_f32_e32 v79, v79
	v_exp_f32_e32 v80, v80
	v_exp_f32_e32 v81, v81
	v_exp_f32_e32 v82, v82
	v_exp_f32_e32 v83, v83
	v_exp_f32_e32 v84, v84
	v_exp_f32_e32 v85, v85
	v_exp_f32_e32 v86, v86
	v_exp_f32_e32 v87, v87
	v_exp_f32_e32 v88, v88
	v_exp_f32_e32 v89, v89
	v_exp_f32_e32 v90, v90
	v_exp_f32_e32 v91, v91
	v_exp_f32_e32 v92, v92
	v_exp_f32_e32 v93, v93
	v_exp_f32_e32 v94, v94
	v_exp_f32_e32 v95, v95
	v_exp_f32_e32 v96, v96
	v_exp_f32_e32 v97, v97
	v_exp_f32_e32 v98, v98
	v_exp_f32_e32 v99, v99
	v_exp_f32_e32 v100, v100
	v_exp_f32_e32 v101, v101
	v_exp_f32_e32 v102, v102
	v_exp_f32_e32 v103, v103
	v_exp_f32_e32 v104, v104
	v_exp_f32_e32 v105, v105
	v_exp_f32_e32 v106, v106
	v_exp_f32_e32 v107, v107
	v_exp_f32_e32 v108, v108
	v_exp_f32_e32 v109, v109
	v_exp_f32_e32 v110, v110
	v_exp_f32_e32 v111, v111
	v_exp_f32_e32 v112, v112
	v_exp_f32_e32 v113, v113
	v_exp_f32_e32 v114, v114
	v_exp_f32_e32 v115, v115
	v_exp_f32_e32 v116, v116
	v_exp_f32_e32 v117, v117
	v_exp_f32_e32 v118, v118
	v_exp_f32_e32 v119, v119
	v_exp_f32_e32 v120, v120
	v_exp_f32_e32 v121, v121
	v_exp_f32_e32 v122, v122
	v_exp_f32_e32 v123, v123
	v_exp_f32_e32 v124, v124
	v_exp_f32_e32 v125, v125
	v_exp_f32_e32 v126, v126
	v_exp_f32_e32 v127, v127
	v_exp_f32_e32 v128, v128
	v_exp_f32_e32 v129, v129
	v_exp_f32_e32 v130, v130
	v_exp_f32_e32 v131, v131
	s_nop 0
	v_add_f32_e32 v201, 0, v68
	v_add_f32_e32 v201, v69, v201
	v_add_f32_e32 v201, v70, v201
	v_add_f32_e32 v201, v71, v201
	v_add_f32_e32 v201, v72, v201
	v_add_f32_e32 v201, v73, v201
	v_add_f32_e32 v201, v74, v201
	v_add_f32_e32 v201, v75, v201
	v_add_f32_e32 v201, v76, v201
	v_add_f32_e32 v201, v77, v201
	v_add_f32_e32 v201, v78, v201
	v_add_f32_e32 v201, v79, v201
	v_add_f32_e32 v201, v80, v201
	v_add_f32_e32 v201, v81, v201
	v_add_f32_e32 v201, v82, v201
	v_add_f32_e32 v201, v83, v201
	v_add_f32_e32 v201, v84, v201
	v_add_f32_e32 v201, v85, v201
	v_add_f32_e32 v201, v86, v201
	v_add_f32_e32 v201, v87, v201
	v_add_f32_e32 v201, v88, v201
	v_add_f32_e32 v201, v89, v201
	v_add_f32_e32 v201, v90, v201
	v_add_f32_e32 v201, v91, v201
	v_add_f32_e32 v201, v92, v201
	v_add_f32_e32 v201, v93, v201
	v_add_f32_e32 v201, v94, v201
	v_add_f32_e32 v201, v95, v201
	v_add_f32_e32 v201, v96, v201
	v_add_f32_e32 v201, v97, v201
	v_add_f32_e32 v201, v98, v201
	v_add_f32_e32 v201, v99, v201
	v_add_f32_e32 v201, v100, v201
	v_add_f32_e32 v201, v101, v201
	v_add_f32_e32 v201, v102, v201
	v_add_f32_e32 v201, v103, v201
	v_add_f32_e32 v201, v104, v201
	v_add_f32_e32 v201, v105, v201
	v_add_f32_e32 v201, v106, v201
	v_add_f32_e32 v201, v107, v201
	v_add_f32_e32 v201, v108, v201
	v_add_f32_e32 v201, v109, v201
	v_add_f32_e32 v201, v110, v201
	v_add_f32_e32 v201, v111, v201
	v_add_f32_e32 v201, v112, v201
	v_add_f32_e32 v201, v113, v201
	v_add_f32_e32 v201, v114, v201
	v_add_f32_e32 v201, v115, v201
	v_add_f32_e32 v201, v116, v201
	v_add_f32_e32 v201, v117, v201
	v_add_f32_e32 v201, v118, v201
	v_add_f32_e32 v201, v119, v201
	v_add_f32_e32 v201, v120, v201
	v_add_f32_e32 v201, v121, v201
	v_add_f32_e32 v201, v122, v201
	v_add_f32_e32 v201, v123, v201
	v_add_f32_e32 v201, v124, v201
	v_add_f32_e32 v201, v125, v201
	v_add_f32_e32 v201, v126, v201
	v_add_f32_e32 v201, v127, v201
	v_add_f32_e32 v201, v128, v201
	v_add_f32_e32 v201, v129, v201
	v_add_f32_e32 v201, v130, v201
	v_add_f32_e32 v201, v131, v201
	ds_bpermute_b32 v199, v196, v201
	s_waitcnt lgkmcnt(0)
	v_add_f32_e32 v201, v201, v199
	ds_bpermute_b32 v199, v197, v201
	s_waitcnt lgkmcnt(0)
	v_add_f32_e32 v201, v201, v199
	v_div_scale_f32 v199, s[8:9], v201, v201, 1.0
	v_rcp_f32_e32 v200, v199
	s_nop 0
	v_fma_f32 v245, -v199, v200, 1.0
	v_fmac_f32_e32 v200, v245, v200
	v_div_scale_f32 v245, vcc, 1.0, v201, 1.0
	v_mul_f32_e32 v202, v245, v200
	v_fma_f32 v203, -v199, v202, v245
	v_fmac_f32_e32 v202, v203, v200
	v_fma_f32 v199, -v199, v202, v245
	s_nop 1
	v_div_fmas_f32 v199, v199, v200, v202
	v_div_fixup_f32 v245, v199, v201, 1.0
	v_cvt_pk_bf16_f32 v68, v68, v69
	v_cvt_pk_bf16_f32 v69, v70, v71
	v_cvt_pk_bf16_f32 v70, v72, v73
	v_cvt_pk_bf16_f32 v71, v74, v75
	v_cvt_pk_bf16_f32 v76, v76, v77
	v_cvt_pk_bf16_f32 v77, v78, v79
	v_cvt_pk_bf16_f32 v78, v80, v81
	v_cvt_pk_bf16_f32 v79, v82, v83
	v_cvt_pk_bf16_f32 v84, v84, v85
	v_cvt_pk_bf16_f32 v85, v86, v87
	v_cvt_pk_bf16_f32 v86, v88, v89
	v_cvt_pk_bf16_f32 v87, v90, v91
	v_cvt_pk_bf16_f32 v92, v92, v93
	v_cvt_pk_bf16_f32 v93, v94, v95
	v_cvt_pk_bf16_f32 v94, v96, v97
	v_cvt_pk_bf16_f32 v95, v98, v99
	v_cvt_pk_bf16_f32 v100, v100, v101
	v_cvt_pk_bf16_f32 v101, v102, v103
	v_cvt_pk_bf16_f32 v102, v104, v105
	v_cvt_pk_bf16_f32 v103, v106, v107
	v_cvt_pk_bf16_f32 v108, v108, v109
	v_cvt_pk_bf16_f32 v109, v110, v111
	v_cvt_pk_bf16_f32 v110, v112, v113
	v_cvt_pk_bf16_f32 v111, v114, v115
	v_cvt_pk_bf16_f32 v116, v116, v117
	v_cvt_pk_bf16_f32 v117, v118, v119
	v_cvt_pk_bf16_f32 v118, v120, v121
	v_cvt_pk_bf16_f32 v119, v122, v123
	v_cvt_pk_bf16_f32 v124, v124, v125
	v_cvt_pk_bf16_f32 v125, v126, v127
	v_cvt_pk_bf16_f32 v126, v128, v129
	v_cvt_pk_bf16_f32 v127, v130, v131
	v_and_b32_e32 v204, 63, v212
	v_and_b32_e32 v205, 15, v204
	v_lshrrev_b32_e32 v204, 4, v204
	v_lshrrev_b32_e32 v206, 2, v205
	v_lshl_add_u32 v206, v204, 2, v206
	v_and_b32_e32 v207, 7, v206
	v_lshlrev_b32_e32 v207, 1, v207
	v_bfe_u32 v204, v205, 1, 1
	v_add_u32_e32 v207, v207, v204
	v_and_b32_e32 v204, 1, v205
	v_lshlrev_b32_e32 v204, 3, v204
	v_lshl_add_u32 v206, v206, 8, v204
	v_add_u32_e32 v204, 0, v207
	v_and_b32_e32 v204, 15, v204
	v_lshl_add_u32 v196, v204, 4, v206
	v_add_u32_e32 v204, 2, v207
	v_and_b32_e32 v204, 15, v204
	v_lshl_add_u32 v197, v204, 4, v206
	v_add_u32_e32 v204, 4, v207
	v_and_b32_e32 v204, 15, v204
	v_lshl_add_u32 v198, v204, 4, v206
	v_add_u32_e32 v204, 6, v207
	v_and_b32_e32 v204, 15, v204
	v_lshl_add_u32 v199, v204, 4, v206
	v_add_u32_e32 v204, 8, v207
	v_and_b32_e32 v204, 15, v204
	v_lshl_add_u32 v200, v204, 4, v206
	v_add_u32_e32 v204, 10, v207
	v_and_b32_e32 v204, 15, v204
	v_lshl_add_u32 v201, v204, 4, v206
	v_add_u32_e32 v204, 12, v207
	v_and_b32_e32 v204, 15, v204
	v_lshl_add_u32 v202, v204, 4, v206
	v_add_u32_e32 v204, 14, v207
	v_and_b32_e32 v204, 15, v204
	v_lshl_add_u32 v203, v204, 4, v206
	s_waitcnt vmcnt(7)
; #define LAS __attribute__((address_space(3)))
; __device__ __forceinline__ f32x4 mfma16(bf16x8 a, bf16x8 b, f32x4 c) { return __builtin_amdgcn_mfma_f32_16x16x32_bf16(a, b, c, 0, 0, 0); }
; #define LDS_BARRIER() do { asm volatile("s_waitcnt lgkmcnt(0)" ::: "memory"); __builtin_amdgcn_s_barrier(); asm volatile("" ::: "memory"); } while (0)
; #define XLOAD(kvbase, c8) do { const bf16_t* _src = (kvbase) + (((c8) >= 4) ? 2048 : 0) + ((c8) & 3) * 128 + piece * 8; \
;         _Pragma("unroll") for (int _it = 0; _it < 8; ++_it) pre[_it] = *(const u32x4*)(_src + (size_t)(srow + 32 * _it) * 4096); } while (0)
; #define XSTORE(buf) do { _Pragma("unroll") for (int _it = 0; _it < 8; ++_it) *(LAS u32x4*)((buf) + (srow + 32 * _it) * KV_STRIDE + piece * 16) = pre[_it]; } while (0)
; __device__ void cross_items(const Params& p, LAS unsigned char* lds) {
;     ...
;         for (int c = 0; c < 4; ++c) {
;             LAS unsigned char* buf = lds + (c & 1) * KV_BUF;
;             XSTORE(buf);
;             if (c < 3) XLOAD(kvb, 5 + c); else XLOAD(nkvb, 0);
;             LDS_BARRIER();
;             f32x4 ot[8];
; #pragma unroll
;             for (int c8 = 0; c8 < 8; ++c8) ot[c8] = (f32x4){0.f, 0.f, 0.f, 0.f};
;             const unsigned bb = lbase + (unsigned)((c & 1) * KV_BUF);
; #pragma unroll
;             for (int sx = 0; sx < 8; ++sx) {
;                 const unsigned aA = bb + (unsigned)((32 * sx + 4 * g + (idx >> 2)) * KV_STRIDE + 8 * (idx & 3));
;                 const unsigned aB = aA + 16u * KV_STRIDE;
;                 bf16x8 vf[4];
;                 tr_frag4(aA, aB, vf);
; #pragma unroll
;                 for (int c8 = 0; c8 < 4; ++c8) ot[c8] = mfma16(vf[c8], pf[sx], ot[c8]);
;                 tr_frag4(aA + 128, aB + 128, vf);
; #pragma unroll
;                 for (int c8 = 0; c8 < 4; ++c8) ot[4 + c8] = mfma16(vf[c8], pf[sx], ot[4 + c8]);
	ds_write_b128 v0, v[164:167]
	s_waitcnt vmcnt(6)
	ds_write_b128 v0, v[168:171] offset:8192
	s_waitcnt vmcnt(5)
	ds_write_b128 v0, v[172:175] offset:16384
	s_waitcnt vmcnt(4)
	ds_write_b128 v0, v[176:179] offset:24576
	s_waitcnt vmcnt(3)
	ds_write_b128 v0, v[180:183] offset:32768
	s_waitcnt vmcnt(2)
	ds_write_b128 v0, v[184:187] offset:40960
	s_waitcnt vmcnt(1)
	ds_write_b128 v0, v[188:191] offset:49152
	s_waitcnt vmcnt(0)
	ds_write_b128 v0, v[192:195] offset:57344
	global_load_dwordx4 v[164:167], v242, s[6:7] offset:256
	v_add_u32_e32 v243, 0x40000, v242
	global_load_dwordx4 v[168:171], v243, s[6:7] offset:256
	v_add_u32_e32 v243, 0x80000, v242
	global_load_dwordx4 v[172:175], v243, s[6:7] offset:256
	v_add_u32_e32 v243, 0xc0000, v242
	global_load_dwordx4 v[176:179], v243, s[6:7] offset:256
	v_add_u32_e32 v243, 0x100000, v242
	global_load_dwordx4 v[180:183], v243, s[6:7] offset:256
	v_add_u32_e32 v243, 0x140000, v242
	global_load_dwordx4 v[184:187], v243, s[6:7] offset:256
	v_add_u32_e32 v243, 0x180000, v242
	global_load_dwordx4 v[188:191], v243, s[6:7] offset:256
	v_add_u32_e32 v243, 0x1c0000, v242
	global_load_dwordx4 v[192:195], v243, s[6:7] offset:256
	s_waitcnt lgkmcnt(0)
	s_barrier
	ds_read_b64_tr_b16 v[72:73], v196
	ds_read_b64_tr_b16 v[80:81], v197
	ds_read_b64_tr_b16 v[74:75], v196 offset:4096
	ds_read_b64_tr_b16 v[82:83], v197 offset:4096
	ds_read_b64_tr_b16 v[88:89], v198
	ds_read_b64_tr_b16 v[96:97], v199
	ds_read_b64_tr_b16 v[90:91], v198 offset:4096
	ds_read_b64_tr_b16 v[98:99], v199 offset:4096
	ds_read_b64_tr_b16 v[104:105], v200
	ds_read_b64_tr_b16 v[112:113], v201
	ds_read_b64_tr_b16 v[106:107], v200 offset:4096
	ds_read_b64_tr_b16 v[114:115], v201 offset:4096
	s_waitcnt lgkmcnt(8)
	ds_read_b64_tr_b16 v[120:121], v202
	ds_read_b64_tr_b16 v[128:129], v203
	ds_read_b64_tr_b16 v[122:123], v202 offset:4096
	ds_read_b64_tr_b16 v[130:131], v203 offset:4096
	v_mfma_f32_16x16x32_bf16 v[132:135], v[72:75], v[4:7], 0
	v_mfma_f32_16x16x32_bf16 v[8:11], v[72:75], v[68:71], 0
	v_mfma_f32_16x16x32_bf16 v[136:139], v[80:83], v[4:7], 0
	v_mfma_f32_16x16x32_bf16 v[16:19], v[80:83], v[68:71], 0
	s_waitcnt lgkmcnt(8)
	ds_read_b64_tr_b16 v[72:73], v196 offset:8192
	ds_read_b64_tr_b16 v[80:81], v197 offset:8192
	ds_read_b64_tr_b16 v[74:75], v196 offset:12288
	ds_read_b64_tr_b16 v[82:83], v197 offset:12288
	v_mfma_f32_16x16x32_bf16 v[140:143], v[88:91], v[4:7], 0
	v_mfma_f32_16x16x32_bf16 v[24:27], v[88:91], v[68:71], 0
	v_mfma_f32_16x16x32_bf16 v[144:147], v[96:99], v[4:7], 0
	v_mfma_f32_16x16x32_bf16 v[32:35], v[96:99], v[68:71], 0
	s_waitcnt lgkmcnt(8)
	ds_read_b64_tr_b16 v[88:89], v198 offset:8192
	ds_read_b64_tr_b16 v[96:97], v199 offset:8192
	ds_read_b64_tr_b16 v[90:91], v198 offset:12288
	ds_read_b64_tr_b16 v[98:99], v199 offset:12288
	v_mfma_f32_16x16x32_bf16 v[148:151], v[104:107], v[4:7], 0
	v_mfma_f32_16x16x32_bf16 v[40:43], v[104:107], v[68:71], 0
	v_mfma_f32_16x16x32_bf16 v[152:155], v[112:115], v[4:7], 0
	v_mfma_f32_16x16x32_bf16 v[48:51], v[112:115], v[68:71], 0
	s_waitcnt lgkmcnt(8)
	ds_read_b64_tr_b16 v[104:105], v200 offset:8192
	ds_read_b64_tr_b16 v[112:113], v201 offset:8192
	ds_read_b64_tr_b16 v[106:107], v200 offset:12288
	ds_read_b64_tr_b16 v[114:115], v201 offset:12288
	v_mfma_f32_16x16x32_bf16 v[156:159], v[120:123], v[4:7], 0
	v_mfma_f32_16x16x32_bf16 v[56:59], v[120:123], v[68:71], 0
	v_mfma_f32_16x16x32_bf16 v[160:163], v[128:131], v[4:7], 0
	v_mfma_f32_16x16x32_bf16 v[64:67], v[128:131], v[68:71], 0
	s_waitcnt lgkmcnt(8)
	ds_read_b64_tr_b16 v[120:121], v202 offset:8192
	ds_read_b64_tr_b16 v[128:129], v203 offset:8192
	ds_read_b64_tr_b16 v[122:123], v202 offset:12288
	ds_read_b64_tr_b16 v[130:131], v203 offset:12288
	v_mfma_f32_16x16x32_bf16 v[132:135], v[72:75], v[12:15], v[132:135]
	v_mfma_f32_16x16x32_bf16 v[8:11], v[72:75], v[76:79], v[8:11]
	v_mfma_f32_16x16x32_bf16 v[136:139], v[80:83], v[12:15], v[136:139]
	v_mfma_f32_16x16x32_bf16 v[16:19], v[80:83], v[76:79], v[16:19]
	s_waitcnt lgkmcnt(8)
	ds_read_b64_tr_b16 v[72:73], v196 offset:16384
	ds_read_b64_tr_b16 v[80:81], v197 offset:16384
	ds_read_b64_tr_b16 v[74:75], v196 offset:20480
	ds_read_b64_tr_b16 v[82:83], v197 offset:20480
	v_mfma_f32_16x16x32_bf16 v[140:143], v[88:91], v[12:15], v[140:143]
	v_mfma_f32_16x16x32_bf16 v[24:27], v[88:91], v[76:79], v[24:27]
	v_mfma_f32_16x16x32_bf16 v[144:147], v[96:99], v[12:15], v[144:147]
	v_mfma_f32_16x16x32_bf16 v[32:35], v[96:99], v[76:79], v[32:35]
	s_waitcnt lgkmcnt(8)
	ds_read_b64_tr_b16 v[88:89], v198 offset:16384
	ds_read_b64_tr_b16 v[96:97], v199 offset:16384
	ds_read_b64_tr_b16 v[90:91], v198 offset:20480
	ds_read_b64_tr_b16 v[98:99], v199 offset:20480
	v_mfma_f32_16x16x32_bf16 v[148:151], v[104:107], v[12:15], v[148:151]
	v_mfma_f32_16x16x32_bf16 v[40:43], v[104:107], v[76:79], v[40:43]
	v_mfma_f32_16x16x32_bf16 v[152:155], v[112:115], v[12:15], v[152:155]
	v_mfma_f32_16x16x32_bf16 v[48:51], v[112:115], v[76:79], v[48:51]
	s_waitcnt lgkmcnt(8)
	ds_read_b64_tr_b16 v[104:105], v200 offset:16384
	ds_read_b64_tr_b16 v[112:113], v201 offset:16384
	ds_read_b64_tr_b16 v[106:107], v200 offset:20480
	ds_read_b64_tr_b16 v[114:115], v201 offset:20480
	v_mfma_f32_16x16x32_bf16 v[156:159], v[120:123], v[12:15], v[156:159]
	v_mfma_f32_16x16x32_bf16 v[56:59], v[120:123], v[76:79], v[56:59]
	v_mfma_f32_16x16x32_bf16 v[160:163], v[128:131], v[12:15], v[160:163]
	v_mfma_f32_16x16x32_bf16 v[64:67], v[128:131], v[76:79], v[64:67]
	s_waitcnt lgkmcnt(8)
; __device__ __forceinline__ f32x4 mfma16(bf16x8 a, bf16x8 b, f32x4 c) { return __builtin_amdgcn_mfma_f32_16x16x32_bf16(a, b, c, 0, 0, 0); }
; __device__ void cross_items(const Params& p, LAS unsigned char* lds) {
;     ...
; #pragma unroll
;             for (int sx = 0; sx < 8; ++sx) {
;                 const unsigned aA = bb + (unsigned)((32 * sx + 4 * g + (idx >> 2)) * KV_STRIDE + 8 * (idx & 3));
;                 const unsigned aB = aA + 16u * KV_STRIDE;
;                 bf16x8 vf[4];
;                 tr_frag4(aA, aB, vf);
; #pragma unroll
;                 for (int c8 = 0; c8 < 4; ++c8) ot[c8] = mfma16(vf[c8], pf[sx], ot[c8]);
;                 tr_frag4(aA + 128, aB + 128, vf);
; #pragma unroll
;                 for (int c8 = 0; c8 < 4; ++c8) ot[4 + c8] = mfma16(vf[c8], pf[sx], ot[4 + c8]);
	ds_read_b64_tr_b16 v[120:121], v202 offset:16384
	ds_read_b64_tr_b16 v[128:129], v203 offset:16384
	ds_read_b64_tr_b16 v[122:123], v202 offset:20480
	ds_read_b64_tr_b16 v[130:131], v203 offset:20480
	v_mfma_f32_16x16x32_bf16 v[132:135], v[72:75], v[20:23], v[132:135]
	v_mfma_f32_16x16x32_bf16 v[8:11], v[72:75], v[84:87], v[8:11]
	v_mfma_f32_16x16x32_bf16 v[136:139], v[80:83], v[20:23], v[136:139]
	v_mfma_f32_16x16x32_bf16 v[16:19], v[80:83], v[84:87], v[16:19]
	s_waitcnt lgkmcnt(8)
	ds_read_b64_tr_b16 v[72:73], v196 offset:24576
	ds_read_b64_tr_b16 v[80:81], v197 offset:24576
	ds_read_b64_tr_b16 v[74:75], v196 offset:28672
	ds_read_b64_tr_b16 v[82:83], v197 offset:28672
	v_mfma_f32_16x16x32_bf16 v[140:143], v[88:91], v[20:23], v[140:143]
	v_mfma_f32_16x16x32_bf16 v[24:27], v[88:91], v[84:87], v[24:27]
	v_mfma_f32_16x16x32_bf16 v[144:147], v[96:99], v[20:23], v[144:147]
	v_mfma_f32_16x16x32_bf16 v[32:35], v[96:99], v[84:87], v[32:35]
	s_waitcnt lgkmcnt(8)
	ds_read_b64_tr_b16 v[88:89], v198 offset:24576
	ds_read_b64_tr_b16 v[96:97], v199 offset:24576
	ds_read_b64_tr_b16 v[90:91], v198 offset:28672
	ds_read_b64_tr_b16 v[98:99], v199 offset:28672
	v_mfma_f32_16x16x32_bf16 v[148:151], v[104:107], v[20:23], v[148:151]
	v_mfma_f32_16x16x32_bf16 v[40:43], v[104:107], v[84:87], v[40:43]
	v_mfma_f32_16x16x32_bf16 v[152:155], v[112:115], v[20:23], v[152:155]
	v_mfma_f32_16x16x32_bf16 v[48:51], v[112:115], v[84:87], v[48:51]
	s_waitcnt lgkmcnt(8)
	ds_read_b64_tr_b16 v[104:105], v200 offset:24576
	ds_read_b64_tr_b16 v[112:113], v201 offset:24576
	ds_read_b64_tr_b16 v[106:107], v200 offset:28672
	ds_read_b64_tr_b16 v[114:115], v201 offset:28672
	v_mfma_f32_16x16x32_bf16 v[156:159], v[120:123], v[20:23], v[156:159]
	v_mfma_f32_16x16x32_bf16 v[56:59], v[120:123], v[84:87], v[56:59]
	v_mfma_f32_16x16x32_bf16 v[160:163], v[128:131], v[20:23], v[160:163]
	v_mfma_f32_16x16x32_bf16 v[64:67], v[128:131], v[84:87], v[64:67]
	s_waitcnt lgkmcnt(8)
	ds_read_b64_tr_b16 v[120:121], v202 offset:24576
	ds_read_b64_tr_b16 v[128:129], v203 offset:24576
	ds_read_b64_tr_b16 v[122:123], v202 offset:28672
	ds_read_b64_tr_b16 v[130:131], v203 offset:28672
	v_mfma_f32_16x16x32_bf16 v[132:135], v[72:75], v[28:31], v[132:135]
	v_mfma_f32_16x16x32_bf16 v[8:11], v[72:75], v[92:95], v[8:11]
	v_mfma_f32_16x16x32_bf16 v[136:139], v[80:83], v[28:31], v[136:139]
	v_mfma_f32_16x16x32_bf16 v[16:19], v[80:83], v[92:95], v[16:19]
	s_waitcnt lgkmcnt(8)
	ds_read_b64_tr_b16 v[72:73], v196 offset:32768
	ds_read_b64_tr_b16 v[80:81], v197 offset:32768
	ds_read_b64_tr_b16 v[74:75], v196 offset:36864
	ds_read_b64_tr_b16 v[82:83], v197 offset:36864
	v_mfma_f32_16x16x32_bf16 v[140:143], v[88:91], v[28:31], v[140:143]
	v_mfma_f32_16x16x32_bf16 v[24:27], v[88:91], v[92:95], v[24:27]
	v_mfma_f32_16x16x32_bf16 v[144:147], v[96:99], v[28:31], v[144:147]
	v_mfma_f32_16x16x32_bf16 v[32:35], v[96:99], v[92:95], v[32:35]
	s_waitcnt lgkmcnt(8)
	ds_read_b64_tr_b16 v[88:89], v198 offset:32768
	ds_read_b64_tr_b16 v[96:97], v199 offset:32768
	ds_read_b64_tr_b16 v[90:91], v198 offset:36864
	ds_read_b64_tr_b16 v[98:99], v199 offset:36864
	v_mfma_f32_16x16x32_bf16 v[148:151], v[104:107], v[28:31], v[148:151]
	v_mfma_f32_16x16x32_bf16 v[40:43], v[104:107], v[92:95], v[40:43]
	v_mfma_f32_16x16x32_bf16 v[152:155], v[112:115], v[28:31], v[152:155]
	v_mfma_f32_16x16x32_bf16 v[48:51], v[112:115], v[92:95], v[48:51]
	s_waitcnt lgkmcnt(8)
	ds_read_b64_tr_b16 v[104:105], v200 offset:32768
	ds_read_b64_tr_b16 v[112:113], v201 offset:32768
	ds_read_b64_tr_b16 v[106:107], v200 offset:36864
	ds_read_b64_tr_b16 v[114:115], v201 offset:36864
	v_mfma_f32_16x16x32_bf16 v[156:159], v[120:123], v[28:31], v[156:159]
	v_mfma_f32_16x16x32_bf16 v[56:59], v[120:123], v[92:95], v[56:59]
	v_mfma_f32_16x16x32_bf16 v[160:163], v[128:131], v[28:31], v[160:163]
	v_mfma_f32_16x16x32_bf16 v[64:67], v[128:131], v[92:95], v[64:67]
	s_waitcnt lgkmcnt(8)
	ds_read_b64_tr_b16 v[120:121], v202 offset:32768
	ds_read_b64_tr_b16 v[128:129], v203 offset:32768
	ds_read_b64_tr_b16 v[122:123], v202 offset:36864
	ds_read_b64_tr_b16 v[130:131], v203 offset:36864
	v_mfma_f32_16x16x32_bf16 v[132:135], v[72:75], v[36:39], v[132:135]
	v_mfma_f32_16x16x32_bf16 v[8:11], v[72:75], v[100:103], v[8:11]
	v_mfma_f32_16x16x32_bf16 v[136:139], v[80:83], v[36:39], v[136:139]
	v_mfma_f32_16x16x32_bf16 v[16:19], v[80:83], v[100:103], v[16:19]
	s_waitcnt lgkmcnt(8)
	ds_read_b64_tr_b16 v[72:73], v196 offset:40960
	ds_read_b64_tr_b16 v[80:81], v197 offset:40960
	ds_read_b64_tr_b16 v[74:75], v196 offset:45056
	ds_read_b64_tr_b16 v[82:83], v197 offset:45056
	v_mfma_f32_16x16x32_bf16 v[140:143], v[88:91], v[36:39], v[140:143]
	v_mfma_f32_16x16x32_bf16 v[24:27], v[88:91], v[100:103], v[24:27]
	v_mfma_f32_16x16x32_bf16 v[144:147], v[96:99], v[36:39], v[144:147]
	v_mfma_f32_16x16x32_bf16 v[32:35], v[96:99], v[100:103], v[32:35]
	s_waitcnt lgkmcnt(8)
	ds_read_b64_tr_b16 v[88:89], v198 offset:40960
	ds_read_b64_tr_b16 v[96:97], v199 offset:40960
	ds_read_b64_tr_b16 v[90:91], v198 offset:45056
	ds_read_b64_tr_b16 v[98:99], v199 offset:45056
	v_mfma_f32_16x16x32_bf16 v[148:151], v[104:107], v[36:39], v[148:151]
	v_mfma_f32_16x16x32_bf16 v[40:43], v[104:107], v[100:103], v[40:43]
	v_mfma_f32_16x16x32_bf16 v[152:155], v[112:115], v[36:39], v[152:155]
	v_mfma_f32_16x16x32_bf16 v[48:51], v[112:115], v[100:103], v[48:51]
	s_waitcnt lgkmcnt(8)
	ds_read_b64_tr_b16 v[104:105], v200 offset:40960
	ds_read_b64_tr_b16 v[112:113], v201 offset:40960
	ds_read_b64_tr_b16 v[106:107], v200 offset:45056
	ds_read_b64_tr_b16 v[114:115], v201 offset:45056
	v_mfma_f32_16x16x32_bf16 v[156:159], v[120:123], v[36:39], v[156:159]
	v_mfma_f32_16x16x32_bf16 v[56:59], v[120:123], v[100:103], v[56:59]
	v_mfma_f32_16x16x32_bf16 v[160:163], v[128:131], v[36:39], v[160:163]
	v_mfma_f32_16x16x32_bf16 v[64:67], v[128:131], v[100:103], v[64:67]
	s_waitcnt lgkmcnt(8)
; __device__ __forceinline__ f32x4 mfma16(bf16x8 a, bf16x8 b, f32x4 c) { return __builtin_amdgcn_mfma_f32_16x16x32_bf16(a, b, c, 0, 0, 0); }
; __device__ __forceinline__ void tr_frag4(unsigned a, unsigned b, bf16x8 (&f)[4]) {
;     s16x4 x0, x1, x2, x3, y0, y1, y2, y3;
;     asm volatile("ds_read_b64_tr_b16 %0, %8\n\tds_read_b64_tr_b16 %1, %8 offset:32\n\tds_read_b64_tr_b16 %2, %8 offset:64\n\tds_read_b64_tr_b16 %3, %8 offset:96\n\t"
;                  "ds_read_b64_tr_b16 %4, %9\n\tds_read_b64_tr_b16 %5, %9 offset:32\n\tds_read_b64_tr_b16 %6, %9 offset:64\n\tds_read_b64_tr_b16 %7, %9 offset:96\n\t"
;                  "s_waitcnt lgkmcnt(0)"
;                  : "=&v"(x0), "=&v"(x1), "=&v"(x2), "=&v"(x3), "=&v"(y0), "=&v"(y1), "=&v"(y2), "=&v"(y3) : "v"(a), "v"(b) : "memory");
; __device__ void cross_items(const Params& p, LAS unsigned char* lds) {
;     ...
; #pragma unroll
;             for (int sx = 0; sx < 8; ++sx) {
;                 const unsigned aA = bb + (unsigned)((32 * sx + 4 * g + (idx >> 2)) * KV_STRIDE + 8 * (idx & 3));
;                 const unsigned aB = aA + 16u * KV_STRIDE;
;                 bf16x8 vf[4];
;                 tr_frag4(aA, aB, vf);
; #pragma unroll
;                 for (int c8 = 0; c8 < 4; ++c8) ot[c8] = mfma16(vf[c8], pf[sx], ot[c8]);
;                 tr_frag4(aA + 128, aB + 128, vf);
; #pragma unroll
;                 for (int c8 = 0; c8 < 4; ++c8) ot[4 + c8] = mfma16(vf[c8], pf[sx], ot[4 + c8]);
;             }
	ds_read_b64_tr_b16 v[120:121], v202 offset:40960
	ds_read_b64_tr_b16 v[128:129], v203 offset:40960
	ds_read_b64_tr_b16 v[122:123], v202 offset:45056
	ds_read_b64_tr_b16 v[130:131], v203 offset:45056
	v_mfma_f32_16x16x32_bf16 v[132:135], v[72:75], v[44:47], v[132:135]
	v_mfma_f32_16x16x32_bf16 v[8:11], v[72:75], v[108:111], v[8:11]
	v_mfma_f32_16x16x32_bf16 v[136:139], v[80:83], v[44:47], v[136:139]
	v_mfma_f32_16x16x32_bf16 v[16:19], v[80:83], v[108:111], v[16:19]
	s_waitcnt lgkmcnt(8)
	ds_read_b64_tr_b16 v[72:73], v196 offset:49152
	ds_read_b64_tr_b16 v[80:81], v197 offset:49152
	ds_read_b64_tr_b16 v[74:75], v196 offset:53248
	ds_read_b64_tr_b16 v[82:83], v197 offset:53248
	v_mfma_f32_16x16x32_bf16 v[140:143], v[88:91], v[44:47], v[140:143]
	v_mfma_f32_16x16x32_bf16 v[24:27], v[88:91], v[108:111], v[24:27]
	v_mfma_f32_16x16x32_bf16 v[144:147], v[96:99], v[44:47], v[144:147]
	v_mfma_f32_16x16x32_bf16 v[32:35], v[96:99], v[108:111], v[32:35]
	s_waitcnt lgkmcnt(8)
	ds_read_b64_tr_b16 v[88:89], v198 offset:49152
	ds_read_b64_tr_b16 v[96:97], v199 offset:49152
	ds_read_b64_tr_b16 v[90:91], v198 offset:53248
	ds_read_b64_tr_b16 v[98:99], v199 offset:53248
	v_mfma_f32_16x16x32_bf16 v[148:151], v[104:107], v[44:47], v[148:151]
	v_mfma_f32_16x16x32_bf16 v[40:43], v[104:107], v[108:111], v[40:43]
	v_mfma_f32_16x16x32_bf16 v[152:155], v[112:115], v[44:47], v[152:155]
	v_mfma_f32_16x16x32_bf16 v[48:51], v[112:115], v[108:111], v[48:51]
	s_waitcnt lgkmcnt(8)
	ds_read_b64_tr_b16 v[104:105], v200 offset:49152
	ds_read_b64_tr_b16 v[112:113], v201 offset:49152
	ds_read_b64_tr_b16 v[106:107], v200 offset:53248
	ds_read_b64_tr_b16 v[114:115], v201 offset:53248
	v_mfma_f32_16x16x32_bf16 v[156:159], v[120:123], v[44:47], v[156:159]
	v_mfma_f32_16x16x32_bf16 v[56:59], v[120:123], v[108:111], v[56:59]
	v_mfma_f32_16x16x32_bf16 v[160:163], v[128:131], v[44:47], v[160:163]
	v_mfma_f32_16x16x32_bf16 v[64:67], v[128:131], v[108:111], v[64:67]
	s_waitcnt lgkmcnt(8)
	ds_read_b64_tr_b16 v[120:121], v202 offset:49152
	ds_read_b64_tr_b16 v[128:129], v203 offset:49152
	ds_read_b64_tr_b16 v[122:123], v202 offset:53248
	ds_read_b64_tr_b16 v[130:131], v203 offset:53248
	v_mfma_f32_16x16x32_bf16 v[132:135], v[72:75], v[52:55], v[132:135]
	v_mfma_f32_16x16x32_bf16 v[8:11], v[72:75], v[116:119], v[8:11]
	v_mfma_f32_16x16x32_bf16 v[136:139], v[80:83], v[52:55], v[136:139]
	v_mfma_f32_16x16x32_bf16 v[16:19], v[80:83], v[116:119], v[16:19]
	s_waitcnt lgkmcnt(8)
	ds_read_b64_tr_b16 v[72:73], v196 offset:57344
	ds_read_b64_tr_b16 v[80:81], v197 offset:57344
	ds_read_b64_tr_b16 v[74:75], v196 offset:61440
	ds_read_b64_tr_b16 v[82:83], v197 offset:61440
	v_mfma_f32_16x16x32_bf16 v[140:143], v[88:91], v[52:55], v[140:143]
	v_mfma_f32_16x16x32_bf16 v[24:27], v[88:91], v[116:119], v[24:27]
	v_mfma_f32_16x16x32_bf16 v[144:147], v[96:99], v[52:55], v[144:147]
	v_mfma_f32_16x16x32_bf16 v[32:35], v[96:99], v[116:119], v[32:35]
	s_waitcnt lgkmcnt(8)
	ds_read_b64_tr_b16 v[88:89], v198 offset:57344
	ds_read_b64_tr_b16 v[96:97], v199 offset:57344
	ds_read_b64_tr_b16 v[90:91], v198 offset:61440
	ds_read_b64_tr_b16 v[98:99], v199 offset:61440
	v_mfma_f32_16x16x32_bf16 v[148:151], v[104:107], v[52:55], v[148:151]
	v_mfma_f32_16x16x32_bf16 v[40:43], v[104:107], v[116:119], v[40:43]
	v_mfma_f32_16x16x32_bf16 v[152:155], v[112:115], v[52:55], v[152:155]
	v_mfma_f32_16x16x32_bf16 v[48:51], v[112:115], v[116:119], v[48:51]
	s_waitcnt lgkmcnt(8)
	ds_read_b64_tr_b16 v[104:105], v200 offset:57344
	ds_read_b64_tr_b16 v[112:113], v201 offset:57344
	ds_read_b64_tr_b16 v[106:107], v200 offset:61440
	ds_read_b64_tr_b16 v[114:115], v201 offset:61440
	v_mfma_f32_16x16x32_bf16 v[156:159], v[120:123], v[52:55], v[156:159]
	v_mfma_f32_16x16x32_bf16 v[56:59], v[120:123], v[116:119], v[56:59]
	v_mfma_f32_16x16x32_bf16 v[160:163], v[128:131], v[52:55], v[160:163]
	v_mfma_f32_16x16x32_bf16 v[64:67], v[128:131], v[116:119], v[64:67]
	s_waitcnt lgkmcnt(8)
	ds_read_b64_tr_b16 v[120:121], v202 offset:57344
	ds_read_b64_tr_b16 v[128:129], v203 offset:57344
	ds_read_b64_tr_b16 v[122:123], v202 offset:61440
	ds_read_b64_tr_b16 v[130:131], v203 offset:61440
	v_mfma_f32_16x16x32_bf16 v[132:135], v[72:75], v[60:63], v[132:135]
	v_mfma_f32_16x16x32_bf16 v[8:11], v[72:75], v[124:127], v[8:11]
	v_mfma_f32_16x16x32_bf16 v[136:139], v[80:83], v[60:63], v[136:139]
	v_mfma_f32_16x16x32_bf16 v[16:19], v[80:83], v[124:127], v[16:19]
	s_waitcnt lgkmcnt(8)
	v_mfma_f32_16x16x32_bf16 v[140:143], v[88:91], v[60:63], v[140:143]
	v_mfma_f32_16x16x32_bf16 v[24:27], v[88:91], v[124:127], v[24:27]
	v_mfma_f32_16x16x32_bf16 v[144:147], v[96:99], v[60:63], v[144:147]
	v_mfma_f32_16x16x32_bf16 v[32:35], v[96:99], v[124:127], v[32:35]
	s_waitcnt lgkmcnt(4)
	v_mfma_f32_16x16x32_bf16 v[148:151], v[104:107], v[60:63], v[148:151]
	v_mfma_f32_16x16x32_bf16 v[40:43], v[104:107], v[124:127], v[40:43]
	v_mfma_f32_16x16x32_bf16 v[152:155], v[112:115], v[60:63], v[152:155]
	v_mfma_f32_16x16x32_bf16 v[48:51], v[112:115], v[124:127], v[48:51]
	s_waitcnt lgkmcnt(0)
; #define LAS __attribute__((address_space(3)))
; __device__ __forceinline__ unsigned cvt_pk_bf16(float lo, float hi) { const f32x2v v = {lo, hi}; const b16x2v r = __builtin_convertvector(v, b16x2v); return __builtin_bit_cast(unsigned, r); }
; __device__ __forceinline__ f32x4 mfma16(bf16x8 a, bf16x8 b, f32x4 c) { return __builtin_amdgcn_mfma_f32_16x16x32_bf16(a, b, c, 0, 0, 0); }
; #define LDS_BARRIER() do { asm volatile("s_waitcnt lgkmcnt(0)" ::: "memory"); __builtin_amdgcn_s_barrier(); asm volatile("" ::: "memory"); } while (0)
; #define XLOAD(kvbase, c8) do { const bf16_t* _src = (kvbase) + (((c8) >= 4) ? 2048 : 0) + ((c8) & 3) * 128 + piece * 8; \
;         _Pragma("unroll") for (int _it = 0; _it < 8; ++_it) pre[_it] = *(const u32x4*)(_src + (size_t)(srow + 32 * _it) * 4096); } while (0)
; #define XSTORE(buf) do { _Pragma("unroll") for (int _it = 0; _it < 8; ++_it) *(LAS u32x4*)((buf) + (srow + 32 * _it) * KV_STRIDE + piece * 16) = pre[_it]; } while (0)
; __device__ void cross_items(const Params& p, LAS unsigned char* lds) {
;     ...
;         for (int c = 0; c < 4; ++c) {
;             LAS unsigned char* buf = lds + (c & 1) * KV_BUF;
;             XSTORE(buf);
;             if (c < 3) XLOAD(kvb, 5 + c); else XLOAD(nkvb, 0);
;             LDS_BARRIER();
;     ...
;                 tr_frag4(aA, aB, vf);
; #pragma unroll
;                 for (int c8 = 0; c8 < 4; ++c8) ot[c8] = mfma16(vf[c8], pf[sx], ot[c8]);
;                 tr_frag4(aA + 128, aB + 128, vf);
; #pragma unroll
;                 for (int c8 = 0; c8 < 4; ++c8) ot[4 + c8] = mfma16(vf[c8], pf[sx], ot[4 + c8]);
;             }
; #pragma unroll
;             for (int c8 = 0; c8 < 8; ++c8) { u32x2 wv; wv.x = cvt_pk_bf16(ot[c8][0] * inv, ot[c8][1] * inv); wv.y = cvt_pk_bf16(ot[c8][2] * inv, ot[c8][3] * inv);
;                 *(u32x2*)(oc + tok * DM + head * 512 + c * 128 + 16 * c8 + 4 * g) = wv; }
	v_mfma_f32_16x16x32_bf16 v[156:159], v[120:123], v[60:63], v[156:159]
	v_mfma_f32_16x16x32_bf16 v[56:59], v[120:123], v[124:127], v[56:59]
	v_mfma_f32_16x16x32_bf16 v[160:163], v[128:131], v[60:63], v[160:163]
	v_mfma_f32_16x16x32_bf16 v[64:67], v[128:131], v[124:127], v[64:67]
	s_nop 7
	s_nop 7
	v_mul_f32_e32 v230, v244, v132
	v_mul_f32_e32 v231, v244, v133
	v_mul_f32_e32 v232, v244, v134
	v_mul_f32_e32 v233, v244, v135
	v_cvt_pk_bf16_f32 v230, v230, v231
	v_cvt_pk_bf16_f32 v231, v232, v233
	global_store_dwordx2 v248, v[230:231], s[92:93] offset:0
	v_mul_f32_e32 v234, v244, v136
	v_mul_f32_e32 v235, v244, v137
	v_mul_f32_e32 v236, v244, v138
	v_mul_f32_e32 v237, v244, v139
	v_cvt_pk_bf16_f32 v234, v234, v235
	v_cvt_pk_bf16_f32 v235, v236, v237
	global_store_dwordx2 v248, v[234:235], s[92:93] offset:32
	v_mul_f32_e32 v230, v244, v140
	v_mul_f32_e32 v231, v244, v141
	v_mul_f32_e32 v232, v244, v142
	v_mul_f32_e32 v233, v244, v143
	v_cvt_pk_bf16_f32 v230, v230, v231
	v_cvt_pk_bf16_f32 v231, v232, v233
	global_store_dwordx2 v248, v[230:231], s[92:93] offset:64
	v_mul_f32_e32 v234, v244, v144
	v_mul_f32_e32 v235, v244, v145
	v_mul_f32_e32 v236, v244, v146
	v_mul_f32_e32 v237, v244, v147
	v_cvt_pk_bf16_f32 v234, v234, v235
	v_cvt_pk_bf16_f32 v235, v236, v237
	global_store_dwordx2 v248, v[234:235], s[92:93] offset:96
	v_mul_f32_e32 v230, v244, v148
	v_mul_f32_e32 v231, v244, v149
	v_mul_f32_e32 v232, v244, v150
	v_mul_f32_e32 v233, v244, v151
	v_cvt_pk_bf16_f32 v230, v230, v231
	v_cvt_pk_bf16_f32 v231, v232, v233
	global_store_dwordx2 v248, v[230:231], s[92:93] offset:128
	v_mul_f32_e32 v234, v244, v152
	v_mul_f32_e32 v235, v244, v153
	v_mul_f32_e32 v236, v244, v154
	v_mul_f32_e32 v237, v244, v155
	v_cvt_pk_bf16_f32 v234, v234, v235
	v_cvt_pk_bf16_f32 v235, v236, v237
	global_store_dwordx2 v248, v[234:235], s[92:93] offset:160
	v_mul_f32_e32 v230, v244, v156
	v_mul_f32_e32 v231, v244, v157
	v_mul_f32_e32 v232, v244, v158
	v_mul_f32_e32 v233, v244, v159
	v_cvt_pk_bf16_f32 v230, v230, v231
	v_cvt_pk_bf16_f32 v231, v232, v233
	global_store_dwordx2 v248, v[230:231], s[92:93] offset:192
	v_mul_f32_e32 v234, v244, v160
	v_mul_f32_e32 v235, v244, v161
	v_mul_f32_e32 v236, v244, v162
	v_mul_f32_e32 v237, v244, v163
	v_cvt_pk_bf16_f32 v234, v234, v235
	v_cvt_pk_bf16_f32 v235, v236, v237
	global_store_dwordx2 v248, v[234:235], s[92:93] offset:224
	v_mul_f32_e32 v230, v245, v8
	v_mul_f32_e32 v231, v245, v9
	v_mul_f32_e32 v232, v245, v10
	v_mul_f32_e32 v233, v245, v11
	v_cvt_pk_bf16_f32 v230, v230, v231
	v_cvt_pk_bf16_f32 v231, v232, v233
	global_store_dwordx2 v249, v[230:231], s[92:93] offset:0
	v_mul_f32_e32 v234, v245, v16
	v_mul_f32_e32 v235, v245, v17
	v_mul_f32_e32 v236, v245, v18
	v_mul_f32_e32 v237, v245, v19
	v_cvt_pk_bf16_f32 v234, v234, v235
	v_cvt_pk_bf16_f32 v235, v236, v237
	global_store_dwordx2 v249, v[234:235], s[92:93] offset:32
	v_mul_f32_e32 v230, v245, v24
	v_mul_f32_e32 v231, v245, v25
	v_mul_f32_e32 v232, v245, v26
	v_mul_f32_e32 v233, v245, v27
	v_cvt_pk_bf16_f32 v230, v230, v231
	v_cvt_pk_bf16_f32 v231, v232, v233
	global_store_dwordx2 v249, v[230:231], s[92:93] offset:64
	v_mul_f32_e32 v234, v245, v32
	v_mul_f32_e32 v235, v245, v33
	v_mul_f32_e32 v236, v245, v34
	v_mul_f32_e32 v237, v245, v35
	v_cvt_pk_bf16_f32 v234, v234, v235
	v_cvt_pk_bf16_f32 v235, v236, v237
	global_store_dwordx2 v249, v[234:235], s[92:93] offset:96
	v_mul_f32_e32 v230, v245, v40
	v_mul_f32_e32 v231, v245, v41
	v_mul_f32_e32 v232, v245, v42
	v_mul_f32_e32 v233, v245, v43
	v_cvt_pk_bf16_f32 v230, v230, v231
	v_cvt_pk_bf16_f32 v231, v232, v233
	global_store_dwordx2 v249, v[230:231], s[92:93] offset:128
	v_mul_f32_e32 v234, v245, v48
	v_mul_f32_e32 v235, v245, v49
	v_mul_f32_e32 v236, v245, v50
	v_mul_f32_e32 v237, v245, v51
	v_cvt_pk_bf16_f32 v234, v234, v235
	v_cvt_pk_bf16_f32 v235, v236, v237
	global_store_dwordx2 v249, v[234:235], s[92:93] offset:160
	v_mul_f32_e32 v230, v245, v56
	v_mul_f32_e32 v231, v245, v57
	v_mul_f32_e32 v232, v245, v58
	v_mul_f32_e32 v233, v245, v59
	v_cvt_pk_bf16_f32 v230, v230, v231
	v_cvt_pk_bf16_f32 v231, v232, v233
	global_store_dwordx2 v249, v[230:231], s[92:93] offset:192
	v_mul_f32_e32 v234, v245, v64
	v_mul_f32_e32 v235, v245, v65
	v_mul_f32_e32 v236, v245, v66
	v_mul_f32_e32 v237, v245, v67
	v_cvt_pk_bf16_f32 v234, v234, v235
	v_cvt_pk_bf16_f32 v235, v236, v237
	global_store_dwordx2 v249, v[234:235], s[92:93] offset:224
	v_xor_b32_e32 v196, 0x10000, v196
	v_xor_b32_e32 v197, 0x10000, v197
	v_xor_b32_e32 v198, 0x10000, v198
	v_xor_b32_e32 v199, 0x10000, v199
	v_xor_b32_e32 v200, 0x10000, v200
	v_xor_b32_e32 v201, 0x10000, v201
	v_xor_b32_e32 v202, 0x10000, v202
	v_xor_b32_e32 v203, 0x10000, v203
	s_waitcnt vmcnt(23)
	ds_write_b128 v1, v[164:167]
	s_waitcnt vmcnt(22)
	ds_write_b128 v1, v[168:171] offset:8192
	s_waitcnt vmcnt(21)
	ds_write_b128 v1, v[172:175] offset:16384
	s_waitcnt vmcnt(20)
	ds_write_b128 v1, v[176:179] offset:24576
	s_waitcnt vmcnt(19)
	ds_write_b128 v1, v[180:183] offset:32768
	s_waitcnt vmcnt(18)
	ds_write_b128 v1, v[184:187] offset:40960
	s_waitcnt vmcnt(17)
	ds_write_b128 v1, v[188:191] offset:49152
	s_waitcnt vmcnt(16)
	ds_write_b128 v1, v[192:195] offset:57344
	global_load_dwordx4 v[164:167], v242, s[6:7] offset:512
	v_add_u32_e32 v243, 0x40000, v242
	global_load_dwordx4 v[168:171], v243, s[6:7] offset:512
	v_add_u32_e32 v243, 0x80000, v242
	global_load_dwordx4 v[172:175], v243, s[6:7] offset:512
	v_add_u32_e32 v243, 0xc0000, v242
	global_load_dwordx4 v[176:179], v243, s[6:7] offset:512
	v_add_u32_e32 v243, 0x100000, v242
	global_load_dwordx4 v[180:183], v243, s[6:7] offset:512
	v_add_u32_e32 v243, 0x140000, v242
	global_load_dwordx4 v[184:187], v243, s[6:7] offset:512
	v_add_u32_e32 v243, 0x180000, v242
	global_load_dwordx4 v[188:191], v243, s[6:7] offset:512
	v_add_u32_e32 v243, 0x1c0000, v242
	global_load_dwordx4 v[192:195], v243, s[6:7] offset:512
	s_waitcnt lgkmcnt(0)
	s_barrier
; __device__ __forceinline__ f32x4 mfma16(bf16x8 a, bf16x8 b, f32x4 c) { return __builtin_amdgcn_mfma_f32_16x16x32_bf16(a, b, c, 0, 0, 0); }
; __device__ __forceinline__ void tr_frag4(unsigned a, unsigned b, bf16x8 (&f)[4]) {
;     s16x4 x0, x1, x2, x3, y0, y1, y2, y3;
;     asm volatile("ds_read_b64_tr_b16 %0, %8\n\tds_read_b64_tr_b16 %1, %8 offset:32\n\tds_read_b64_tr_b16 %2, %8 offset:64\n\tds_read_b64_tr_b16 %3, %8 offset:96\n\t"
;                  "ds_read_b64_tr_b16 %4, %9\n\tds_read_b64_tr_b16 %5, %9 offset:32\n\tds_read_b64_tr_b16 %6, %9 offset:64\n\tds_read_b64_tr_b16 %7, %9 offset:96\n\t"
;                  "s_waitcnt lgkmcnt(0)"
;                  : "=&v"(x0), "=&v"(x1), "=&v"(x2), "=&v"(x3), "=&v"(y0), "=&v"(y1), "=&v"(y2), "=&v"(y3) : "v"(a), "v"(b) : "memory");
; __device__ void cross_items(const Params& p, LAS unsigned char* lds) {
;     ...
;             const unsigned bb = lbase + (unsigned)((c & 1) * KV_BUF);
; #pragma unroll
;             for (int sx = 0; sx < 8; ++sx) {
;                 const unsigned aA = bb + (unsigned)((32 * sx + 4 * g + (idx >> 2)) * KV_STRIDE + 8 * (idx & 3));
;                 const unsigned aB = aA + 16u * KV_STRIDE;
;                 bf16x8 vf[4];
;                 tr_frag4(aA, aB, vf);
; #pragma unroll
;                 for (int c8 = 0; c8 < 4; ++c8) ot[c8] = mfma16(vf[c8], pf[sx], ot[c8]);
;                 tr_frag4(aA + 128, aB + 128, vf);
; #pragma unroll
;                 for (int c8 = 0; c8 < 4; ++c8) ot[4 + c8] = mfma16(vf[c8], pf[sx], ot[4 + c8]);
;             }
	ds_read_b64_tr_b16 v[72:73], v196
	ds_read_b64_tr_b16 v[80:81], v197
	ds_read_b64_tr_b16 v[74:75], v196 offset:4096
	ds_read_b64_tr_b16 v[82:83], v197 offset:4096
	ds_read_b64_tr_b16 v[88:89], v198
	ds_read_b64_tr_b16 v[96:97], v199
	ds_read_b64_tr_b16 v[90:91], v198 offset:4096
	ds_read_b64_tr_b16 v[98:99], v199 offset:4096
	ds_read_b64_tr_b16 v[104:105], v200
	ds_read_b64_tr_b16 v[112:113], v201
	ds_read_b64_tr_b16 v[106:107], v200 offset:4096
	ds_read_b64_tr_b16 v[114:115], v201 offset:4096
	s_waitcnt lgkmcnt(8)
	ds_read_b64_tr_b16 v[120:121], v202
	ds_read_b64_tr_b16 v[128:129], v203
	ds_read_b64_tr_b16 v[122:123], v202 offset:4096
	ds_read_b64_tr_b16 v[130:131], v203 offset:4096
	v_mfma_f32_16x16x32_bf16 v[132:135], v[72:75], v[4:7], 0
	v_mfma_f32_16x16x32_bf16 v[8:11], v[72:75], v[68:71], 0
	v_mfma_f32_16x16x32_bf16 v[136:139], v[80:83], v[4:7], 0
	v_mfma_f32_16x16x32_bf16 v[16:19], v[80:83], v[68:71], 0
	s_waitcnt lgkmcnt(8)
	ds_read_b64_tr_b16 v[72:73], v196 offset:8192
	ds_read_b64_tr_b16 v[80:81], v197 offset:8192
	ds_read_b64_tr_b16 v[74:75], v196 offset:12288
	ds_read_b64_tr_b16 v[82:83], v197 offset:12288
	v_mfma_f32_16x16x32_bf16 v[140:143], v[88:91], v[4:7], 0
	v_mfma_f32_16x16x32_bf16 v[24:27], v[88:91], v[68:71], 0
	v_mfma_f32_16x16x32_bf16 v[144:147], v[96:99], v[4:7], 0
	v_mfma_f32_16x16x32_bf16 v[32:35], v[96:99], v[68:71], 0
	s_waitcnt lgkmcnt(8)
	ds_read_b64_tr_b16 v[88:89], v198 offset:8192
	ds_read_b64_tr_b16 v[96:97], v199 offset:8192
	ds_read_b64_tr_b16 v[90:91], v198 offset:12288
	ds_read_b64_tr_b16 v[98:99], v199 offset:12288
	v_mfma_f32_16x16x32_bf16 v[148:151], v[104:107], v[4:7], 0
	v_mfma_f32_16x16x32_bf16 v[40:43], v[104:107], v[68:71], 0
	v_mfma_f32_16x16x32_bf16 v[152:155], v[112:115], v[4:7], 0
	v_mfma_f32_16x16x32_bf16 v[48:51], v[112:115], v[68:71], 0
	s_waitcnt lgkmcnt(8)
	ds_read_b64_tr_b16 v[104:105], v200 offset:8192
	ds_read_b64_tr_b16 v[112:113], v201 offset:8192
	ds_read_b64_tr_b16 v[106:107], v200 offset:12288
	ds_read_b64_tr_b16 v[114:115], v201 offset:12288
	v_mfma_f32_16x16x32_bf16 v[156:159], v[120:123], v[4:7], 0
	v_mfma_f32_16x16x32_bf16 v[56:59], v[120:123], v[68:71], 0
	v_mfma_f32_16x16x32_bf16 v[160:163], v[128:131], v[4:7], 0
	v_mfma_f32_16x16x32_bf16 v[64:67], v[128:131], v[68:71], 0
	s_waitcnt lgkmcnt(8)
	ds_read_b64_tr_b16 v[120:121], v202 offset:8192
	ds_read_b64_tr_b16 v[128:129], v203 offset:8192
	ds_read_b64_tr_b16 v[122:123], v202 offset:12288
	ds_read_b64_tr_b16 v[130:131], v203 offset:12288
	v_mfma_f32_16x16x32_bf16 v[132:135], v[72:75], v[12:15], v[132:135]
	v_mfma_f32_16x16x32_bf16 v[8:11], v[72:75], v[76:79], v[8:11]
	v_mfma_f32_16x16x32_bf16 v[136:139], v[80:83], v[12:15], v[136:139]
	v_mfma_f32_16x16x32_bf16 v[16:19], v[80:83], v[76:79], v[16:19]
	s_waitcnt lgkmcnt(8)
	ds_read_b64_tr_b16 v[72:73], v196 offset:16384
	ds_read_b64_tr_b16 v[80:81], v197 offset:16384
	ds_read_b64_tr_b16 v[74:75], v196 offset:20480
	ds_read_b64_tr_b16 v[82:83], v197 offset:20480
	v_mfma_f32_16x16x32_bf16 v[140:143], v[88:91], v[12:15], v[140:143]
	v_mfma_f32_16x16x32_bf16 v[24:27], v[88:91], v[76:79], v[24:27]
	v_mfma_f32_16x16x32_bf16 v[144:147], v[96:99], v[12:15], v[144:147]
	v_mfma_f32_16x16x32_bf16 v[32:35], v[96:99], v[76:79], v[32:35]
	s_waitcnt lgkmcnt(8)
	ds_read_b64_tr_b16 v[88:89], v198 offset:16384
	ds_read_b64_tr_b16 v[96:97], v199 offset:16384
	ds_read_b64_tr_b16 v[90:91], v198 offset:20480
	ds_read_b64_tr_b16 v[98:99], v199 offset:20480
	v_mfma_f32_16x16x32_bf16 v[148:151], v[104:107], v[12:15], v[148:151]
	v_mfma_f32_16x16x32_bf16 v[40:43], v[104:107], v[76:79], v[40:43]
	v_mfma_f32_16x16x32_bf16 v[152:155], v[112:115], v[12:15], v[152:155]
	v_mfma_f32_16x16x32_bf16 v[48:51], v[112:115], v[76:79], v[48:51]
	s_waitcnt lgkmcnt(8)
	ds_read_b64_tr_b16 v[104:105], v200 offset:16384
	ds_read_b64_tr_b16 v[112:113], v201 offset:16384
	ds_read_b64_tr_b16 v[106:107], v200 offset:20480
	ds_read_b64_tr_b16 v[114:115], v201 offset:20480
	v_mfma_f32_16x16x32_bf16 v[156:159], v[120:123], v[12:15], v[156:159]
	v_mfma_f32_16x16x32_bf16 v[56:59], v[120:123], v[76:79], v[56:59]
	v_mfma_f32_16x16x32_bf16 v[160:163], v[128:131], v[12:15], v[160:163]
	v_mfma_f32_16x16x32_bf16 v[64:67], v[128:131], v[76:79], v[64:67]
	s_waitcnt lgkmcnt(8)
	ds_read_b64_tr_b16 v[120:121], v202 offset:16384
	ds_read_b64_tr_b16 v[128:129], v203 offset:16384
	ds_read_b64_tr_b16 v[122:123], v202 offset:20480
	ds_read_b64_tr_b16 v[130:131], v203 offset:20480
	v_mfma_f32_16x16x32_bf16 v[132:135], v[72:75], v[20:23], v[132:135]
	v_mfma_f32_16x16x32_bf16 v[8:11], v[72:75], v[84:87], v[8:11]
	v_mfma_f32_16x16x32_bf16 v[136:139], v[80:83], v[20:23], v[136:139]
	v_mfma_f32_16x16x32_bf16 v[16:19], v[80:83], v[84:87], v[16:19]
	s_waitcnt lgkmcnt(8)
	ds_read_b64_tr_b16 v[72:73], v196 offset:24576
	ds_read_b64_tr_b16 v[80:81], v197 offset:24576
	ds_read_b64_tr_b16 v[74:75], v196 offset:28672
	ds_read_b64_tr_b16 v[82:83], v197 offset:28672
	v_mfma_f32_16x16x32_bf16 v[140:143], v[88:91], v[20:23], v[140:143]
	v_mfma_f32_16x16x32_bf16 v[24:27], v[88:91], v[84:87], v[24:27]
	v_mfma_f32_16x16x32_bf16 v[144:147], v[96:99], v[20:23], v[144:147]
	v_mfma_f32_16x16x32_bf16 v[32:35], v[96:99], v[84:87], v[32:35]
	s_waitcnt lgkmcnt(8)
	ds_read_b64_tr_b16 v[88:89], v198 offset:24576
	ds_read_b64_tr_b16 v[96:97], v199 offset:24576
	ds_read_b64_tr_b16 v[90:91], v198 offset:28672
	ds_read_b64_tr_b16 v[98:99], v199 offset:28672
	v_mfma_f32_16x16x32_bf16 v[148:151], v[104:107], v[20:23], v[148:151]
	v_mfma_f32_16x16x32_bf16 v[40:43], v[104:107], v[84:87], v[40:43]
	v_mfma_f32_16x16x32_bf16 v[152:155], v[112:115], v[20:23], v[152:155]
	v_mfma_f32_16x16x32_bf16 v[48:51], v[112:115], v[84:87], v[48:51]
	s_waitcnt lgkmcnt(8)
; __device__ __forceinline__ f32x4 mfma16(bf16x8 a, bf16x8 b, f32x4 c) { return __builtin_amdgcn_mfma_f32_16x16x32_bf16(a, b, c, 0, 0, 0); }
; __device__ void cross_items(const Params& p, LAS unsigned char* lds) {
;     ...
; #pragma unroll
;             for (int sx = 0; sx < 8; ++sx) {
;                 const unsigned aA = bb + (unsigned)((32 * sx + 4 * g + (idx >> 2)) * KV_STRIDE + 8 * (idx & 3));
;                 const unsigned aB = aA + 16u * KV_STRIDE;
;                 bf16x8 vf[4];
;                 tr_frag4(aA, aB, vf);
; #pragma unroll
;                 for (int c8 = 0; c8 < 4; ++c8) ot[c8] = mfma16(vf[c8], pf[sx], ot[c8]);
;                 tr_frag4(aA + 128, aB + 128, vf);
; #pragma unroll
;                 for (int c8 = 0; c8 < 4; ++c8) ot[4 + c8] = mfma16(vf[c8], pf[sx], ot[4 + c8]);
;             }
	ds_read_b64_tr_b16 v[104:105], v200 offset:24576
	ds_read_b64_tr_b16 v[112:113], v201 offset:24576
	ds_read_b64_tr_b16 v[106:107], v200 offset:28672
	ds_read_b64_tr_b16 v[114:115], v201 offset:28672
	v_mfma_f32_16x16x32_bf16 v[156:159], v[120:123], v[20:23], v[156:159]
	v_mfma_f32_16x16x32_bf16 v[56:59], v[120:123], v[84:87], v[56:59]
	v_mfma_f32_16x16x32_bf16 v[160:163], v[128:131], v[20:23], v[160:163]
	v_mfma_f32_16x16x32_bf16 v[64:67], v[128:131], v[84:87], v[64:67]
	s_waitcnt lgkmcnt(8)
	ds_read_b64_tr_b16 v[120:121], v202 offset:24576
	ds_read_b64_tr_b16 v[128:129], v203 offset:24576
	ds_read_b64_tr_b16 v[122:123], v202 offset:28672
	ds_read_b64_tr_b16 v[130:131], v203 offset:28672
	v_mfma_f32_16x16x32_bf16 v[132:135], v[72:75], v[28:31], v[132:135]
	v_mfma_f32_16x16x32_bf16 v[8:11], v[72:75], v[92:95], v[8:11]
	v_mfma_f32_16x16x32_bf16 v[136:139], v[80:83], v[28:31], v[136:139]
	v_mfma_f32_16x16x32_bf16 v[16:19], v[80:83], v[92:95], v[16:19]
	s_waitcnt lgkmcnt(8)
	ds_read_b64_tr_b16 v[72:73], v196 offset:32768
	ds_read_b64_tr_b16 v[80:81], v197 offset:32768
	ds_read_b64_tr_b16 v[74:75], v196 offset:36864
	ds_read_b64_tr_b16 v[82:83], v197 offset:36864
	v_mfma_f32_16x16x32_bf16 v[140:143], v[88:91], v[28:31], v[140:143]
	v_mfma_f32_16x16x32_bf16 v[24:27], v[88:91], v[92:95], v[24:27]
	v_mfma_f32_16x16x32_bf16 v[144:147], v[96:99], v[28:31], v[144:147]
	v_mfma_f32_16x16x32_bf16 v[32:35], v[96:99], v[92:95], v[32:35]
	s_waitcnt lgkmcnt(8)
	ds_read_b64_tr_b16 v[88:89], v198 offset:32768
	ds_read_b64_tr_b16 v[96:97], v199 offset:32768
	ds_read_b64_tr_b16 v[90:91], v198 offset:36864
	ds_read_b64_tr_b16 v[98:99], v199 offset:36864
	v_mfma_f32_16x16x32_bf16 v[148:151], v[104:107], v[28:31], v[148:151]
	v_mfma_f32_16x16x32_bf16 v[40:43], v[104:107], v[92:95], v[40:43]
	v_mfma_f32_16x16x32_bf16 v[152:155], v[112:115], v[28:31], v[152:155]
	v_mfma_f32_16x16x32_bf16 v[48:51], v[112:115], v[92:95], v[48:51]
	s_waitcnt lgkmcnt(8)
	ds_read_b64_tr_b16 v[104:105], v200 offset:32768
	ds_read_b64_tr_b16 v[112:113], v201 offset:32768
	ds_read_b64_tr_b16 v[106:107], v200 offset:36864
	ds_read_b64_tr_b16 v[114:115], v201 offset:36864
	v_mfma_f32_16x16x32_bf16 v[156:159], v[120:123], v[28:31], v[156:159]
	v_mfma_f32_16x16x32_bf16 v[56:59], v[120:123], v[92:95], v[56:59]
	v_mfma_f32_16x16x32_bf16 v[160:163], v[128:131], v[28:31], v[160:163]
	v_mfma_f32_16x16x32_bf16 v[64:67], v[128:131], v[92:95], v[64:67]
	s_waitcnt lgkmcnt(8)
	ds_read_b64_tr_b16 v[120:121], v202 offset:32768
	ds_read_b64_tr_b16 v[128:129], v203 offset:32768
	ds_read_b64_tr_b16 v[122:123], v202 offset:36864
	ds_read_b64_tr_b16 v[130:131], v203 offset:36864
	v_mfma_f32_16x16x32_bf16 v[132:135], v[72:75], v[36:39], v[132:135]
	v_mfma_f32_16x16x32_bf16 v[8:11], v[72:75], v[100:103], v[8:11]
	v_mfma_f32_16x16x32_bf16 v[136:139], v[80:83], v[36:39], v[136:139]
	v_mfma_f32_16x16x32_bf16 v[16:19], v[80:83], v[100:103], v[16:19]
	s_waitcnt lgkmcnt(8)
	ds_read_b64_tr_b16 v[72:73], v196 offset:40960
	ds_read_b64_tr_b16 v[80:81], v197 offset:40960
	ds_read_b64_tr_b16 v[74:75], v196 offset:45056
	ds_read_b64_tr_b16 v[82:83], v197 offset:45056
	v_mfma_f32_16x16x32_bf16 v[140:143], v[88:91], v[36:39], v[140:143]
	v_mfma_f32_16x16x32_bf16 v[24:27], v[88:91], v[100:103], v[24:27]
	v_mfma_f32_16x16x32_bf16 v[144:147], v[96:99], v[36:39], v[144:147]
	v_mfma_f32_16x16x32_bf16 v[32:35], v[96:99], v[100:103], v[32:35]
	s_waitcnt lgkmcnt(8)
	ds_read_b64_tr_b16 v[88:89], v198 offset:40960
	ds_read_b64_tr_b16 v[96:97], v199 offset:40960
	ds_read_b64_tr_b16 v[90:91], v198 offset:45056
	ds_read_b64_tr_b16 v[98:99], v199 offset:45056
	v_mfma_f32_16x16x32_bf16 v[148:151], v[104:107], v[36:39], v[148:151]
	v_mfma_f32_16x16x32_bf16 v[40:43], v[104:107], v[100:103], v[40:43]
	v_mfma_f32_16x16x32_bf16 v[152:155], v[112:115], v[36:39], v[152:155]
	v_mfma_f32_16x16x32_bf16 v[48:51], v[112:115], v[100:103], v[48:51]
	s_waitcnt lgkmcnt(8)
	ds_read_b64_tr_b16 v[104:105], v200 offset:40960
	ds_read_b64_tr_b16 v[112:113], v201 offset:40960
	ds_read_b64_tr_b16 v[106:107], v200 offset:45056
	ds_read_b64_tr_b16 v[114:115], v201 offset:45056
	v_mfma_f32_16x16x32_bf16 v[156:159], v[120:123], v[36:39], v[156:159]
	v_mfma_f32_16x16x32_bf16 v[56:59], v[120:123], v[100:103], v[56:59]
	v_mfma_f32_16x16x32_bf16 v[160:163], v[128:131], v[36:39], v[160:163]
	v_mfma_f32_16x16x32_bf16 v[64:67], v[128:131], v[100:103], v[64:67]
	s_waitcnt lgkmcnt(8)
	ds_read_b64_tr_b16 v[120:121], v202 offset:40960
	ds_read_b64_tr_b16 v[128:129], v203 offset:40960
	ds_read_b64_tr_b16 v[122:123], v202 offset:45056
	ds_read_b64_tr_b16 v[130:131], v203 offset:45056
	v_mfma_f32_16x16x32_bf16 v[132:135], v[72:75], v[44:47], v[132:135]
	v_mfma_f32_16x16x32_bf16 v[8:11], v[72:75], v[108:111], v[8:11]
	v_mfma_f32_16x16x32_bf16 v[136:139], v[80:83], v[44:47], v[136:139]
	v_mfma_f32_16x16x32_bf16 v[16:19], v[80:83], v[108:111], v[16:19]
	s_waitcnt lgkmcnt(8)
	ds_read_b64_tr_b16 v[72:73], v196 offset:49152
	ds_read_b64_tr_b16 v[80:81], v197 offset:49152
	ds_read_b64_tr_b16 v[74:75], v196 offset:53248
	ds_read_b64_tr_b16 v[82:83], v197 offset:53248
	v_mfma_f32_16x16x32_bf16 v[140:143], v[88:91], v[44:47], v[140:143]
	v_mfma_f32_16x16x32_bf16 v[24:27], v[88:91], v[108:111], v[24:27]
	v_mfma_f32_16x16x32_bf16 v[144:147], v[96:99], v[44:47], v[144:147]
	v_mfma_f32_16x16x32_bf16 v[32:35], v[96:99], v[108:111], v[32:35]
	s_waitcnt lgkmcnt(8)
; __device__ __forceinline__ unsigned cvt_pk_bf16(float lo, float hi) { const f32x2v v = {lo, hi}; const b16x2v r = __builtin_convertvector(v, b16x2v); return __builtin_bit_cast(unsigned, r); }
; __device__ __forceinline__ f32x4 mfma16(bf16x8 a, bf16x8 b, f32x4 c) { return __builtin_amdgcn_mfma_f32_16x16x32_bf16(a, b, c, 0, 0, 0); }
; __device__ void cross_items(const Params& p, LAS unsigned char* lds) {
;     ...
;                 tr_frag4(aA, aB, vf);
; #pragma unroll
;                 for (int c8 = 0; c8 < 4; ++c8) ot[c8] = mfma16(vf[c8], pf[sx], ot[c8]);
;                 tr_frag4(aA + 128, aB + 128, vf);
; #pragma unroll
;                 for (int c8 = 0; c8 < 4; ++c8) ot[4 + c8] = mfma16(vf[c8], pf[sx], ot[4 + c8]);
;             }
; #pragma unroll
;             for (int c8 = 0; c8 < 8; ++c8) { u32x2 wv; wv.x = cvt_pk_bf16(ot[c8][0] * inv, ot[c8][1] * inv); wv.y = cvt_pk_bf16(ot[c8][2] * inv, ot[c8][3] * inv);
;                 *(u32x2*)(oc + tok * DM + head * 512 + c * 128 + 16 * c8 + 4 * g) = wv; }
	ds_read_b64_tr_b16 v[88:89], v198 offset:49152
	ds_read_b64_tr_b16 v[96:97], v199 offset:49152
	ds_read_b64_tr_b16 v[90:91], v198 offset:53248
	ds_read_b64_tr_b16 v[98:99], v199 offset:53248
	v_mfma_f32_16x16x32_bf16 v[148:151], v[104:107], v[44:47], v[148:151]
	v_mfma_f32_16x16x32_bf16 v[40:43], v[104:107], v[108:111], v[40:43]
	v_mfma_f32_16x16x32_bf16 v[152:155], v[112:115], v[44:47], v[152:155]
	v_mfma_f32_16x16x32_bf16 v[48:51], v[112:115], v[108:111], v[48:51]
	s_waitcnt lgkmcnt(8)
	ds_read_b64_tr_b16 v[104:105], v200 offset:49152
	ds_read_b64_tr_b16 v[112:113], v201 offset:49152
	ds_read_b64_tr_b16 v[106:107], v200 offset:53248
	ds_read_b64_tr_b16 v[114:115], v201 offset:53248
	v_mfma_f32_16x16x32_bf16 v[156:159], v[120:123], v[44:47], v[156:159]
	v_mfma_f32_16x16x32_bf16 v[56:59], v[120:123], v[108:111], v[56:59]
	v_mfma_f32_16x16x32_bf16 v[160:163], v[128:131], v[44:47], v[160:163]
	v_mfma_f32_16x16x32_bf16 v[64:67], v[128:131], v[108:111], v[64:67]
	s_waitcnt lgkmcnt(8)
	ds_read_b64_tr_b16 v[120:121], v202 offset:49152
	ds_read_b64_tr_b16 v[128:129], v203 offset:49152
	ds_read_b64_tr_b16 v[122:123], v202 offset:53248
	ds_read_b64_tr_b16 v[130:131], v203 offset:53248
	v_mfma_f32_16x16x32_bf16 v[132:135], v[72:75], v[52:55], v[132:135]
	v_mfma_f32_16x16x32_bf16 v[8:11], v[72:75], v[116:119], v[8:11]
	v_mfma_f32_16x16x32_bf16 v[136:139], v[80:83], v[52:55], v[136:139]
	v_mfma_f32_16x16x32_bf16 v[16:19], v[80:83], v[116:119], v[16:19]
	s_waitcnt lgkmcnt(8)
	ds_read_b64_tr_b16 v[72:73], v196 offset:57344
	ds_read_b64_tr_b16 v[80:81], v197 offset:57344
	ds_read_b64_tr_b16 v[74:75], v196 offset:61440
	ds_read_b64_tr_b16 v[82:83], v197 offset:61440
	v_mfma_f32_16x16x32_bf16 v[140:143], v[88:91], v[52:55], v[140:143]
	v_mfma_f32_16x16x32_bf16 v[24:27], v[88:91], v[116:119], v[24:27]
	v_mfma_f32_16x16x32_bf16 v[144:147], v[96:99], v[52:55], v[144:147]
	v_mfma_f32_16x16x32_bf16 v[32:35], v[96:99], v[116:119], v[32:35]
	s_waitcnt lgkmcnt(8)
	ds_read_b64_tr_b16 v[88:89], v198 offset:57344
	ds_read_b64_tr_b16 v[96:97], v199 offset:57344
	ds_read_b64_tr_b16 v[90:91], v198 offset:61440
	ds_read_b64_tr_b16 v[98:99], v199 offset:61440
	v_mfma_f32_16x16x32_bf16 v[148:151], v[104:107], v[52:55], v[148:151]
	v_mfma_f32_16x16x32_bf16 v[40:43], v[104:107], v[116:119], v[40:43]
	v_mfma_f32_16x16x32_bf16 v[152:155], v[112:115], v[52:55], v[152:155]
	v_mfma_f32_16x16x32_bf16 v[48:51], v[112:115], v[116:119], v[48:51]
	s_waitcnt lgkmcnt(8)
	ds_read_b64_tr_b16 v[104:105], v200 offset:57344
	ds_read_b64_tr_b16 v[112:113], v201 offset:57344
	ds_read_b64_tr_b16 v[106:107], v200 offset:61440
	ds_read_b64_tr_b16 v[114:115], v201 offset:61440
	v_mfma_f32_16x16x32_bf16 v[156:159], v[120:123], v[52:55], v[156:159]
	v_mfma_f32_16x16x32_bf16 v[56:59], v[120:123], v[116:119], v[56:59]
	v_mfma_f32_16x16x32_bf16 v[160:163], v[128:131], v[52:55], v[160:163]
	v_mfma_f32_16x16x32_bf16 v[64:67], v[128:131], v[116:119], v[64:67]
	s_waitcnt lgkmcnt(8)
	ds_read_b64_tr_b16 v[120:121], v202 offset:57344
	ds_read_b64_tr_b16 v[128:129], v203 offset:57344
	ds_read_b64_tr_b16 v[122:123], v202 offset:61440
	ds_read_b64_tr_b16 v[130:131], v203 offset:61440
	v_mfma_f32_16x16x32_bf16 v[132:135], v[72:75], v[60:63], v[132:135]
	v_mfma_f32_16x16x32_bf16 v[8:11], v[72:75], v[124:127], v[8:11]
	v_mfma_f32_16x16x32_bf16 v[136:139], v[80:83], v[60:63], v[136:139]
	v_mfma_f32_16x16x32_bf16 v[16:19], v[80:83], v[124:127], v[16:19]
	s_waitcnt lgkmcnt(8)
	v_mfma_f32_16x16x32_bf16 v[140:143], v[88:91], v[60:63], v[140:143]
	v_mfma_f32_16x16x32_bf16 v[24:27], v[88:91], v[124:127], v[24:27]
	v_mfma_f32_16x16x32_bf16 v[144:147], v[96:99], v[60:63], v[144:147]
	v_mfma_f32_16x16x32_bf16 v[32:35], v[96:99], v[124:127], v[32:35]
	s_waitcnt lgkmcnt(4)
	v_mfma_f32_16x16x32_bf16 v[148:151], v[104:107], v[60:63], v[148:151]
	v_mfma_f32_16x16x32_bf16 v[40:43], v[104:107], v[124:127], v[40:43]
	v_mfma_f32_16x16x32_bf16 v[152:155], v[112:115], v[60:63], v[152:155]
	v_mfma_f32_16x16x32_bf16 v[48:51], v[112:115], v[124:127], v[48:51]
	s_waitcnt lgkmcnt(0)
	v_mfma_f32_16x16x32_bf16 v[156:159], v[120:123], v[60:63], v[156:159]
	v_mfma_f32_16x16x32_bf16 v[56:59], v[120:123], v[124:127], v[56:59]
	v_mfma_f32_16x16x32_bf16 v[160:163], v[128:131], v[60:63], v[160:163]
	v_mfma_f32_16x16x32_bf16 v[64:67], v[128:131], v[124:127], v[64:67]
	s_nop 7
	s_nop 7
	v_mul_f32_e32 v230, v244, v132
	v_mul_f32_e32 v231, v244, v133
	v_mul_f32_e32 v232, v244, v134
	v_mul_f32_e32 v233, v244, v135
	v_cvt_pk_bf16_f32 v230, v230, v231
	v_cvt_pk_bf16_f32 v231, v232, v233
	global_store_dwordx2 v248, v[230:231], s[92:93] offset:256
	v_mul_f32_e32 v234, v244, v136
	v_mul_f32_e32 v235, v244, v137
	v_mul_f32_e32 v236, v244, v138
	v_mul_f32_e32 v237, v244, v139
	v_cvt_pk_bf16_f32 v234, v234, v235
	v_cvt_pk_bf16_f32 v235, v236, v237
	global_store_dwordx2 v248, v[234:235], s[92:93] offset:288
	v_mul_f32_e32 v230, v244, v140
	v_mul_f32_e32 v231, v244, v141
	v_mul_f32_e32 v232, v244, v142
	v_mul_f32_e32 v233, v244, v143
	v_cvt_pk_bf16_f32 v230, v230, v231
	v_cvt_pk_bf16_f32 v231, v232, v233
	global_store_dwordx2 v248, v[230:231], s[92:93] offset:320
	v_mul_f32_e32 v234, v244, v144
	v_mul_f32_e32 v235, v244, v145
	v_mul_f32_e32 v236, v244, v146
	v_mul_f32_e32 v237, v244, v147
	v_cvt_pk_bf16_f32 v234, v234, v235
	v_cvt_pk_bf16_f32 v235, v236, v237
	global_store_dwordx2 v248, v[234:235], s[92:93] offset:352
	v_mul_f32_e32 v230, v244, v148
	v_mul_f32_e32 v231, v244, v149
	v_mul_f32_e32 v232, v244, v150
	v_mul_f32_e32 v233, v244, v151
	v_cvt_pk_bf16_f32 v230, v230, v231
	v_cvt_pk_bf16_f32 v231, v232, v233
	global_store_dwordx2 v248, v[230:231], s[92:93] offset:384
; #define LAS __attribute__((address_space(3)))
; __device__ __forceinline__ unsigned cvt_pk_bf16(float lo, float hi) { const f32x2v v = {lo, hi}; const b16x2v r = __builtin_convertvector(v, b16x2v); return __builtin_bit_cast(unsigned, r); }
; #define LDS_BARRIER() do { asm volatile("s_waitcnt lgkmcnt(0)" ::: "memory"); __builtin_amdgcn_s_barrier(); asm volatile("" ::: "memory"); } while (0)
; #define XLOAD(kvbase, c8) do { const bf16_t* _src = (kvbase) + (((c8) >= 4) ? 2048 : 0) + ((c8) & 3) * 128 + piece * 8; \
;         _Pragma("unroll") for (int _it = 0; _it < 8; ++_it) pre[_it] = *(const u32x4*)(_src + (size_t)(srow + 32 * _it) * 4096); } while (0)
; #define XSTORE(buf) do { _Pragma("unroll") for (int _it = 0; _it < 8; ++_it) *(LAS u32x4*)((buf) + (srow + 32 * _it) * KV_STRIDE + piece * 16) = pre[_it]; } while (0)
; __device__ void cross_items(const Params& p, LAS unsigned char* lds) {
;     ...
;         for (int c = 0; c < 4; ++c) {
;             LAS unsigned char* buf = lds + (c & 1) * KV_BUF;
;             XSTORE(buf);
;             if (c < 3) XLOAD(kvb, 5 + c); else XLOAD(nkvb, 0);
;             LDS_BARRIER();
;     ...
; #pragma unroll
;             for (int c8 = 0; c8 < 8; ++c8) { u32x2 wv; wv.x = cvt_pk_bf16(ot[c8][0] * inv, ot[c8][1] * inv); wv.y = cvt_pk_bf16(ot[c8][2] * inv, ot[c8][3] * inv);
;                 *(u32x2*)(oc + tok * DM + head * 512 + c * 128 + 16 * c8 + 4 * g) = wv; }
	v_mul_f32_e32 v234, v244, v152
	v_mul_f32_e32 v235, v244, v153
	v_mul_f32_e32 v236, v244, v154
	v_mul_f32_e32 v237, v244, v155
	v_cvt_pk_bf16_f32 v234, v234, v235
	v_cvt_pk_bf16_f32 v235, v236, v237
	global_store_dwordx2 v248, v[234:235], s[92:93] offset:416
	v_mul_f32_e32 v230, v244, v156
	v_mul_f32_e32 v231, v244, v157
	v_mul_f32_e32 v232, v244, v158
	v_mul_f32_e32 v233, v244, v159
	v_cvt_pk_bf16_f32 v230, v230, v231
	v_cvt_pk_bf16_f32 v231, v232, v233
	global_store_dwordx2 v248, v[230:231], s[92:93] offset:448
	v_mul_f32_e32 v234, v244, v160
	v_mul_f32_e32 v235, v244, v161
	v_mul_f32_e32 v236, v244, v162
	v_mul_f32_e32 v237, v244, v163
	v_cvt_pk_bf16_f32 v234, v234, v235
	v_cvt_pk_bf16_f32 v235, v236, v237
	global_store_dwordx2 v248, v[234:235], s[92:93] offset:480
	v_mul_f32_e32 v230, v245, v8
	v_mul_f32_e32 v231, v245, v9
	v_mul_f32_e32 v232, v245, v10
	v_mul_f32_e32 v233, v245, v11
	v_cvt_pk_bf16_f32 v230, v230, v231
	v_cvt_pk_bf16_f32 v231, v232, v233
	global_store_dwordx2 v249, v[230:231], s[92:93] offset:256
	v_mul_f32_e32 v234, v245, v16
	v_mul_f32_e32 v235, v245, v17
	v_mul_f32_e32 v236, v245, v18
	v_mul_f32_e32 v237, v245, v19
	v_cvt_pk_bf16_f32 v234, v234, v235
	v_cvt_pk_bf16_f32 v235, v236, v237
	global_store_dwordx2 v249, v[234:235], s[92:93] offset:288
	v_mul_f32_e32 v230, v245, v24
	v_mul_f32_e32 v231, v245, v25
	v_mul_f32_e32 v232, v245, v26
	v_mul_f32_e32 v233, v245, v27
	v_cvt_pk_bf16_f32 v230, v230, v231
	v_cvt_pk_bf16_f32 v231, v232, v233
	global_store_dwordx2 v249, v[230:231], s[92:93] offset:320
	v_mul_f32_e32 v234, v245, v32
	v_mul_f32_e32 v235, v245, v33
	v_mul_f32_e32 v236, v245, v34
	v_mul_f32_e32 v237, v245, v35
	v_cvt_pk_bf16_f32 v234, v234, v235
	v_cvt_pk_bf16_f32 v235, v236, v237
	global_store_dwordx2 v249, v[234:235], s[92:93] offset:352
	v_mul_f32_e32 v230, v245, v40
	v_mul_f32_e32 v231, v245, v41
	v_mul_f32_e32 v232, v245, v42
	v_mul_f32_e32 v233, v245, v43
	v_cvt_pk_bf16_f32 v230, v230, v231
	v_cvt_pk_bf16_f32 v231, v232, v233
	global_store_dwordx2 v249, v[230:231], s[92:93] offset:384
	v_mul_f32_e32 v234, v245, v48
	v_mul_f32_e32 v235, v245, v49
	v_mul_f32_e32 v236, v245, v50
	v_mul_f32_e32 v237, v245, v51
	v_cvt_pk_bf16_f32 v234, v234, v235
	v_cvt_pk_bf16_f32 v235, v236, v237
	global_store_dwordx2 v249, v[234:235], s[92:93] offset:416
	v_mul_f32_e32 v230, v245, v56
	v_mul_f32_e32 v231, v245, v57
	v_mul_f32_e32 v232, v245, v58
	v_mul_f32_e32 v233, v245, v59
	v_cvt_pk_bf16_f32 v230, v230, v231
	v_cvt_pk_bf16_f32 v231, v232, v233
	global_store_dwordx2 v249, v[230:231], s[92:93] offset:448
	v_mul_f32_e32 v234, v245, v64
	v_mul_f32_e32 v235, v245, v65
	v_mul_f32_e32 v236, v245, v66
	v_mul_f32_e32 v237, v245, v67
	v_cvt_pk_bf16_f32 v234, v234, v235
	v_cvt_pk_bf16_f32 v235, v236, v237
	global_store_dwordx2 v249, v[234:235], s[92:93] offset:480
	v_xor_b32_e32 v196, 0x10000, v196
	v_xor_b32_e32 v197, 0x10000, v197
	v_xor_b32_e32 v198, 0x10000, v198
	v_xor_b32_e32 v199, 0x10000, v199
	v_xor_b32_e32 v200, 0x10000, v200
	v_xor_b32_e32 v201, 0x10000, v201
	v_xor_b32_e32 v202, 0x10000, v202
	v_xor_b32_e32 v203, 0x10000, v203
	s_waitcnt vmcnt(23)
	ds_write_b128 v0, v[164:167]
	s_waitcnt vmcnt(22)
	ds_write_b128 v0, v[168:171] offset:8192
	s_waitcnt vmcnt(21)
	ds_write_b128 v0, v[172:175] offset:16384
	s_waitcnt vmcnt(20)
	ds_write_b128 v0, v[176:179] offset:24576
	s_waitcnt vmcnt(19)
	ds_write_b128 v0, v[180:183] offset:32768
	s_waitcnt vmcnt(18)
	ds_write_b128 v0, v[184:187] offset:40960
	s_waitcnt vmcnt(17)
	ds_write_b128 v0, v[188:191] offset:49152
	s_waitcnt vmcnt(16)
	ds_write_b128 v0, v[192:195] offset:57344
	global_load_dwordx4 v[164:167], v242, s[6:7] offset:768
	v_add_u32_e32 v243, 0x40000, v242
	global_load_dwordx4 v[168:171], v243, s[6:7] offset:768
	v_add_u32_e32 v243, 0x80000, v242
	global_load_dwordx4 v[172:175], v243, s[6:7] offset:768
	v_add_u32_e32 v243, 0xc0000, v242
	global_load_dwordx4 v[176:179], v243, s[6:7] offset:768
	v_add_u32_e32 v243, 0x100000, v242
	global_load_dwordx4 v[180:183], v243, s[6:7] offset:768
	v_add_u32_e32 v243, 0x140000, v242
	global_load_dwordx4 v[184:187], v243, s[6:7] offset:768
	v_add_u32_e32 v243, 0x180000, v242
	global_load_dwordx4 v[188:191], v243, s[6:7] offset:768
	v_add_u32_e32 v243, 0x1c0000, v242
	global_load_dwordx4 v[192:195], v243, s[6:7] offset:768
	s_waitcnt lgkmcnt(0)
	s_barrier
; __device__ __forceinline__ f32x4 mfma16(bf16x8 a, bf16x8 b, f32x4 c) { return __builtin_amdgcn_mfma_f32_16x16x32_bf16(a, b, c, 0, 0, 0); }
; __device__ __forceinline__ void tr_frag4(unsigned a, unsigned b, bf16x8 (&f)[4]) {
;     s16x4 x0, x1, x2, x3, y0, y1, y2, y3;
;     asm volatile("ds_read_b64_tr_b16 %0, %8\n\tds_read_b64_tr_b16 %1, %8 offset:32\n\tds_read_b64_tr_b16 %2, %8 offset:64\n\tds_read_b64_tr_b16 %3, %8 offset:96\n\t"
;                  "ds_read_b64_tr_b16 %4, %9\n\tds_read_b64_tr_b16 %5, %9 offset:32\n\tds_read_b64_tr_b16 %6, %9 offset:64\n\tds_read_b64_tr_b16 %7, %9 offset:96\n\t"
;                  "s_waitcnt lgkmcnt(0)"
;                  : "=&v"(x0), "=&v"(x1), "=&v"(x2), "=&v"(x3), "=&v"(y0), "=&v"(y1), "=&v"(y2), "=&v"(y3) : "v"(a), "v"(b) : "memory");
; __device__ void cross_items(const Params& p, LAS unsigned char* lds) {
;     ...
;             const unsigned bb = lbase + (unsigned)((c & 1) * KV_BUF);
; #pragma unroll
;             for (int sx = 0; sx < 8; ++sx) {
;                 const unsigned aA = bb + (unsigned)((32 * sx + 4 * g + (idx >> 2)) * KV_STRIDE + 8 * (idx & 3));
;                 const unsigned aB = aA + 16u * KV_STRIDE;
;                 bf16x8 vf[4];
;                 tr_frag4(aA, aB, vf);
; #pragma unroll
;                 for (int c8 = 0; c8 < 4; ++c8) ot[c8] = mfma16(vf[c8], pf[sx], ot[c8]);
;                 tr_frag4(aA + 128, aB + 128, vf);
; #pragma unroll
;                 for (int c8 = 0; c8 < 4; ++c8) ot[4 + c8] = mfma16(vf[c8], pf[sx], ot[4 + c8]);
;             }
	ds_read_b64_tr_b16 v[72:73], v196
	ds_read_b64_tr_b16 v[80:81], v197
	ds_read_b64_tr_b16 v[74:75], v196 offset:4096
	ds_read_b64_tr_b16 v[82:83], v197 offset:4096
	ds_read_b64_tr_b16 v[88:89], v198
	ds_read_b64_tr_b16 v[96:97], v199
	ds_read_b64_tr_b16 v[90:91], v198 offset:4096
	ds_read_b64_tr_b16 v[98:99], v199 offset:4096
	ds_read_b64_tr_b16 v[104:105], v200
	ds_read_b64_tr_b16 v[112:113], v201
	ds_read_b64_tr_b16 v[106:107], v200 offset:4096
	ds_read_b64_tr_b16 v[114:115], v201 offset:4096
	s_waitcnt lgkmcnt(8)
	ds_read_b64_tr_b16 v[120:121], v202
	ds_read_b64_tr_b16 v[128:129], v203
	ds_read_b64_tr_b16 v[122:123], v202 offset:4096
	ds_read_b64_tr_b16 v[130:131], v203 offset:4096
	v_mfma_f32_16x16x32_bf16 v[132:135], v[72:75], v[4:7], 0
	v_mfma_f32_16x16x32_bf16 v[8:11], v[72:75], v[68:71], 0
	v_mfma_f32_16x16x32_bf16 v[136:139], v[80:83], v[4:7], 0
	v_mfma_f32_16x16x32_bf16 v[16:19], v[80:83], v[68:71], 0
	s_waitcnt lgkmcnt(8)
	ds_read_b64_tr_b16 v[72:73], v196 offset:8192
	ds_read_b64_tr_b16 v[80:81], v197 offset:8192
	ds_read_b64_tr_b16 v[74:75], v196 offset:12288
	ds_read_b64_tr_b16 v[82:83], v197 offset:12288
	v_mfma_f32_16x16x32_bf16 v[140:143], v[88:91], v[4:7], 0
	v_mfma_f32_16x16x32_bf16 v[24:27], v[88:91], v[68:71], 0
	v_mfma_f32_16x16x32_bf16 v[144:147], v[96:99], v[4:7], 0
	v_mfma_f32_16x16x32_bf16 v[32:35], v[96:99], v[68:71], 0
	s_waitcnt lgkmcnt(8)
	ds_read_b64_tr_b16 v[88:89], v198 offset:8192
	ds_read_b64_tr_b16 v[96:97], v199 offset:8192
	ds_read_b64_tr_b16 v[90:91], v198 offset:12288
	ds_read_b64_tr_b16 v[98:99], v199 offset:12288
	v_mfma_f32_16x16x32_bf16 v[148:151], v[104:107], v[4:7], 0
	v_mfma_f32_16x16x32_bf16 v[40:43], v[104:107], v[68:71], 0
	v_mfma_f32_16x16x32_bf16 v[152:155], v[112:115], v[4:7], 0
	v_mfma_f32_16x16x32_bf16 v[48:51], v[112:115], v[68:71], 0
	s_waitcnt lgkmcnt(8)
	ds_read_b64_tr_b16 v[104:105], v200 offset:8192
	ds_read_b64_tr_b16 v[112:113], v201 offset:8192
	ds_read_b64_tr_b16 v[106:107], v200 offset:12288
	ds_read_b64_tr_b16 v[114:115], v201 offset:12288
	v_mfma_f32_16x16x32_bf16 v[156:159], v[120:123], v[4:7], 0
	v_mfma_f32_16x16x32_bf16 v[56:59], v[120:123], v[68:71], 0
	v_mfma_f32_16x16x32_bf16 v[160:163], v[128:131], v[4:7], 0
	v_mfma_f32_16x16x32_bf16 v[64:67], v[128:131], v[68:71], 0
	s_waitcnt lgkmcnt(8)
	ds_read_b64_tr_b16 v[120:121], v202 offset:8192
	ds_read_b64_tr_b16 v[128:129], v203 offset:8192
	ds_read_b64_tr_b16 v[122:123], v202 offset:12288
	ds_read_b64_tr_b16 v[130:131], v203 offset:12288
	v_mfma_f32_16x16x32_bf16 v[132:135], v[72:75], v[12:15], v[132:135]
	v_mfma_f32_16x16x32_bf16 v[8:11], v[72:75], v[76:79], v[8:11]
	v_mfma_f32_16x16x32_bf16 v[136:139], v[80:83], v[12:15], v[136:139]
	v_mfma_f32_16x16x32_bf16 v[16:19], v[80:83], v[76:79], v[16:19]
	s_waitcnt lgkmcnt(8)
	ds_read_b64_tr_b16 v[72:73], v196 offset:16384
	ds_read_b64_tr_b16 v[80:81], v197 offset:16384
	ds_read_b64_tr_b16 v[74:75], v196 offset:20480
	ds_read_b64_tr_b16 v[82:83], v197 offset:20480
	v_mfma_f32_16x16x32_bf16 v[140:143], v[88:91], v[12:15], v[140:143]
	v_mfma_f32_16x16x32_bf16 v[24:27], v[88:91], v[76:79], v[24:27]
	v_mfma_f32_16x16x32_bf16 v[144:147], v[96:99], v[12:15], v[144:147]
	v_mfma_f32_16x16x32_bf16 v[32:35], v[96:99], v[76:79], v[32:35]
	s_waitcnt lgkmcnt(8)
	ds_read_b64_tr_b16 v[88:89], v198 offset:16384
	ds_read_b64_tr_b16 v[96:97], v199 offset:16384
	ds_read_b64_tr_b16 v[90:91], v198 offset:20480
	ds_read_b64_tr_b16 v[98:99], v199 offset:20480
	v_mfma_f32_16x16x32_bf16 v[148:151], v[104:107], v[12:15], v[148:151]
	v_mfma_f32_16x16x32_bf16 v[40:43], v[104:107], v[76:79], v[40:43]
	v_mfma_f32_16x16x32_bf16 v[152:155], v[112:115], v[12:15], v[152:155]
	v_mfma_f32_16x16x32_bf16 v[48:51], v[112:115], v[76:79], v[48:51]
	s_waitcnt lgkmcnt(8)
	ds_read_b64_tr_b16 v[104:105], v200 offset:16384
	ds_read_b64_tr_b16 v[112:113], v201 offset:16384
	ds_read_b64_tr_b16 v[106:107], v200 offset:20480
	ds_read_b64_tr_b16 v[114:115], v201 offset:20480
	v_mfma_f32_16x16x32_bf16 v[156:159], v[120:123], v[12:15], v[156:159]
	v_mfma_f32_16x16x32_bf16 v[56:59], v[120:123], v[76:79], v[56:59]
	v_mfma_f32_16x16x32_bf16 v[160:163], v[128:131], v[12:15], v[160:163]
	v_mfma_f32_16x16x32_bf16 v[64:67], v[128:131], v[76:79], v[64:67]
	s_waitcnt lgkmcnt(8)
	ds_read_b64_tr_b16 v[120:121], v202 offset:16384
	ds_read_b64_tr_b16 v[128:129], v203 offset:16384
	ds_read_b64_tr_b16 v[122:123], v202 offset:20480
	ds_read_b64_tr_b16 v[130:131], v203 offset:20480
	v_mfma_f32_16x16x32_bf16 v[132:135], v[72:75], v[20:23], v[132:135]
	v_mfma_f32_16x16x32_bf16 v[8:11], v[72:75], v[84:87], v[8:11]
	v_mfma_f32_16x16x32_bf16 v[136:139], v[80:83], v[20:23], v[136:139]
	v_mfma_f32_16x16x32_bf16 v[16:19], v[80:83], v[84:87], v[16:19]
	s_waitcnt lgkmcnt(8)
	ds_read_b64_tr_b16 v[72:73], v196 offset:24576
	ds_read_b64_tr_b16 v[80:81], v197 offset:24576
	ds_read_b64_tr_b16 v[74:75], v196 offset:28672
	ds_read_b64_tr_b16 v[82:83], v197 offset:28672
	v_mfma_f32_16x16x32_bf16 v[140:143], v[88:91], v[20:23], v[140:143]
	v_mfma_f32_16x16x32_bf16 v[24:27], v[88:91], v[84:87], v[24:27]
	v_mfma_f32_16x16x32_bf16 v[144:147], v[96:99], v[20:23], v[144:147]
	v_mfma_f32_16x16x32_bf16 v[32:35], v[96:99], v[84:87], v[32:35]
	s_waitcnt lgkmcnt(8)
	ds_read_b64_tr_b16 v[88:89], v198 offset:24576
	ds_read_b64_tr_b16 v[96:97], v199 offset:24576
	ds_read_b64_tr_b16 v[90:91], v198 offset:28672
	ds_read_b64_tr_b16 v[98:99], v199 offset:28672
	v_mfma_f32_16x16x32_bf16 v[148:151], v[104:107], v[20:23], v[148:151]
	v_mfma_f32_16x16x32_bf16 v[40:43], v[104:107], v[84:87], v[40:43]
	v_mfma_f32_16x16x32_bf16 v[152:155], v[112:115], v[20:23], v[152:155]
	v_mfma_f32_16x16x32_bf16 v[48:51], v[112:115], v[84:87], v[48:51]
	s_waitcnt lgkmcnt(8)
; __device__ __forceinline__ f32x4 mfma16(bf16x8 a, bf16x8 b, f32x4 c) { return __builtin_amdgcn_mfma_f32_16x16x32_bf16(a, b, c, 0, 0, 0); }
; __device__ void cross_items(const Params& p, LAS unsigned char* lds) {
;     ...
; #pragma unroll
;             for (int sx = 0; sx < 8; ++sx) {
;                 const unsigned aA = bb + (unsigned)((32 * sx + 4 * g + (idx >> 2)) * KV_STRIDE + 8 * (idx & 3));
;                 const unsigned aB = aA + 16u * KV_STRIDE;
;                 bf16x8 vf[4];
;                 tr_frag4(aA, aB, vf);
; #pragma unroll
;                 for (int c8 = 0; c8 < 4; ++c8) ot[c8] = mfma16(vf[c8], pf[sx], ot[c8]);
;                 tr_frag4(aA + 128, aB + 128, vf);
; #pragma unroll
;                 for (int c8 = 0; c8 < 4; ++c8) ot[4 + c8] = mfma16(vf[c8], pf[sx], ot[4 + c8]);
;             }
	ds_read_b64_tr_b16 v[104:105], v200 offset:24576
	ds_read_b64_tr_b16 v[112:113], v201 offset:24576
	ds_read_b64_tr_b16 v[106:107], v200 offset:28672
	ds_read_b64_tr_b16 v[114:115], v201 offset:28672
	v_mfma_f32_16x16x32_bf16 v[156:159], v[120:123], v[20:23], v[156:159]
	v_mfma_f32_16x16x32_bf16 v[56:59], v[120:123], v[84:87], v[56:59]
	v_mfma_f32_16x16x32_bf16 v[160:163], v[128:131], v[20:23], v[160:163]
	v_mfma_f32_16x16x32_bf16 v[64:67], v[128:131], v[84:87], v[64:67]
	s_waitcnt lgkmcnt(8)
	ds_read_b64_tr_b16 v[120:121], v202 offset:24576
	ds_read_b64_tr_b16 v[128:129], v203 offset:24576
	ds_read_b64_tr_b16 v[122:123], v202 offset:28672
	ds_read_b64_tr_b16 v[130:131], v203 offset:28672
	v_mfma_f32_16x16x32_bf16 v[132:135], v[72:75], v[28:31], v[132:135]
	v_mfma_f32_16x16x32_bf16 v[8:11], v[72:75], v[92:95], v[8:11]
	v_mfma_f32_16x16x32_bf16 v[136:139], v[80:83], v[28:31], v[136:139]
	v_mfma_f32_16x16x32_bf16 v[16:19], v[80:83], v[92:95], v[16:19]
	s_waitcnt lgkmcnt(8)
	ds_read_b64_tr_b16 v[72:73], v196 offset:32768
	ds_read_b64_tr_b16 v[80:81], v197 offset:32768
	ds_read_b64_tr_b16 v[74:75], v196 offset:36864
	ds_read_b64_tr_b16 v[82:83], v197 offset:36864
	v_mfma_f32_16x16x32_bf16 v[140:143], v[88:91], v[28:31], v[140:143]
	v_mfma_f32_16x16x32_bf16 v[24:27], v[88:91], v[92:95], v[24:27]
	v_mfma_f32_16x16x32_bf16 v[144:147], v[96:99], v[28:31], v[144:147]
	v_mfma_f32_16x16x32_bf16 v[32:35], v[96:99], v[92:95], v[32:35]
	s_waitcnt lgkmcnt(8)
	ds_read_b64_tr_b16 v[88:89], v198 offset:32768
	ds_read_b64_tr_b16 v[96:97], v199 offset:32768
	ds_read_b64_tr_b16 v[90:91], v198 offset:36864
	ds_read_b64_tr_b16 v[98:99], v199 offset:36864
	v_mfma_f32_16x16x32_bf16 v[148:151], v[104:107], v[28:31], v[148:151]
	v_mfma_f32_16x16x32_bf16 v[40:43], v[104:107], v[92:95], v[40:43]
	v_mfma_f32_16x16x32_bf16 v[152:155], v[112:115], v[28:31], v[152:155]
	v_mfma_f32_16x16x32_bf16 v[48:51], v[112:115], v[92:95], v[48:51]
	s_waitcnt lgkmcnt(8)
	ds_read_b64_tr_b16 v[104:105], v200 offset:32768
	ds_read_b64_tr_b16 v[112:113], v201 offset:32768
	ds_read_b64_tr_b16 v[106:107], v200 offset:36864
	ds_read_b64_tr_b16 v[114:115], v201 offset:36864
	v_mfma_f32_16x16x32_bf16 v[156:159], v[120:123], v[28:31], v[156:159]
	v_mfma_f32_16x16x32_bf16 v[56:59], v[120:123], v[92:95], v[56:59]
	v_mfma_f32_16x16x32_bf16 v[160:163], v[128:131], v[28:31], v[160:163]
	v_mfma_f32_16x16x32_bf16 v[64:67], v[128:131], v[92:95], v[64:67]
	s_waitcnt lgkmcnt(8)
	ds_read_b64_tr_b16 v[120:121], v202 offset:32768
	ds_read_b64_tr_b16 v[128:129], v203 offset:32768
	ds_read_b64_tr_b16 v[122:123], v202 offset:36864
	ds_read_b64_tr_b16 v[130:131], v203 offset:36864
	v_mfma_f32_16x16x32_bf16 v[132:135], v[72:75], v[36:39], v[132:135]
	v_mfma_f32_16x16x32_bf16 v[8:11], v[72:75], v[100:103], v[8:11]
	v_mfma_f32_16x16x32_bf16 v[136:139], v[80:83], v[36:39], v[136:139]
	v_mfma_f32_16x16x32_bf16 v[16:19], v[80:83], v[100:103], v[16:19]
	s_waitcnt lgkmcnt(8)
	ds_read_b64_tr_b16 v[72:73], v196 offset:40960
	ds_read_b64_tr_b16 v[80:81], v197 offset:40960
	ds_read_b64_tr_b16 v[74:75], v196 offset:45056
	ds_read_b64_tr_b16 v[82:83], v197 offset:45056
	v_mfma_f32_16x16x32_bf16 v[140:143], v[88:91], v[36:39], v[140:143]
	v_mfma_f32_16x16x32_bf16 v[24:27], v[88:91], v[100:103], v[24:27]
	v_mfma_f32_16x16x32_bf16 v[144:147], v[96:99], v[36:39], v[144:147]
	v_mfma_f32_16x16x32_bf16 v[32:35], v[96:99], v[100:103], v[32:35]
	s_waitcnt lgkmcnt(8)
	ds_read_b64_tr_b16 v[88:89], v198 offset:40960
	ds_read_b64_tr_b16 v[96:97], v199 offset:40960
	ds_read_b64_tr_b16 v[90:91], v198 offset:45056
	ds_read_b64_tr_b16 v[98:99], v199 offset:45056
	v_mfma_f32_16x16x32_bf16 v[148:151], v[104:107], v[36:39], v[148:151]
	v_mfma_f32_16x16x32_bf16 v[40:43], v[104:107], v[100:103], v[40:43]
	v_mfma_f32_16x16x32_bf16 v[152:155], v[112:115], v[36:39], v[152:155]
	v_mfma_f32_16x16x32_bf16 v[48:51], v[112:115], v[100:103], v[48:51]
	s_waitcnt lgkmcnt(8)
	ds_read_b64_tr_b16 v[104:105], v200 offset:40960
	ds_read_b64_tr_b16 v[112:113], v201 offset:40960
	ds_read_b64_tr_b16 v[106:107], v200 offset:45056
	ds_read_b64_tr_b16 v[114:115], v201 offset:45056
	v_mfma_f32_16x16x32_bf16 v[156:159], v[120:123], v[36:39], v[156:159]
	v_mfma_f32_16x16x32_bf16 v[56:59], v[120:123], v[100:103], v[56:59]
	v_mfma_f32_16x16x32_bf16 v[160:163], v[128:131], v[36:39], v[160:163]
	v_mfma_f32_16x16x32_bf16 v[64:67], v[128:131], v[100:103], v[64:67]
	s_waitcnt lgkmcnt(8)
	ds_read_b64_tr_b16 v[120:121], v202 offset:40960
	ds_read_b64_tr_b16 v[128:129], v203 offset:40960
	ds_read_b64_tr_b16 v[122:123], v202 offset:45056
	ds_read_b64_tr_b16 v[130:131], v203 offset:45056
	v_mfma_f32_16x16x32_bf16 v[132:135], v[72:75], v[44:47], v[132:135]
	v_mfma_f32_16x16x32_bf16 v[8:11], v[72:75], v[108:111], v[8:11]
	v_mfma_f32_16x16x32_bf16 v[136:139], v[80:83], v[44:47], v[136:139]
	v_mfma_f32_16x16x32_bf16 v[16:19], v[80:83], v[108:111], v[16:19]
	s_waitcnt lgkmcnt(8)
	ds_read_b64_tr_b16 v[72:73], v196 offset:49152
	ds_read_b64_tr_b16 v[80:81], v197 offset:49152
	ds_read_b64_tr_b16 v[74:75], v196 offset:53248
	ds_read_b64_tr_b16 v[82:83], v197 offset:53248
	v_mfma_f32_16x16x32_bf16 v[140:143], v[88:91], v[44:47], v[140:143]
	v_mfma_f32_16x16x32_bf16 v[24:27], v[88:91], v[108:111], v[24:27]
	v_mfma_f32_16x16x32_bf16 v[144:147], v[96:99], v[44:47], v[144:147]
	v_mfma_f32_16x16x32_bf16 v[32:35], v[96:99], v[108:111], v[32:35]
	s_waitcnt lgkmcnt(8)
; __device__ __forceinline__ unsigned cvt_pk_bf16(float lo, float hi) { const f32x2v v = {lo, hi}; const b16x2v r = __builtin_convertvector(v, b16x2v); return __builtin_bit_cast(unsigned, r); }
; __device__ __forceinline__ f32x4 mfma16(bf16x8 a, bf16x8 b, f32x4 c) { return __builtin_amdgcn_mfma_f32_16x16x32_bf16(a, b, c, 0, 0, 0); }
; __device__ void cross_items(const Params& p, LAS unsigned char* lds) {
;     ...
;                 tr_frag4(aA, aB, vf);
; #pragma unroll
;                 for (int c8 = 0; c8 < 4; ++c8) ot[c8] = mfma16(vf[c8], pf[sx], ot[c8]);
;                 tr_frag4(aA + 128, aB + 128, vf);
; #pragma unroll
;                 for (int c8 = 0; c8 < 4; ++c8) ot[4 + c8] = mfma16(vf[c8], pf[sx], ot[4 + c8]);
;             }
; #pragma unroll
;             for (int c8 = 0; c8 < 8; ++c8) { u32x2 wv; wv.x = cvt_pk_bf16(ot[c8][0] * inv, ot[c8][1] * inv); wv.y = cvt_pk_bf16(ot[c8][2] * inv, ot[c8][3] * inv);
;                 *(u32x2*)(oc + tok * DM + head * 512 + c * 128 + 16 * c8 + 4 * g) = wv; }
	ds_read_b64_tr_b16 v[88:89], v198 offset:49152
	ds_read_b64_tr_b16 v[96:97], v199 offset:49152
	ds_read_b64_tr_b16 v[90:91], v198 offset:53248
	ds_read_b64_tr_b16 v[98:99], v199 offset:53248
	v_mfma_f32_16x16x32_bf16 v[148:151], v[104:107], v[44:47], v[148:151]
	v_mfma_f32_16x16x32_bf16 v[40:43], v[104:107], v[108:111], v[40:43]
	v_mfma_f32_16x16x32_bf16 v[152:155], v[112:115], v[44:47], v[152:155]
	v_mfma_f32_16x16x32_bf16 v[48:51], v[112:115], v[108:111], v[48:51]
	s_waitcnt lgkmcnt(8)
	ds_read_b64_tr_b16 v[104:105], v200 offset:49152
	ds_read_b64_tr_b16 v[112:113], v201 offset:49152
	ds_read_b64_tr_b16 v[106:107], v200 offset:53248
	ds_read_b64_tr_b16 v[114:115], v201 offset:53248
	v_mfma_f32_16x16x32_bf16 v[156:159], v[120:123], v[44:47], v[156:159]
	v_mfma_f32_16x16x32_bf16 v[56:59], v[120:123], v[108:111], v[56:59]
	v_mfma_f32_16x16x32_bf16 v[160:163], v[128:131], v[44:47], v[160:163]
	v_mfma_f32_16x16x32_bf16 v[64:67], v[128:131], v[108:111], v[64:67]
	s_waitcnt lgkmcnt(8)
	ds_read_b64_tr_b16 v[120:121], v202 offset:49152
	ds_read_b64_tr_b16 v[128:129], v203 offset:49152
	ds_read_b64_tr_b16 v[122:123], v202 offset:53248
	ds_read_b64_tr_b16 v[130:131], v203 offset:53248
	v_mfma_f32_16x16x32_bf16 v[132:135], v[72:75], v[52:55], v[132:135]
	v_mfma_f32_16x16x32_bf16 v[8:11], v[72:75], v[116:119], v[8:11]
	v_mfma_f32_16x16x32_bf16 v[136:139], v[80:83], v[52:55], v[136:139]
	v_mfma_f32_16x16x32_bf16 v[16:19], v[80:83], v[116:119], v[16:19]
	s_waitcnt lgkmcnt(8)
	ds_read_b64_tr_b16 v[72:73], v196 offset:57344
	ds_read_b64_tr_b16 v[80:81], v197 offset:57344
	ds_read_b64_tr_b16 v[74:75], v196 offset:61440
	ds_read_b64_tr_b16 v[82:83], v197 offset:61440
	v_mfma_f32_16x16x32_bf16 v[140:143], v[88:91], v[52:55], v[140:143]
	v_mfma_f32_16x16x32_bf16 v[24:27], v[88:91], v[116:119], v[24:27]
	v_mfma_f32_16x16x32_bf16 v[144:147], v[96:99], v[52:55], v[144:147]
	v_mfma_f32_16x16x32_bf16 v[32:35], v[96:99], v[116:119], v[32:35]
	s_waitcnt lgkmcnt(8)
	ds_read_b64_tr_b16 v[88:89], v198 offset:57344
	ds_read_b64_tr_b16 v[96:97], v199 offset:57344
	ds_read_b64_tr_b16 v[90:91], v198 offset:61440
	ds_read_b64_tr_b16 v[98:99], v199 offset:61440
	v_mfma_f32_16x16x32_bf16 v[148:151], v[104:107], v[52:55], v[148:151]
	v_mfma_f32_16x16x32_bf16 v[40:43], v[104:107], v[116:119], v[40:43]
	v_mfma_f32_16x16x32_bf16 v[152:155], v[112:115], v[52:55], v[152:155]
	v_mfma_f32_16x16x32_bf16 v[48:51], v[112:115], v[116:119], v[48:51]
	s_waitcnt lgkmcnt(8)
	ds_read_b64_tr_b16 v[104:105], v200 offset:57344
	ds_read_b64_tr_b16 v[112:113], v201 offset:57344
	ds_read_b64_tr_b16 v[106:107], v200 offset:61440
	ds_read_b64_tr_b16 v[114:115], v201 offset:61440
	v_mfma_f32_16x16x32_bf16 v[156:159], v[120:123], v[52:55], v[156:159]
	v_mfma_f32_16x16x32_bf16 v[56:59], v[120:123], v[116:119], v[56:59]
	v_mfma_f32_16x16x32_bf16 v[160:163], v[128:131], v[52:55], v[160:163]
	v_mfma_f32_16x16x32_bf16 v[64:67], v[128:131], v[116:119], v[64:67]
	s_waitcnt lgkmcnt(8)
	ds_read_b64_tr_b16 v[120:121], v202 offset:57344
	ds_read_b64_tr_b16 v[128:129], v203 offset:57344
	ds_read_b64_tr_b16 v[122:123], v202 offset:61440
	ds_read_b64_tr_b16 v[130:131], v203 offset:61440
	v_mfma_f32_16x16x32_bf16 v[132:135], v[72:75], v[60:63], v[132:135]
	v_mfma_f32_16x16x32_bf16 v[8:11], v[72:75], v[124:127], v[8:11]
	v_mfma_f32_16x16x32_bf16 v[136:139], v[80:83], v[60:63], v[136:139]
	v_mfma_f32_16x16x32_bf16 v[16:19], v[80:83], v[124:127], v[16:19]
	s_waitcnt lgkmcnt(8)
	v_mfma_f32_16x16x32_bf16 v[140:143], v[88:91], v[60:63], v[140:143]
	v_mfma_f32_16x16x32_bf16 v[24:27], v[88:91], v[124:127], v[24:27]
	v_mfma_f32_16x16x32_bf16 v[144:147], v[96:99], v[60:63], v[144:147]
	v_mfma_f32_16x16x32_bf16 v[32:35], v[96:99], v[124:127], v[32:35]
	s_waitcnt lgkmcnt(4)
	v_mfma_f32_16x16x32_bf16 v[148:151], v[104:107], v[60:63], v[148:151]
	v_mfma_f32_16x16x32_bf16 v[40:43], v[104:107], v[124:127], v[40:43]
	v_mfma_f32_16x16x32_bf16 v[152:155], v[112:115], v[60:63], v[152:155]
	v_mfma_f32_16x16x32_bf16 v[48:51], v[112:115], v[124:127], v[48:51]
	s_waitcnt lgkmcnt(0)
	v_mfma_f32_16x16x32_bf16 v[156:159], v[120:123], v[60:63], v[156:159]
	v_mfma_f32_16x16x32_bf16 v[56:59], v[120:123], v[124:127], v[56:59]
	v_mfma_f32_16x16x32_bf16 v[160:163], v[128:131], v[60:63], v[160:163]
	v_mfma_f32_16x16x32_bf16 v[64:67], v[128:131], v[124:127], v[64:67]
	s_nop 7
	s_nop 7
	v_mul_f32_e32 v230, v244, v132
	v_mul_f32_e32 v231, v244, v133
	v_mul_f32_e32 v232, v244, v134
	v_mul_f32_e32 v233, v244, v135
	v_cvt_pk_bf16_f32 v230, v230, v231
	v_cvt_pk_bf16_f32 v231, v232, v233
	global_store_dwordx2 v248, v[230:231], s[92:93] offset:512
	v_mul_f32_e32 v234, v244, v136
	v_mul_f32_e32 v235, v244, v137
	v_mul_f32_e32 v236, v244, v138
	v_mul_f32_e32 v237, v244, v139
	v_cvt_pk_bf16_f32 v234, v234, v235
	v_cvt_pk_bf16_f32 v235, v236, v237
	global_store_dwordx2 v248, v[234:235], s[92:93] offset:544
	v_mul_f32_e32 v230, v244, v140
	v_mul_f32_e32 v231, v244, v141
	v_mul_f32_e32 v232, v244, v142
	v_mul_f32_e32 v233, v244, v143
	v_cvt_pk_bf16_f32 v230, v230, v231
	v_cvt_pk_bf16_f32 v231, v232, v233
	global_store_dwordx2 v248, v[230:231], s[92:93] offset:576
	v_mul_f32_e32 v234, v244, v144
	v_mul_f32_e32 v235, v244, v145
	v_mul_f32_e32 v236, v244, v146
	v_mul_f32_e32 v237, v244, v147
	v_cvt_pk_bf16_f32 v234, v234, v235
	v_cvt_pk_bf16_f32 v235, v236, v237
	global_store_dwordx2 v248, v[234:235], s[92:93] offset:608
	v_mul_f32_e32 v230, v244, v148
	v_mul_f32_e32 v231, v244, v149
	v_mul_f32_e32 v232, v244, v150
	v_mul_f32_e32 v233, v244, v151
	v_cvt_pk_bf16_f32 v230, v230, v231
	v_cvt_pk_bf16_f32 v231, v232, v233
	global_store_dwordx2 v248, v[230:231], s[92:93] offset:640
; #define LAS __attribute__((address_space(3)))
; __device__ __forceinline__ f32x4 mfma16(bf16x8 a, bf16x8 b, f32x4 c) { return __builtin_amdgcn_mfma_f32_16x16x32_bf16(a, b, c, 0, 0, 0); }
; #define LDS_BARRIER() do { asm volatile("s_waitcnt lgkmcnt(0)" ::: "memory"); __builtin_amdgcn_s_barrier(); asm volatile("" ::: "memory"); } while (0)
; #define XLOAD(kvbase, c8) do { const bf16_t* _src = (kvbase) + (((c8) >= 4) ? 2048 : 0) + ((c8) & 3) * 128 + piece * 8; \
;         _Pragma("unroll") for (int _it = 0; _it < 8; ++_it) pre[_it] = *(const u32x4*)(_src + (size_t)(srow + 32 * _it) * 4096); } while (0)
; #define XSTORE(buf) do { _Pragma("unroll") for (int _it = 0; _it < 8; ++_it) *(LAS u32x4*)((buf) + (srow + 32 * _it) * KV_STRIDE + piece * 16) = pre[_it]; } while (0)
; __device__ void cross_items(const Params& p, LAS unsigned char* lds) {
;     ...
;         for (int c = 0; c < 4; ++c) {
;             LAS unsigned char* buf = lds + (c & 1) * KV_BUF;
;             XSTORE(buf);
;             if (c < 3) XLOAD(kvb, 5 + c); else XLOAD(nkvb, 0);
;             LDS_BARRIER();
;             f32x4 ot[8];
; #pragma unroll
;             for (int c8 = 0; c8 < 8; ++c8) ot[c8] = (f32x4){0.f, 0.f, 0.f, 0.f};
;             const unsigned bb = lbase + (unsigned)((c & 1) * KV_BUF);
; #pragma unroll
;             for (int sx = 0; sx < 8; ++sx) {
;                 const unsigned aA = bb + (unsigned)((32 * sx + 4 * g + (idx >> 2)) * KV_STRIDE + 8 * (idx & 3));
;                 const unsigned aB = aA + 16u * KV_STRIDE;
;                 bf16x8 vf[4];
;                 tr_frag4(aA, aB, vf);
; #pragma unroll
;                 for (int c8 = 0; c8 < 4; ++c8) ot[c8] = mfma16(vf[c8], pf[sx], ot[c8]);
;                 tr_frag4(aA + 128, aB + 128, vf);
; #pragma unroll
;                 for (int c8 = 0; c8 < 4; ++c8) ot[4 + c8] = mfma16(vf[c8], pf[sx], ot[4 + c8]);
;             }
	v_mul_f32_e32 v234, v244, v152
	v_mul_f32_e32 v235, v244, v153
	v_mul_f32_e32 v236, v244, v154
	v_mul_f32_e32 v237, v244, v155
	v_cvt_pk_bf16_f32 v234, v234, v235
	v_cvt_pk_bf16_f32 v235, v236, v237
	global_store_dwordx2 v248, v[234:235], s[92:93] offset:672
	v_mul_f32_e32 v230, v244, v156
	v_mul_f32_e32 v231, v244, v157
	v_mul_f32_e32 v232, v244, v158
	v_mul_f32_e32 v233, v244, v159
	v_cvt_pk_bf16_f32 v230, v230, v231
	v_cvt_pk_bf16_f32 v231, v232, v233
	global_store_dwordx2 v248, v[230:231], s[92:93] offset:704
	v_mul_f32_e32 v234, v244, v160
	v_mul_f32_e32 v235, v244, v161
	v_mul_f32_e32 v236, v244, v162
	v_mul_f32_e32 v237, v244, v163
	v_cvt_pk_bf16_f32 v234, v234, v235
	v_cvt_pk_bf16_f32 v235, v236, v237
	global_store_dwordx2 v248, v[234:235], s[92:93] offset:736
	v_mul_f32_e32 v230, v245, v8
	v_mul_f32_e32 v231, v245, v9
	v_mul_f32_e32 v232, v245, v10
	v_mul_f32_e32 v233, v245, v11
	v_cvt_pk_bf16_f32 v230, v230, v231
	v_cvt_pk_bf16_f32 v231, v232, v233
	global_store_dwordx2 v249, v[230:231], s[92:93] offset:512
	v_mul_f32_e32 v234, v245, v16
	v_mul_f32_e32 v235, v245, v17
	v_mul_f32_e32 v236, v245, v18
	v_mul_f32_e32 v237, v245, v19
	v_cvt_pk_bf16_f32 v234, v234, v235
	v_cvt_pk_bf16_f32 v235, v236, v237
	global_store_dwordx2 v249, v[234:235], s[92:93] offset:544
	v_mul_f32_e32 v230, v245, v24
	v_mul_f32_e32 v231, v245, v25
	v_mul_f32_e32 v232, v245, v26
	v_mul_f32_e32 v233, v245, v27
	v_cvt_pk_bf16_f32 v230, v230, v231
	v_cvt_pk_bf16_f32 v231, v232, v233
	global_store_dwordx2 v249, v[230:231], s[92:93] offset:576
	v_mul_f32_e32 v234, v245, v32
	v_mul_f32_e32 v235, v245, v33
	v_mul_f32_e32 v236, v245, v34
	v_mul_f32_e32 v237, v245, v35
	v_cvt_pk_bf16_f32 v234, v234, v235
	v_cvt_pk_bf16_f32 v235, v236, v237
	global_store_dwordx2 v249, v[234:235], s[92:93] offset:608
	v_mul_f32_e32 v230, v245, v40
	v_mul_f32_e32 v231, v245, v41
	v_mul_f32_e32 v232, v245, v42
	v_mul_f32_e32 v233, v245, v43
	v_cvt_pk_bf16_f32 v230, v230, v231
	v_cvt_pk_bf16_f32 v231, v232, v233
	global_store_dwordx2 v249, v[230:231], s[92:93] offset:640
	v_mul_f32_e32 v234, v245, v48
	v_mul_f32_e32 v235, v245, v49
	v_mul_f32_e32 v236, v245, v50
	v_mul_f32_e32 v237, v245, v51
	v_cvt_pk_bf16_f32 v234, v234, v235
	v_cvt_pk_bf16_f32 v235, v236, v237
	global_store_dwordx2 v249, v[234:235], s[92:93] offset:672
	v_mul_f32_e32 v230, v245, v56
	v_mul_f32_e32 v231, v245, v57
	v_mul_f32_e32 v232, v245, v58
	v_mul_f32_e32 v233, v245, v59
	v_cvt_pk_bf16_f32 v230, v230, v231
	v_cvt_pk_bf16_f32 v231, v232, v233
	global_store_dwordx2 v249, v[230:231], s[92:93] offset:704
	v_mul_f32_e32 v234, v245, v64
	v_mul_f32_e32 v235, v245, v65
	v_mul_f32_e32 v236, v245, v66
	v_mul_f32_e32 v237, v245, v67
	v_cvt_pk_bf16_f32 v234, v234, v235
	v_cvt_pk_bf16_f32 v235, v236, v237
	global_store_dwordx2 v249, v[234:235], s[92:93] offset:736
	v_xor_b32_e32 v196, 0x10000, v196
	v_xor_b32_e32 v197, 0x10000, v197
	v_xor_b32_e32 v198, 0x10000, v198
	v_xor_b32_e32 v199, 0x10000, v199
	v_xor_b32_e32 v200, 0x10000, v200
	v_xor_b32_e32 v201, 0x10000, v201
	v_xor_b32_e32 v202, 0x10000, v202
	v_xor_b32_e32 v203, 0x10000, v203
	s_waitcnt vmcnt(23)
	ds_write_b128 v1, v[164:167]
	s_waitcnt vmcnt(22)
	ds_write_b128 v1, v[168:171] offset:8192
	s_waitcnt vmcnt(21)
	ds_write_b128 v1, v[172:175] offset:16384
	s_waitcnt vmcnt(20)
	ds_write_b128 v1, v[176:179] offset:24576
	s_waitcnt vmcnt(19)
	ds_write_b128 v1, v[180:183] offset:32768
	s_waitcnt vmcnt(18)
	ds_write_b128 v1, v[184:187] offset:40960
	s_waitcnt vmcnt(17)
	ds_write_b128 v1, v[188:191] offset:49152
	s_waitcnt vmcnt(16)
	ds_write_b128 v1, v[192:195] offset:57344
	s_waitcnt lgkmcnt(0)
	s_barrier
	ds_read_b64_tr_b16 v[72:73], v196
	ds_read_b64_tr_b16 v[80:81], v197
	ds_read_b64_tr_b16 v[74:75], v196 offset:4096
	ds_read_b64_tr_b16 v[82:83], v197 offset:4096
	ds_read_b64_tr_b16 v[88:89], v198
	ds_read_b64_tr_b16 v[96:97], v199
	ds_read_b64_tr_b16 v[90:91], v198 offset:4096
	ds_read_b64_tr_b16 v[98:99], v199 offset:4096
	ds_read_b64_tr_b16 v[104:105], v200
	ds_read_b64_tr_b16 v[112:113], v201
	ds_read_b64_tr_b16 v[106:107], v200 offset:4096
	ds_read_b64_tr_b16 v[114:115], v201 offset:4096
	s_waitcnt lgkmcnt(8)
	ds_read_b64_tr_b16 v[120:121], v202
	ds_read_b64_tr_b16 v[128:129], v203
	ds_read_b64_tr_b16 v[122:123], v202 offset:4096
	ds_read_b64_tr_b16 v[130:131], v203 offset:4096
	v_mfma_f32_16x16x32_bf16 v[132:135], v[72:75], v[4:7], 0
	v_mfma_f32_16x16x32_bf16 v[8:11], v[72:75], v[68:71], 0
	v_mfma_f32_16x16x32_bf16 v[136:139], v[80:83], v[4:7], 0
	v_mfma_f32_16x16x32_bf16 v[16:19], v[80:83], v[68:71], 0
	s_waitcnt lgkmcnt(8)
	ds_read_b64_tr_b16 v[72:73], v196 offset:8192
	ds_read_b64_tr_b16 v[80:81], v197 offset:8192
	ds_read_b64_tr_b16 v[74:75], v196 offset:12288
	ds_read_b64_tr_b16 v[82:83], v197 offset:12288
	v_mfma_f32_16x16x32_bf16 v[140:143], v[88:91], v[4:7], 0
	v_mfma_f32_16x16x32_bf16 v[24:27], v[88:91], v[68:71], 0
	v_mfma_f32_16x16x32_bf16 v[144:147], v[96:99], v[4:7], 0
	v_mfma_f32_16x16x32_bf16 v[32:35], v[96:99], v[68:71], 0
	s_waitcnt lgkmcnt(8)
	ds_read_b64_tr_b16 v[88:89], v198 offset:8192
	ds_read_b64_tr_b16 v[96:97], v199 offset:8192
	ds_read_b64_tr_b16 v[90:91], v198 offset:12288
	ds_read_b64_tr_b16 v[98:99], v199 offset:12288
	v_mfma_f32_16x16x32_bf16 v[148:151], v[104:107], v[4:7], 0
	v_mfma_f32_16x16x32_bf16 v[40:43], v[104:107], v[68:71], 0
	v_mfma_f32_16x16x32_bf16 v[152:155], v[112:115], v[4:7], 0
	v_mfma_f32_16x16x32_bf16 v[48:51], v[112:115], v[68:71], 0
	s_waitcnt lgkmcnt(8)
; __device__ __forceinline__ f32x4 mfma16(bf16x8 a, bf16x8 b, f32x4 c) { return __builtin_amdgcn_mfma_f32_16x16x32_bf16(a, b, c, 0, 0, 0); }
; __device__ void cross_items(const Params& p, LAS unsigned char* lds) {
;     ...
; #pragma unroll
;             for (int sx = 0; sx < 8; ++sx) {
;                 const unsigned aA = bb + (unsigned)((32 * sx + 4 * g + (idx >> 2)) * KV_STRIDE + 8 * (idx & 3));
;                 const unsigned aB = aA + 16u * KV_STRIDE;
;                 bf16x8 vf[4];
;                 tr_frag4(aA, aB, vf);
; #pragma unroll
;                 for (int c8 = 0; c8 < 4; ++c8) ot[c8] = mfma16(vf[c8], pf[sx], ot[c8]);
;                 tr_frag4(aA + 128, aB + 128, vf);
; #pragma unroll
;                 for (int c8 = 0; c8 < 4; ++c8) ot[4 + c8] = mfma16(vf[c8], pf[sx], ot[4 + c8]);
;             }
	ds_read_b64_tr_b16 v[104:105], v200 offset:8192
	ds_read_b64_tr_b16 v[112:113], v201 offset:8192
	ds_read_b64_tr_b16 v[106:107], v200 offset:12288
	ds_read_b64_tr_b16 v[114:115], v201 offset:12288
	v_mfma_f32_16x16x32_bf16 v[156:159], v[120:123], v[4:7], 0
	v_mfma_f32_16x16x32_bf16 v[56:59], v[120:123], v[68:71], 0
	v_mfma_f32_16x16x32_bf16 v[160:163], v[128:131], v[4:7], 0
	v_mfma_f32_16x16x32_bf16 v[64:67], v[128:131], v[68:71], 0
	s_waitcnt lgkmcnt(8)
	ds_read_b64_tr_b16 v[120:121], v202 offset:8192
	ds_read_b64_tr_b16 v[128:129], v203 offset:8192
	ds_read_b64_tr_b16 v[122:123], v202 offset:12288
	ds_read_b64_tr_b16 v[130:131], v203 offset:12288
	v_mfma_f32_16x16x32_bf16 v[132:135], v[72:75], v[12:15], v[132:135]
	v_mfma_f32_16x16x32_bf16 v[8:11], v[72:75], v[76:79], v[8:11]
	v_mfma_f32_16x16x32_bf16 v[136:139], v[80:83], v[12:15], v[136:139]
	v_mfma_f32_16x16x32_bf16 v[16:19], v[80:83], v[76:79], v[16:19]
	s_waitcnt lgkmcnt(8)
	ds_read_b64_tr_b16 v[72:73], v196 offset:16384
	ds_read_b64_tr_b16 v[80:81], v197 offset:16384
	ds_read_b64_tr_b16 v[74:75], v196 offset:20480
	ds_read_b64_tr_b16 v[82:83], v197 offset:20480
	v_mfma_f32_16x16x32_bf16 v[140:143], v[88:91], v[12:15], v[140:143]
	v_mfma_f32_16x16x32_bf16 v[24:27], v[88:91], v[76:79], v[24:27]
	v_mfma_f32_16x16x32_bf16 v[144:147], v[96:99], v[12:15], v[144:147]
	v_mfma_f32_16x16x32_bf16 v[32:35], v[96:99], v[76:79], v[32:35]
	s_waitcnt lgkmcnt(8)
	ds_read_b64_tr_b16 v[88:89], v198 offset:16384
	ds_read_b64_tr_b16 v[96:97], v199 offset:16384
	ds_read_b64_tr_b16 v[90:91], v198 offset:20480
	ds_read_b64_tr_b16 v[98:99], v199 offset:20480
	v_mfma_f32_16x16x32_bf16 v[148:151], v[104:107], v[12:15], v[148:151]
	v_mfma_f32_16x16x32_bf16 v[40:43], v[104:107], v[76:79], v[40:43]
	v_mfma_f32_16x16x32_bf16 v[152:155], v[112:115], v[12:15], v[152:155]
	v_mfma_f32_16x16x32_bf16 v[48:51], v[112:115], v[76:79], v[48:51]
	s_waitcnt lgkmcnt(8)
	ds_read_b64_tr_b16 v[104:105], v200 offset:16384
	ds_read_b64_tr_b16 v[112:113], v201 offset:16384
	ds_read_b64_tr_b16 v[106:107], v200 offset:20480
	ds_read_b64_tr_b16 v[114:115], v201 offset:20480
	v_mfma_f32_16x16x32_bf16 v[156:159], v[120:123], v[12:15], v[156:159]
	v_mfma_f32_16x16x32_bf16 v[56:59], v[120:123], v[76:79], v[56:59]
	v_mfma_f32_16x16x32_bf16 v[160:163], v[128:131], v[12:15], v[160:163]
	v_mfma_f32_16x16x32_bf16 v[64:67], v[128:131], v[76:79], v[64:67]
	s_waitcnt lgkmcnt(8)
	ds_read_b64_tr_b16 v[120:121], v202 offset:16384
	ds_read_b64_tr_b16 v[128:129], v203 offset:16384
	ds_read_b64_tr_b16 v[122:123], v202 offset:20480
	ds_read_b64_tr_b16 v[130:131], v203 offset:20480
	v_mfma_f32_16x16x32_bf16 v[132:135], v[72:75], v[20:23], v[132:135]
	v_mfma_f32_16x16x32_bf16 v[8:11], v[72:75], v[84:87], v[8:11]
	v_mfma_f32_16x16x32_bf16 v[136:139], v[80:83], v[20:23], v[136:139]
	v_mfma_f32_16x16x32_bf16 v[16:19], v[80:83], v[84:87], v[16:19]
	s_waitcnt lgkmcnt(8)
	ds_read_b64_tr_b16 v[72:73], v196 offset:24576
	ds_read_b64_tr_b16 v[80:81], v197 offset:24576
	ds_read_b64_tr_b16 v[74:75], v196 offset:28672
	ds_read_b64_tr_b16 v[82:83], v197 offset:28672
	v_mfma_f32_16x16x32_bf16 v[140:143], v[88:91], v[20:23], v[140:143]
	v_mfma_f32_16x16x32_bf16 v[24:27], v[88:91], v[84:87], v[24:27]
	v_mfma_f32_16x16x32_bf16 v[144:147], v[96:99], v[20:23], v[144:147]
	v_mfma_f32_16x16x32_bf16 v[32:35], v[96:99], v[84:87], v[32:35]
	s_waitcnt lgkmcnt(8)
	ds_read_b64_tr_b16 v[88:89], v198 offset:24576
	ds_read_b64_tr_b16 v[96:97], v199 offset:24576
	ds_read_b64_tr_b16 v[90:91], v198 offset:28672
	ds_read_b64_tr_b16 v[98:99], v199 offset:28672
	v_mfma_f32_16x16x32_bf16 v[148:151], v[104:107], v[20:23], v[148:151]
	v_mfma_f32_16x16x32_bf16 v[40:43], v[104:107], v[84:87], v[40:43]
	v_mfma_f32_16x16x32_bf16 v[152:155], v[112:115], v[20:23], v[152:155]
	v_mfma_f32_16x16x32_bf16 v[48:51], v[112:115], v[84:87], v[48:51]
	s_waitcnt lgkmcnt(8)
	ds_read_b64_tr_b16 v[104:105], v200 offset:24576
	ds_read_b64_tr_b16 v[112:113], v201 offset:24576
	ds_read_b64_tr_b16 v[106:107], v200 offset:28672
	ds_read_b64_tr_b16 v[114:115], v201 offset:28672
	v_mfma_f32_16x16x32_bf16 v[156:159], v[120:123], v[20:23], v[156:159]
	v_mfma_f32_16x16x32_bf16 v[56:59], v[120:123], v[84:87], v[56:59]
	v_mfma_f32_16x16x32_bf16 v[160:163], v[128:131], v[20:23], v[160:163]
	v_mfma_f32_16x16x32_bf16 v[64:67], v[128:131], v[84:87], v[64:67]
	s_waitcnt lgkmcnt(8)
	ds_read_b64_tr_b16 v[120:121], v202 offset:24576
	ds_read_b64_tr_b16 v[128:129], v203 offset:24576
	ds_read_b64_tr_b16 v[122:123], v202 offset:28672
	ds_read_b64_tr_b16 v[130:131], v203 offset:28672
	v_mfma_f32_16x16x32_bf16 v[132:135], v[72:75], v[28:31], v[132:135]
	v_mfma_f32_16x16x32_bf16 v[8:11], v[72:75], v[92:95], v[8:11]
	v_mfma_f32_16x16x32_bf16 v[136:139], v[80:83], v[28:31], v[136:139]
	v_mfma_f32_16x16x32_bf16 v[16:19], v[80:83], v[92:95], v[16:19]
	s_waitcnt lgkmcnt(8)
	ds_read_b64_tr_b16 v[72:73], v196 offset:32768
	ds_read_b64_tr_b16 v[80:81], v197 offset:32768
	ds_read_b64_tr_b16 v[74:75], v196 offset:36864
	ds_read_b64_tr_b16 v[82:83], v197 offset:36864
	v_mfma_f32_16x16x32_bf16 v[140:143], v[88:91], v[28:31], v[140:143]
	v_mfma_f32_16x16x32_bf16 v[24:27], v[88:91], v[92:95], v[24:27]
	v_mfma_f32_16x16x32_bf16 v[144:147], v[96:99], v[28:31], v[144:147]
	v_mfma_f32_16x16x32_bf16 v[32:35], v[96:99], v[92:95], v[32:35]
	s_waitcnt lgkmcnt(8)
	ds_read_b64_tr_b16 v[88:89], v198 offset:32768
	ds_read_b64_tr_b16 v[96:97], v199 offset:32768
	ds_read_b64_tr_b16 v[90:91], v198 offset:36864
	ds_read_b64_tr_b16 v[98:99], v199 offset:36864
	v_mfma_f32_16x16x32_bf16 v[148:151], v[104:107], v[28:31], v[148:151]
	v_mfma_f32_16x16x32_bf16 v[40:43], v[104:107], v[92:95], v[40:43]
	v_mfma_f32_16x16x32_bf16 v[152:155], v[112:115], v[28:31], v[152:155]
	v_mfma_f32_16x16x32_bf16 v[48:51], v[112:115], v[92:95], v[48:51]
	s_waitcnt lgkmcnt(8)
; __device__ __forceinline__ f32x4 mfma16(bf16x8 a, bf16x8 b, f32x4 c) { return __builtin_amdgcn_mfma_f32_16x16x32_bf16(a, b, c, 0, 0, 0); }
; __device__ void cross_items(const Params& p, LAS unsigned char* lds) {
;     ...
; #pragma unroll
;             for (int sx = 0; sx < 8; ++sx) {
;                 const unsigned aA = bb + (unsigned)((32 * sx + 4 * g + (idx >> 2)) * KV_STRIDE + 8 * (idx & 3));
;                 const unsigned aB = aA + 16u * KV_STRIDE;
;                 bf16x8 vf[4];
;                 tr_frag4(aA, aB, vf);
; #pragma unroll
;                 for (int c8 = 0; c8 < 4; ++c8) ot[c8] = mfma16(vf[c8], pf[sx], ot[c8]);
;                 tr_frag4(aA + 128, aB + 128, vf);
; #pragma unroll
;                 for (int c8 = 0; c8 < 4; ++c8) ot[4 + c8] = mfma16(vf[c8], pf[sx], ot[4 + c8]);
;             }
	ds_read_b64_tr_b16 v[104:105], v200 offset:32768
	ds_read_b64_tr_b16 v[112:113], v201 offset:32768
	ds_read_b64_tr_b16 v[106:107], v200 offset:36864
	ds_read_b64_tr_b16 v[114:115], v201 offset:36864
	v_mfma_f32_16x16x32_bf16 v[156:159], v[120:123], v[28:31], v[156:159]
	v_mfma_f32_16x16x32_bf16 v[56:59], v[120:123], v[92:95], v[56:59]
	v_mfma_f32_16x16x32_bf16 v[160:163], v[128:131], v[28:31], v[160:163]
	v_mfma_f32_16x16x32_bf16 v[64:67], v[128:131], v[92:95], v[64:67]
	s_waitcnt lgkmcnt(8)
	ds_read_b64_tr_b16 v[120:121], v202 offset:32768
	ds_read_b64_tr_b16 v[128:129], v203 offset:32768
	ds_read_b64_tr_b16 v[122:123], v202 offset:36864
	ds_read_b64_tr_b16 v[130:131], v203 offset:36864
	v_mfma_f32_16x16x32_bf16 v[132:135], v[72:75], v[36:39], v[132:135]
	v_mfma_f32_16x16x32_bf16 v[8:11], v[72:75], v[100:103], v[8:11]
	v_mfma_f32_16x16x32_bf16 v[136:139], v[80:83], v[36:39], v[136:139]
	v_mfma_f32_16x16x32_bf16 v[16:19], v[80:83], v[100:103], v[16:19]
	s_waitcnt lgkmcnt(8)
	ds_read_b64_tr_b16 v[72:73], v196 offset:40960
	ds_read_b64_tr_b16 v[80:81], v197 offset:40960
	ds_read_b64_tr_b16 v[74:75], v196 offset:45056
	ds_read_b64_tr_b16 v[82:83], v197 offset:45056
	v_mfma_f32_16x16x32_bf16 v[140:143], v[88:91], v[36:39], v[140:143]
	v_mfma_f32_16x16x32_bf16 v[24:27], v[88:91], v[100:103], v[24:27]
	v_mfma_f32_16x16x32_bf16 v[144:147], v[96:99], v[36:39], v[144:147]
	v_mfma_f32_16x16x32_bf16 v[32:35], v[96:99], v[100:103], v[32:35]
	s_waitcnt lgkmcnt(8)
	ds_read_b64_tr_b16 v[88:89], v198 offset:40960
	ds_read_b64_tr_b16 v[96:97], v199 offset:40960
	ds_read_b64_tr_b16 v[90:91], v198 offset:45056
	ds_read_b64_tr_b16 v[98:99], v199 offset:45056
	v_mfma_f32_16x16x32_bf16 v[148:151], v[104:107], v[36:39], v[148:151]
	v_mfma_f32_16x16x32_bf16 v[40:43], v[104:107], v[100:103], v[40:43]
	v_mfma_f32_16x16x32_bf16 v[152:155], v[112:115], v[36:39], v[152:155]
	v_mfma_f32_16x16x32_bf16 v[48:51], v[112:115], v[100:103], v[48:51]
	s_waitcnt lgkmcnt(8)
	ds_read_b64_tr_b16 v[104:105], v200 offset:40960
	ds_read_b64_tr_b16 v[112:113], v201 offset:40960
	ds_read_b64_tr_b16 v[106:107], v200 offset:45056
	ds_read_b64_tr_b16 v[114:115], v201 offset:45056
	v_mfma_f32_16x16x32_bf16 v[156:159], v[120:123], v[36:39], v[156:159]
	v_mfma_f32_16x16x32_bf16 v[56:59], v[120:123], v[100:103], v[56:59]
	v_mfma_f32_16x16x32_bf16 v[160:163], v[128:131], v[36:39], v[160:163]
	v_mfma_f32_16x16x32_bf16 v[64:67], v[128:131], v[100:103], v[64:67]
	s_waitcnt lgkmcnt(8)
	ds_read_b64_tr_b16 v[120:121], v202 offset:40960
	ds_read_b64_tr_b16 v[128:129], v203 offset:40960
	ds_read_b64_tr_b16 v[122:123], v202 offset:45056
	ds_read_b64_tr_b16 v[130:131], v203 offset:45056
	v_mfma_f32_16x16x32_bf16 v[132:135], v[72:75], v[44:47], v[132:135]
	v_mfma_f32_16x16x32_bf16 v[8:11], v[72:75], v[108:111], v[8:11]
	v_mfma_f32_16x16x32_bf16 v[136:139], v[80:83], v[44:47], v[136:139]
	v_mfma_f32_16x16x32_bf16 v[16:19], v[80:83], v[108:111], v[16:19]
	s_waitcnt lgkmcnt(8)
	ds_read_b64_tr_b16 v[72:73], v196 offset:49152
	ds_read_b64_tr_b16 v[80:81], v197 offset:49152
	ds_read_b64_tr_b16 v[74:75], v196 offset:53248
	ds_read_b64_tr_b16 v[82:83], v197 offset:53248
	v_mfma_f32_16x16x32_bf16 v[140:143], v[88:91], v[44:47], v[140:143]
	v_mfma_f32_16x16x32_bf16 v[24:27], v[88:91], v[108:111], v[24:27]
	v_mfma_f32_16x16x32_bf16 v[144:147], v[96:99], v[44:47], v[144:147]
	v_mfma_f32_16x16x32_bf16 v[32:35], v[96:99], v[108:111], v[32:35]
	s_waitcnt lgkmcnt(8)
	ds_read_b64_tr_b16 v[88:89], v198 offset:49152
	ds_read_b64_tr_b16 v[96:97], v199 offset:49152
	ds_read_b64_tr_b16 v[90:91], v198 offset:53248
	ds_read_b64_tr_b16 v[98:99], v199 offset:53248
	v_mfma_f32_16x16x32_bf16 v[148:151], v[104:107], v[44:47], v[148:151]
	v_mfma_f32_16x16x32_bf16 v[40:43], v[104:107], v[108:111], v[40:43]
	v_mfma_f32_16x16x32_bf16 v[152:155], v[112:115], v[44:47], v[152:155]
	v_mfma_f32_16x16x32_bf16 v[48:51], v[112:115], v[108:111], v[48:51]
	s_waitcnt lgkmcnt(8)
	ds_read_b64_tr_b16 v[104:105], v200 offset:49152
	ds_read_b64_tr_b16 v[112:113], v201 offset:49152
	ds_read_b64_tr_b16 v[106:107], v200 offset:53248
	ds_read_b64_tr_b16 v[114:115], v201 offset:53248
	v_mfma_f32_16x16x32_bf16 v[156:159], v[120:123], v[44:47], v[156:159]
	v_mfma_f32_16x16x32_bf16 v[56:59], v[120:123], v[108:111], v[56:59]
	v_mfma_f32_16x16x32_bf16 v[160:163], v[128:131], v[44:47], v[160:163]
	v_mfma_f32_16x16x32_bf16 v[64:67], v[128:131], v[108:111], v[64:67]
	s_waitcnt lgkmcnt(8)
	ds_read_b64_tr_b16 v[120:121], v202 offset:49152
	ds_read_b64_tr_b16 v[128:129], v203 offset:49152
	ds_read_b64_tr_b16 v[122:123], v202 offset:53248
	ds_read_b64_tr_b16 v[130:131], v203 offset:53248
	v_mfma_f32_16x16x32_bf16 v[132:135], v[72:75], v[52:55], v[132:135]
	v_mfma_f32_16x16x32_bf16 v[8:11], v[72:75], v[116:119], v[8:11]
	v_mfma_f32_16x16x32_bf16 v[136:139], v[80:83], v[52:55], v[136:139]
	v_mfma_f32_16x16x32_bf16 v[16:19], v[80:83], v[116:119], v[16:19]
	s_waitcnt lgkmcnt(8)
	ds_read_b64_tr_b16 v[72:73], v196 offset:57344
	ds_read_b64_tr_b16 v[80:81], v197 offset:57344
	ds_read_b64_tr_b16 v[74:75], v196 offset:61440
	ds_read_b64_tr_b16 v[82:83], v197 offset:61440
	v_mfma_f32_16x16x32_bf16 v[140:143], v[88:91], v[52:55], v[140:143]
	v_mfma_f32_16x16x32_bf16 v[24:27], v[88:91], v[116:119], v[24:27]
	v_mfma_f32_16x16x32_bf16 v[144:147], v[96:99], v[52:55], v[144:147]
	v_mfma_f32_16x16x32_bf16 v[32:35], v[96:99], v[116:119], v[32:35]
	s_waitcnt lgkmcnt(8)
; __device__ __forceinline__ unsigned cvt_pk_bf16(float lo, float hi) { const f32x2v v = {lo, hi}; const b16x2v r = __builtin_convertvector(v, b16x2v); return __builtin_bit_cast(unsigned, r); }
; __device__ __forceinline__ f32x4 mfma16(bf16x8 a, bf16x8 b, f32x4 c) { return __builtin_amdgcn_mfma_f32_16x16x32_bf16(a, b, c, 0, 0, 0); }
; __device__ void cross_items(const Params& p, LAS unsigned char* lds) {
;     ...
;                 tr_frag4(aA, aB, vf);
; #pragma unroll
;                 for (int c8 = 0; c8 < 4; ++c8) ot[c8] = mfma16(vf[c8], pf[sx], ot[c8]);
;                 tr_frag4(aA + 128, aB + 128, vf);
; #pragma unroll
;                 for (int c8 = 0; c8 < 4; ++c8) ot[4 + c8] = mfma16(vf[c8], pf[sx], ot[4 + c8]);
;             }
; #pragma unroll
;             for (int c8 = 0; c8 < 8; ++c8) { u32x2 wv; wv.x = cvt_pk_bf16(ot[c8][0] * inv, ot[c8][1] * inv); wv.y = cvt_pk_bf16(ot[c8][2] * inv, ot[c8][3] * inv);
;                 *(u32x2*)(oc + tok * DM + head * 512 + c * 128 + 16 * c8 + 4 * g) = wv; }
;         }
;     }
;     ...
;     asm volatile("s_waitcnt vmcnt(0)" ::: "memory");
;     __syncthreads();
	ds_read_b64_tr_b16 v[88:89], v198 offset:57344
	ds_read_b64_tr_b16 v[96:97], v199 offset:57344
	ds_read_b64_tr_b16 v[90:91], v198 offset:61440
	ds_read_b64_tr_b16 v[98:99], v199 offset:61440
	v_mfma_f32_16x16x32_bf16 v[148:151], v[104:107], v[52:55], v[148:151]
	v_mfma_f32_16x16x32_bf16 v[40:43], v[104:107], v[116:119], v[40:43]
	v_mfma_f32_16x16x32_bf16 v[152:155], v[112:115], v[52:55], v[152:155]
	v_mfma_f32_16x16x32_bf16 v[48:51], v[112:115], v[116:119], v[48:51]
	s_waitcnt lgkmcnt(8)
	ds_read_b64_tr_b16 v[104:105], v200 offset:57344
	ds_read_b64_tr_b16 v[112:113], v201 offset:57344
	ds_read_b64_tr_b16 v[106:107], v200 offset:61440
	ds_read_b64_tr_b16 v[114:115], v201 offset:61440
	v_mfma_f32_16x16x32_bf16 v[156:159], v[120:123], v[52:55], v[156:159]
	v_mfma_f32_16x16x32_bf16 v[56:59], v[120:123], v[116:119], v[56:59]
	v_mfma_f32_16x16x32_bf16 v[160:163], v[128:131], v[52:55], v[160:163]
	v_mfma_f32_16x16x32_bf16 v[64:67], v[128:131], v[116:119], v[64:67]
	s_waitcnt lgkmcnt(8)
	ds_read_b64_tr_b16 v[120:121], v202 offset:57344
	ds_read_b64_tr_b16 v[128:129], v203 offset:57344
	ds_read_b64_tr_b16 v[122:123], v202 offset:61440
	ds_read_b64_tr_b16 v[130:131], v203 offset:61440
	v_mfma_f32_16x16x32_bf16 v[132:135], v[72:75], v[60:63], v[132:135]
	v_mfma_f32_16x16x32_bf16 v[8:11], v[72:75], v[124:127], v[8:11]
	v_mfma_f32_16x16x32_bf16 v[136:139], v[80:83], v[60:63], v[136:139]
	v_mfma_f32_16x16x32_bf16 v[16:19], v[80:83], v[124:127], v[16:19]
	s_waitcnt lgkmcnt(8)
	v_mfma_f32_16x16x32_bf16 v[140:143], v[88:91], v[60:63], v[140:143]
	v_mfma_f32_16x16x32_bf16 v[24:27], v[88:91], v[124:127], v[24:27]
	v_mfma_f32_16x16x32_bf16 v[144:147], v[96:99], v[60:63], v[144:147]
	v_mfma_f32_16x16x32_bf16 v[32:35], v[96:99], v[124:127], v[32:35]
	s_waitcnt lgkmcnt(4)
	v_mfma_f32_16x16x32_bf16 v[148:151], v[104:107], v[60:63], v[148:151]
	v_mfma_f32_16x16x32_bf16 v[40:43], v[104:107], v[124:127], v[40:43]
	v_mfma_f32_16x16x32_bf16 v[152:155], v[112:115], v[60:63], v[152:155]
	v_mfma_f32_16x16x32_bf16 v[48:51], v[112:115], v[124:127], v[48:51]
	s_waitcnt lgkmcnt(0)
	v_mfma_f32_16x16x32_bf16 v[156:159], v[120:123], v[60:63], v[156:159]
	v_mfma_f32_16x16x32_bf16 v[56:59], v[120:123], v[124:127], v[56:59]
	v_mfma_f32_16x16x32_bf16 v[160:163], v[128:131], v[60:63], v[160:163]
	v_mfma_f32_16x16x32_bf16 v[64:67], v[128:131], v[124:127], v[64:67]
	s_nop 7
	s_nop 7
	v_mul_f32_e32 v230, v244, v132
	v_mul_f32_e32 v231, v244, v133
	v_mul_f32_e32 v232, v244, v134
	v_mul_f32_e32 v233, v244, v135
	v_cvt_pk_bf16_f32 v230, v230, v231
	v_cvt_pk_bf16_f32 v231, v232, v233
	global_store_dwordx2 v248, v[230:231], s[92:93] offset:768
	v_mul_f32_e32 v234, v244, v136
	v_mul_f32_e32 v235, v244, v137
	v_mul_f32_e32 v236, v244, v138
	v_mul_f32_e32 v237, v244, v139
	v_cvt_pk_bf16_f32 v234, v234, v235
	v_cvt_pk_bf16_f32 v235, v236, v237
	global_store_dwordx2 v248, v[234:235], s[92:93] offset:800
	v_mul_f32_e32 v230, v244, v140
	v_mul_f32_e32 v231, v244, v141
	v_mul_f32_e32 v232, v244, v142
	v_mul_f32_e32 v233, v244, v143
	v_cvt_pk_bf16_f32 v230, v230, v231
	v_cvt_pk_bf16_f32 v231, v232, v233
	global_store_dwordx2 v248, v[230:231], s[92:93] offset:832
	v_mul_f32_e32 v234, v244, v144
	v_mul_f32_e32 v235, v244, v145
	v_mul_f32_e32 v236, v244, v146
	v_mul_f32_e32 v237, v244, v147
	v_cvt_pk_bf16_f32 v234, v234, v235
	v_cvt_pk_bf16_f32 v235, v236, v237
	global_store_dwordx2 v248, v[234:235], s[92:93] offset:864
	v_mul_f32_e32 v230, v244, v148
	v_mul_f32_e32 v231, v244, v149
	v_mul_f32_e32 v232, v244, v150
	v_mul_f32_e32 v233, v244, v151
	v_cvt_pk_bf16_f32 v230, v230, v231
	v_cvt_pk_bf16_f32 v231, v232, v233
	global_store_dwordx2 v248, v[230:231], s[92:93] offset:896
	v_mul_f32_e32 v234, v244, v152
	v_mul_f32_e32 v235, v244, v153
	v_mul_f32_e32 v236, v244, v154
	v_mul_f32_e32 v237, v244, v155
	v_cvt_pk_bf16_f32 v234, v234, v235
	v_cvt_pk_bf16_f32 v235, v236, v237
	global_store_dwordx2 v248, v[234:235], s[92:93] offset:928
	v_mul_f32_e32 v230, v244, v156
	v_mul_f32_e32 v231, v244, v157
	v_mul_f32_e32 v232, v244, v158
	v_mul_f32_e32 v233, v244, v159
	v_cvt_pk_bf16_f32 v230, v230, v231
	v_cvt_pk_bf16_f32 v231, v232, v233
	global_store_dwordx2 v248, v[230:231], s[92:93] offset:960
	v_mul_f32_e32 v234, v244, v160
	v_mul_f32_e32 v235, v244, v161
	v_mul_f32_e32 v236, v244, v162
	v_mul_f32_e32 v237, v244, v163
	v_cvt_pk_bf16_f32 v234, v234, v235
	v_cvt_pk_bf16_f32 v235, v236, v237
	global_store_dwordx2 v248, v[234:235], s[92:93] offset:992
	v_mul_f32_e32 v230, v245, v8
	v_mul_f32_e32 v231, v245, v9
	v_mul_f32_e32 v232, v245, v10
	v_mul_f32_e32 v233, v245, v11
	v_cvt_pk_bf16_f32 v230, v230, v231
	v_cvt_pk_bf16_f32 v231, v232, v233
	global_store_dwordx2 v249, v[230:231], s[92:93] offset:768
	v_mul_f32_e32 v234, v245, v16
	v_mul_f32_e32 v235, v245, v17
	v_mul_f32_e32 v236, v245, v18
	v_mul_f32_e32 v237, v245, v19
	v_cvt_pk_bf16_f32 v234, v234, v235
	v_cvt_pk_bf16_f32 v235, v236, v237
	global_store_dwordx2 v249, v[234:235], s[92:93] offset:800
	v_mul_f32_e32 v230, v245, v24
	v_mul_f32_e32 v231, v245, v25
	v_mul_f32_e32 v232, v245, v26
	v_mul_f32_e32 v233, v245, v27
	v_cvt_pk_bf16_f32 v230, v230, v231
	v_cvt_pk_bf16_f32 v231, v232, v233
	global_store_dwordx2 v249, v[230:231], s[92:93] offset:832
	v_mul_f32_e32 v234, v245, v32
	v_mul_f32_e32 v235, v245, v33
	v_mul_f32_e32 v236, v245, v34
	v_mul_f32_e32 v237, v245, v35
	v_cvt_pk_bf16_f32 v234, v234, v235
	v_cvt_pk_bf16_f32 v235, v236, v237
	global_store_dwordx2 v249, v[234:235], s[92:93] offset:864
	v_mul_f32_e32 v230, v245, v40
	v_mul_f32_e32 v231, v245, v41
	v_mul_f32_e32 v232, v245, v42
	v_mul_f32_e32 v233, v245, v43
	v_cvt_pk_bf16_f32 v230, v230, v231
	v_cvt_pk_bf16_f32 v231, v232, v233
	global_store_dwordx2 v249, v[230:231], s[92:93] offset:896
	v_mul_f32_e32 v234, v245, v48
	v_mul_f32_e32 v235, v245, v49
	v_mul_f32_e32 v236, v245, v50
	v_mul_f32_e32 v237, v245, v51
	v_cvt_pk_bf16_f32 v234, v234, v235
	v_cvt_pk_bf16_f32 v235, v236, v237
	global_store_dwordx2 v249, v[234:235], s[92:93] offset:928
	v_mul_f32_e32 v230, v245, v56
	v_mul_f32_e32 v231, v245, v57
	v_mul_f32_e32 v232, v245, v58
	v_mul_f32_e32 v233, v245, v59
	v_cvt_pk_bf16_f32 v230, v230, v231
	v_cvt_pk_bf16_f32 v231, v232, v233
	global_store_dwordx2 v249, v[230:231], s[92:93] offset:960
	v_mul_f32_e32 v234, v245, v64
	v_mul_f32_e32 v235, v245, v65
	v_mul_f32_e32 v236, v245, v66
	v_mul_f32_e32 v237, v245, v67
	v_cvt_pk_bf16_f32 v234, v234, v235
	v_cvt_pk_bf16_f32 v235, v236, v237
	global_store_dwordx2 v249, v[234:235], s[92:93] offset:992
	v_xor_b32_e32 v196, 0x10000, v196
	v_xor_b32_e32 v197, 0x10000, v197
	v_xor_b32_e32 v198, 0x10000, v198
	v_xor_b32_e32 v199, 0x10000, v199
	v_xor_b32_e32 v200, 0x10000, v200
	v_xor_b32_e32 v201, 0x10000, v201
	v_xor_b32_e32 v202, 0x10000, v202
	v_xor_b32_e32 v203, 0x10000, v203
	s_waitcnt vmcnt(0)
	s_waitcnt lgkmcnt(0)
	s_barrier
